# v12: v6 + static prio for waves 4-7 (flips removed) + duplicate lgkmcnt(0) before MMA blocks removed; baseline placement; measure 1
# speedup vs baseline: 1.0052x; 1.0052x over previous
; #define PG8_STAGE(bufoff, gbase, voff) do { _Pragma("unroll") for (int _i = 0; _i < 2; ++_i) \
;         __builtin_amdgcn_global_load_lds((const unsigned*)((const char*)(gbase) + (voff)[_i]), (LAS unsigned*)(lds + (bufoff) + ldsw + _i * 8192), 16, 0, 0); } while (0)
; #define PG8_LDA(dst, b, h) do { _Pragma("unroll") for (int m = 0; m < 4; ++m) _Pragma("unroll") for (int k = 0; k < 2; ++k) dst[m][k] = *(const LAS bf16x8*)(lds + PG8_SA(b, h) + aoff + m * 2048 + k * 1024); } while (0)
; #define PG8_LDB(dst, b, h) do { _Pragma("unroll") for (int n = 0; n < 2; ++n) _Pragma("unroll") for (int k = 0; k < 2; ++k) dst[n][k] = *(const LAS bf16x8*)(lds + PG8_SB(b, h) + boff + n * 2048 + k * 1024); } while (0)
; #define PG8_MMA(ai, bj, At, Bt) do { __builtin_amdgcn_s_setprio(1); _Pragma("unroll") for (int m = 0; m < 4; ++m) _Pragma("unroll") for (int n = 0; n < 2; ++n) _Pragma("unroll") for (int k = 0; k < 2; ++k) \
;         acc[ai][bj][m][n] = __builtin_amdgcn_mfma_f32_16x16x32_bf16(Bt[n][k], At[m][k], acc[ai][bj][m][n], 0, 0, 0); __builtin_amdgcn_s_setprio(0); } while (0)
; #define PG8_WAIT_L(n) asm volatile("s_waitcnt lgkmcnt(" #n ")" ::: "memory")
; #define PG8_BAR __builtin_amdgcn_s_barrier()
; template <class Epi, class Ptrs>
; __device__ __forceinline__ void gemm_phase(LAS unsigned char* lds, const int K, const StaticOrder& S, const Ptrs& P, const Epi& E) {
;     ...
;         const char* nA = cA; const char* nB = cB; if (has_next) P.get(nxt, nA, nB);
;         for (int t = 0; t < nt; t += 2) {
;             const bool last = (t == nt - 2);
;             const char* a1 = cA + (size_t)(t + 1) * kstep;
;             const char* a2 = last ? nA : cA + (size_t)(t + 2) * kstep; const char* b2 = last ? nB : cB + (size_t)(t + 2) * kstep;
;             const char* a3 = a2 + kstep; const char* b3 = b2 + kstep;
;             PG8_LDB(B0, 0, 0); PG8_SCHED; PG8_LDA(At, 0, 0); PG8_STAGE(PG8_SA(1, 1), a1 + hstep, voffA);
;             PG8_WAIT_L(8); PG8_BAR; PG8_WAIT_L(0); PG8_MMA(0, 0, At, B0); PG8_BAR; PG8_SCHED;
;     ...
; #pragma unroll
;         for (int a = 0; a < 2; ++a)
; #pragma unroll
;             for (int b = 0; b < 2; ++b)
; #pragma unroll
;                 for (int m = 0; m < 4; ++m)
; #pragma unroll
;                     for (int n = 0; n < 2; ++n) acc[a][b][m][n] = (f32x4){0.f, 0.f, 0.f, 0.f};
;         cur = nxt; cA = nA; cB = nB; ++ui;
.LBB0_126:
	s_add_u32 s6, s6, 0x40080
	s_nop 0
	s_nop 0
	s_nop 0
	s_nop 0
	s_nop 0
	s_nop 0
	s_nop 0
	s_nop 0
	s_nop 0
	s_nop 0
	s_nop 0
	s_nop 0
	s_nop 0
	s_nop 0
	s_nop 0
	s_nop 0
	s_nop 0
	s_nop 0
	s_nop 0
	s_nop 0
	s_nop 0
	s_nop 0
	s_nop 0
	s_nop 0
	s_nop 0
	s_nop 0
	s_nop 0
	s_nop 0
	s_nop 0
	s_nop 0
	s_nop 0
	s_nop 0
	s_nop 0
	s_nop 0
	s_nop 0
	s_nop 0
	s_nop 0
	s_nop 0
	s_nop 0
	s_nop 0
	s_nop 0
	s_nop 0
	s_nop 0
	s_nop 0
	s_nop 0
	s_nop 0
	s_nop 0
	s_nop 0
	s_nop 0
	s_nop 0
	s_nop 0
	s_nop 0
	s_nop 0
	s_nop 0
	s_nop 0
	s_nop 0
	s_nop 0
	s_nop 0
	s_nop 0
	s_nop 0
	s_nop 0
	s_addc_u32 s7, s7, 0
	s_add_u32 s20, s78, 0x100
	v_mov_b32_e32 v0, 0
	s_addc_u32 s25, s79, 0
	s_mov_b32 s63, -2
	v_mov_b32_e32 v1, v0
	v_mov_b32_e32 v2, v0
	v_mov_b32_e32 v3, v0
	v_mov_b32_e32 v12, v0
	v_mov_b32_e32 v13, v0
	v_mov_b32_e32 v14, v0
	v_mov_b32_e32 v15, v0
	v_mov_b32_e32 v16, v0
	v_mov_b32_e32 v17, v0
	v_mov_b32_e32 v18, v0
	v_mov_b32_e32 v19, v0
	v_mov_b32_e32 v28, v0
	v_mov_b32_e32 v29, v0
	v_mov_b32_e32 v30, v0
	v_mov_b32_e32 v31, v0
	v_mov_b32_e32 v32, v0
	v_mov_b32_e32 v33, v0
	v_mov_b32_e32 v34, v0
	v_mov_b32_e32 v35, v0
	v_mov_b32_e32 v44, v0
	v_mov_b32_e32 v45, v0
	v_mov_b32_e32 v46, v0
	v_mov_b32_e32 v47, v0
	v_mov_b32_e32 v48, v0
	v_mov_b32_e32 v49, v0
	v_mov_b32_e32 v50, v0
	v_mov_b32_e32 v51, v0
	v_mov_b32_e32 v60, v0
	v_mov_b32_e32 v61, v0
	v_mov_b32_e32 v62, v0
	v_mov_b32_e32 v63, v0
	v_mov_b32_e32 v4, v0
	v_mov_b32_e32 v5, v0
	v_mov_b32_e32 v6, v0
	v_mov_b32_e32 v7, v0
	v_mov_b32_e32 v8, v0
	v_mov_b32_e32 v9, v0
	v_mov_b32_e32 v10, v0
	v_mov_b32_e32 v11, v0
	v_mov_b32_e32 v20, v0
	v_mov_b32_e32 v21, v0
	v_mov_b32_e32 v22, v0
	v_mov_b32_e32 v23, v0
	v_mov_b32_e32 v24, v0
	v_mov_b32_e32 v25, v0
	v_mov_b32_e32 v26, v0
	v_mov_b32_e32 v27, v0
	v_mov_b32_e32 v36, v0
	v_mov_b32_e32 v37, v0
	v_mov_b32_e32 v38, v0
	v_mov_b32_e32 v39, v0
	v_mov_b32_e32 v40, v0
	v_mov_b32_e32 v41, v0
	v_mov_b32_e32 v42, v0
	v_mov_b32_e32 v43, v0
	v_mov_b32_e32 v52, v0
	v_mov_b32_e32 v53, v0
	v_mov_b32_e32 v54, v0
	v_mov_b32_e32 v55, v0
	v_mov_b32_e32 v56, v0
	v_mov_b32_e32 v57, v0
	v_mov_b32_e32 v58, v0
	v_mov_b32_e32 v59, v0
	v_mov_b32_e32 v64, v0
	v_mov_b32_e32 v65, v0
	v_mov_b32_e32 v66, v0
	v_mov_b32_e32 v67, v0
	v_mov_b32_e32 v76, v0
	v_mov_b32_e32 v77, v0
	v_mov_b32_e32 v78, v0
	v_mov_b32_e32 v79, v0
	v_mov_b32_e32 v80, v0
	v_mov_b32_e32 v81, v0
	v_mov_b32_e32 v82, v0
	v_mov_b32_e32 v83, v0
	v_mov_b32_e32 v92, v0
	v_mov_b32_e32 v93, v0
	v_mov_b32_e32 v94, v0
	v_mov_b32_e32 v95, v0
	v_mov_b32_e32 v96, v0
	v_mov_b32_e32 v97, v0
	v_mov_b32_e32 v98, v0
	v_mov_b32_e32 v99, v0
	v_mov_b32_e32 v108, v0
	v_mov_b32_e32 v109, v0
	v_mov_b32_e32 v110, v0
	v_mov_b32_e32 v111, v0
	v_mov_b32_e32 v112, v0
	v_mov_b32_e32 v113, v0
	v_mov_b32_e32 v114, v0
	v_mov_b32_e32 v115, v0
	v_mov_b32_e32 v124, v0
	v_mov_b32_e32 v125, v0
	v_mov_b32_e32 v126, v0
	v_mov_b32_e32 v127, v0
	v_mov_b32_e32 v68, v0
	v_mov_b32_e32 v69, v0
	v_mov_b32_e32 v70, v0
	v_mov_b32_e32 v71, v0
	v_mov_b32_e32 v72, v0
	v_mov_b32_e32 v73, v0
	v_mov_b32_e32 v74, v0
	v_mov_b32_e32 v75, v0
	v_mov_b32_e32 v84, v0
	v_mov_b32_e32 v85, v0
	v_mov_b32_e32 v86, v0
	v_mov_b32_e32 v87, v0
	v_mov_b32_e32 v88, v0
	v_mov_b32_e32 v89, v0
	v_mov_b32_e32 v90, v0
	v_mov_b32_e32 v91, v0
	v_mov_b32_e32 v100, v0
	v_mov_b32_e32 v101, v0
	v_mov_b32_e32 v102, v0
	v_mov_b32_e32 v103, v0
	v_mov_b32_e32 v104, v0
	v_mov_b32_e32 v105, v0
	v_mov_b32_e32 v106, v0
	v_mov_b32_e32 v107, v0
	v_mov_b32_e32 v116, v0
	v_mov_b32_e32 v117, v0
	v_mov_b32_e32 v118, v0
	v_mov_b32_e32 v119, v0
	v_mov_b32_e32 v120, v0
	v_mov_b32_e32 v121, v0
	v_mov_b32_e32 v122, v0
	v_mov_b32_e32 v123, v0
.LBB0_127:
	ds_read_b128 v[150:153], v205
	ds_read_b128 v[154:157], v205 offset:1024
	ds_read_b128 v[158:161], v205 offset:2048
	ds_read_b128 v[162:165], v205 offset:3072
	s_add_u32 s69, s6, 0xfffc0080
	s_addc_u32 s71, s7, -1
	s_cmp_eq_u32 s63, 12
	s_cselect_b32 s81, s1, s71
	s_cselect_b32 s80, s0, s69
	s_cselect_b32 s79, s73, s25
	s_cselect_b32 s78, s72, s20
	s_add_i32 m0, s67, 0xc000
	ds_read_b128 v[166:169], v206
	ds_read_b128 v[170:173], v206 offset:1024
	ds_read_b128 v[174:177], v206 offset:2048
	ds_read_b128 v[178:181], v206 offset:3072
	ds_read_b128 v[182:185], v206 offset:4096
	ds_read_b128 v[186:189], v206 offset:5120
	ds_read_b128 v[190:193], v206 offset:6144
	ds_read_b128 v[194:197], v206 offset:7168
	global_load_lds_dwordx4 v142, s[6:7]
	s_add_i32 m0, s67, 0xe000
	s_nop 0
	global_load_lds_dwordx4 v144, s[6:7]
	s_waitcnt lgkmcnt(8)
	s_barrier
	s_waitcnt lgkmcnt(0)
	v_mfma_f32_16x16x32_bf16 v[120:123], v[150:153], v[166:169], v[120:123]
	v_mfma_f32_16x16x32_bf16 v[120:123], v[154:157], v[170:173], v[120:123]
	v_mfma_f32_16x16x32_bf16 v[116:119], v[162:165], v[170:173], v[116:119]
	v_mfma_f32_16x16x32_bf16 v[116:119], v[158:161], v[166:169], v[116:119]
	v_mfma_f32_16x16x32_bf16 v[100:103], v[158:161], v[174:177], v[100:103]
	v_mfma_f32_16x16x32_bf16 v[100:103], v[162:165], v[178:181], v[100:103]
	v_mfma_f32_16x16x32_bf16 v[104:107], v[154:157], v[178:181], v[104:107]
	v_mfma_f32_16x16x32_bf16 v[104:107], v[150:153], v[174:177], v[104:107]
	v_mfma_f32_16x16x32_bf16 v[88:91], v[150:153], v[182:185], v[88:91]
	v_mfma_f32_16x16x32_bf16 v[88:91], v[154:157], v[186:189], v[88:91]
	v_mfma_f32_16x16x32_bf16 v[84:87], v[162:165], v[186:189], v[84:87]
	v_mfma_f32_16x16x32_bf16 v[84:87], v[158:161], v[182:185], v[84:87]
	v_mfma_f32_16x16x32_bf16 v[68:71], v[158:161], v[190:193], v[68:71]
	v_mfma_f32_16x16x32_bf16 v[68:71], v[162:165], v[194:197], v[68:71]
	v_mfma_f32_16x16x32_bf16 v[72:75], v[154:157], v[194:197], v[72:75]
	v_mfma_f32_16x16x32_bf16 v[72:75], v[150:153], v[190:193], v[72:75]
	s_barrier
; #define PG8_STAGE(bufoff, gbase, voff) do { _Pragma("unroll") for (int _i = 0; _i < 2; ++_i) \
;         __builtin_amdgcn_global_load_lds((const unsigned*)((const char*)(gbase) + (voff)[_i]), (LAS unsigned*)(lds + (bufoff) + ldsw + _i * 8192), 16, 0, 0); } while (0)
; #define PG8_LDA(dst, b, h) do { _Pragma("unroll") for (int m = 0; m < 4; ++m) _Pragma("unroll") for (int k = 0; k < 2; ++k) dst[m][k] = *(const LAS bf16x8*)(lds + PG8_SA(b, h) + aoff + m * 2048 + k * 1024); } while (0)
; #define PG8_LDB(dst, b, h) do { _Pragma("unroll") for (int n = 0; n < 2; ++n) _Pragma("unroll") for (int k = 0; k < 2; ++k) dst[n][k] = *(const LAS bf16x8*)(lds + PG8_SB(b, h) + boff + n * 2048 + k * 1024); } while (0)
; #define PG8_MMA(ai, bj, At, Bt) do { __builtin_amdgcn_s_setprio(1); _Pragma("unroll") for (int m = 0; m < 4; ++m) _Pragma("unroll") for (int n = 0; n < 2; ++n) _Pragma("unroll") for (int k = 0; k < 2; ++k) \
;         acc[ai][bj][m][n] = __builtin_amdgcn_mfma_f32_16x16x32_bf16(Bt[n][k], At[m][k], acc[ai][bj][m][n], 0, 0, 0); __builtin_amdgcn_s_setprio(0); } while (0)
; #define PG8_WAIT_V(n) asm volatile("s_waitcnt vmcnt(" #n ")" ::: "memory")
; #define PG8_WAIT_L(n) asm volatile("s_waitcnt lgkmcnt(" #n ")" ::: "memory")
; #define PG8_BAR __builtin_amdgcn_s_barrier()
; #define PG8_SCHED __builtin_amdgcn_sched_barrier(0)
; template <class Epi, class Ptrs>
; __device__ __forceinline__ void gemm_phase(LAS unsigned char* lds, const int K, const StaticOrder& S, const Ptrs& P, const Epi& E) {
;     ...
;             PG8_WAIT_L(8); PG8_BAR; PG8_WAIT_L(0); PG8_MMA(0, 0, At, B0); PG8_BAR; PG8_SCHED;
;             PG8_LDB(B1, 0, 1); PG8_STAGE(PG8_SB(0, 0), b2, voffB);
;             PG8_BAR; PG8_WAIT_L(0); PG8_MMA(0, 1, At, B1); PG8_BAR;
;             PG8_LDA(At, 0, 1); PG8_STAGE(PG8_SA(0, 0), a2, voffA);
;             PG8_BAR; PG8_WAIT_L(0); PG8_MMA(1, 0, At, B0); PG8_BAR; PG8_SCHED;
;             PG8_STAGE(PG8_SB(0, 1), b2 + hstep, voffB);
;             PG8_WAIT_V(6); PG8_BAR; PG8_MMA(1, 1, At, B1); PG8_BAR;
;             PG8_LDB(B0, 1, 0); PG8_SCHED; PG8_LDA(At, 1, 0); PG8_STAGE(PG8_SA(0, 1), a2 + hstep, voffA);
;             PG8_WAIT_L(8); PG8_BAR; PG8_WAIT_L(0); PG8_MMA(0, 0, At, B0); PG8_BAR; PG8_SCHED;
	s_add_i32 s69, s91, s65
	v_lshl_add_u64 v[202:203], s[78:79], 0, v[134:135]
	s_mov_b32 m0, s69
	ds_read_b128 v[198:201], v207
	ds_read_b128 v[210:213], v207 offset:1024
	ds_read_b128 v[214:217], v207 offset:2048
	ds_read_b128 v[218:221], v207 offset:3072
	global_load_lds_dwordx4 v[202:203], off
	v_lshl_add_u64 v[222:223], s[78:79], 0, v[138:139]
	s_add_i32 m0, s69, 0x2000
	s_nop 0
	global_load_lds_dwordx4 v[222:223], off
	s_barrier
	s_waitcnt lgkmcnt(0)
	v_mfma_f32_16x16x32_bf16 v[124:127], v[198:201], v[166:169], v[124:127]
	v_mfma_f32_16x16x32_bf16 v[124:127], v[210:213], v[170:173], v[124:127]
	v_mfma_f32_16x16x32_bf16 v[112:115], v[218:221], v[170:173], v[112:115]
	v_mfma_f32_16x16x32_bf16 v[112:115], v[214:217], v[166:169], v[112:115]
	v_mfma_f32_16x16x32_bf16 v[96:99], v[214:217], v[174:177], v[96:99]
	v_mfma_f32_16x16x32_bf16 v[96:99], v[218:221], v[178:181], v[96:99]
	v_mfma_f32_16x16x32_bf16 v[108:111], v[210:213], v[178:181], v[108:111]
	v_mfma_f32_16x16x32_bf16 v[108:111], v[198:201], v[174:177], v[108:111]
	v_mfma_f32_16x16x32_bf16 v[92:95], v[198:201], v[182:185], v[92:95]
	v_mfma_f32_16x16x32_bf16 v[92:95], v[210:213], v[186:189], v[92:95]
	v_mfma_f32_16x16x32_bf16 v[80:83], v[218:221], v[186:189], v[80:83]
	v_mfma_f32_16x16x32_bf16 v[80:83], v[214:217], v[182:185], v[80:83]
	v_mfma_f32_16x16x32_bf16 v[64:67], v[214:217], v[190:193], v[64:67]
	v_mfma_f32_16x16x32_bf16 v[64:67], v[218:221], v[194:197], v[64:67]
	v_mfma_f32_16x16x32_bf16 v[76:79], v[210:213], v[194:197], v[76:79]
	v_mfma_f32_16x16x32_bf16 v[76:79], v[198:201], v[190:193], v[76:79]
	s_mov_b32 m0, s67
	v_lshl_add_u64 v[224:225], s[80:81], 0, v[132:133]
	s_barrier
	ds_read_b128 v[166:169], v206 offset:16384
	ds_read_b128 v[170:173], v206 offset:17408
	ds_read_b128 v[174:177], v206 offset:18432
	ds_read_b128 v[178:181], v206 offset:19456
	ds_read_b128 v[182:185], v206 offset:20480
	ds_read_b128 v[186:189], v206 offset:21504
	ds_read_b128 v[190:193], v206 offset:22528
	ds_read_b128 v[194:197], v206 offset:23552
	global_load_lds_dwordx4 v[224:225], off
	v_lshl_add_u64 v[226:227], s[80:81], 0, v[136:137]
	s_mov_b32 m0, s75
	s_nop 0
	global_load_lds_dwordx4 v[226:227], off
	s_barrier
	s_waitcnt lgkmcnt(0)
	v_mfma_f32_16x16x32_bf16 v[56:59], v[150:153], v[166:169], v[56:59]
	v_mfma_f32_16x16x32_bf16 v[56:59], v[154:157], v[170:173], v[56:59]
	v_mfma_f32_16x16x32_bf16 v[52:55], v[162:165], v[170:173], v[52:55]
	v_mfma_f32_16x16x32_bf16 v[52:55], v[158:161], v[166:169], v[52:55]
	v_mfma_f32_16x16x32_bf16 v[36:39], v[158:161], v[174:177], v[36:39]
	v_mfma_f32_16x16x32_bf16 v[36:39], v[162:165], v[178:181], v[36:39]
	v_mfma_f32_16x16x32_bf16 v[40:43], v[154:157], v[178:181], v[40:43]
	v_mfma_f32_16x16x32_bf16 v[40:43], v[150:153], v[174:177], v[40:43]
	v_mfma_f32_16x16x32_bf16 v[24:27], v[150:153], v[182:185], v[24:27]
	v_mfma_f32_16x16x32_bf16 v[24:27], v[154:157], v[186:189], v[24:27]
	v_mfma_f32_16x16x32_bf16 v[20:23], v[162:165], v[186:189], v[20:23]
	v_mfma_f32_16x16x32_bf16 v[20:23], v[158:161], v[182:185], v[20:23]
	v_mfma_f32_16x16x32_bf16 v[4:7], v[158:161], v[190:193], v[4:7]
	v_mfma_f32_16x16x32_bf16 v[4:7], v[162:165], v[194:197], v[4:7]
	v_mfma_f32_16x16x32_bf16 v[8:11], v[154:157], v[194:197], v[8:11]
	v_mfma_f32_16x16x32_bf16 v[8:11], v[150:153], v[190:193], v[8:11]
	s_barrier
	s_add_u32 s82, s78, 0x40000
	s_addc_u32 s83, s79, 0
	s_add_i32 s69, s92, s65
	s_mov_b32 m0, s69
	s_nop 0
	global_load_lds_dwordx4 v134, s[82:83]
	s_add_i32 m0, s69, 0x2000
	s_nop 0
	global_load_lds_dwordx4 v138, s[82:83]
	s_waitcnt vmcnt(6)
	s_barrier
	v_mfma_f32_16x16x32_bf16 v[60:63], v[198:201], v[166:169], v[60:63]
	v_mfma_f32_16x16x32_bf16 v[60:63], v[210:213], v[170:173], v[60:63]
	v_mfma_f32_16x16x32_bf16 v[48:51], v[218:221], v[170:173], v[48:51]
	v_mfma_f32_16x16x32_bf16 v[48:51], v[214:217], v[166:169], v[48:51]
	v_mfma_f32_16x16x32_bf16 v[32:35], v[214:217], v[174:177], v[32:35]
	v_mfma_f32_16x16x32_bf16 v[32:35], v[218:221], v[178:181], v[32:35]
	v_mfma_f32_16x16x32_bf16 v[44:47], v[210:213], v[178:181], v[44:47]
	v_mfma_f32_16x16x32_bf16 v[44:47], v[198:201], v[174:177], v[44:47]
	v_mfma_f32_16x16x32_bf16 v[28:31], v[198:201], v[182:185], v[28:31]
	v_mfma_f32_16x16x32_bf16 v[28:31], v[210:213], v[186:189], v[28:31]
	v_mfma_f32_16x16x32_bf16 v[16:19], v[218:221], v[186:189], v[16:19]
	v_mfma_f32_16x16x32_bf16 v[16:19], v[214:217], v[182:185], v[16:19]
	v_mfma_f32_16x16x32_bf16 v[0:3], v[214:217], v[190:193], v[0:3]
	v_mfma_f32_16x16x32_bf16 v[0:3], v[218:221], v[194:197], v[0:3]
	v_mfma_f32_16x16x32_bf16 v[12:15], v[210:213], v[194:197], v[12:15]
	v_mfma_f32_16x16x32_bf16 v[12:15], v[198:201], v[190:193], v[12:15]
	s_add_i32 s69, 0, 0x18000
	v_add_u32_e32 v140, s69, v131
	s_barrier
	ds_read_b128 v[150:153], v140
	ds_read_b128 v[154:157], v140 offset:1024
	ds_read_b128 v[158:161], v140 offset:2048
	ds_read_b128 v[162:165], v140 offset:3072
	s_add_u32 s80, s80, 0x40000
	s_addc_u32 s81, s81, 0
	s_mov_b32 m0, s77
	ds_read_b128 v[166:169], v206 offset:32768
	ds_read_b128 v[170:173], v206 offset:33792
	ds_read_b128 v[174:177], v206 offset:34816
	ds_read_b128 v[178:181], v206 offset:35840
	ds_read_b128 v[182:185], v206 offset:36864
	ds_read_b128 v[186:189], v206 offset:37888
	ds_read_b128 v[190:193], v206 offset:38912
	ds_read_b128 v[194:197], v206 offset:39936
	global_load_lds_dwordx4 v132, s[80:81]
	s_mov_b32 m0, s85
	s_nop 0
	global_load_lds_dwordx4 v136, s[80:81]
	s_waitcnt lgkmcnt(8)
	s_barrier
; #define PG8_STAGE(bufoff, gbase, voff) do { _Pragma("unroll") for (int _i = 0; _i < 2; ++_i) \
;         __builtin_amdgcn_global_load_lds((const unsigned*)((const char*)(gbase) + (voff)[_i]), (LAS unsigned*)(lds + (bufoff) + ldsw + _i * 8192), 16, 0, 0); } while (0)
; #define PG8_LDA(dst, b, h) do { _Pragma("unroll") for (int m = 0; m < 4; ++m) _Pragma("unroll") for (int k = 0; k < 2; ++k) dst[m][k] = *(const LAS bf16x8*)(lds + PG8_SA(b, h) + aoff + m * 2048 + k * 1024); } while (0)
; #define PG8_LDB(dst, b, h) do { _Pragma("unroll") for (int n = 0; n < 2; ++n) _Pragma("unroll") for (int k = 0; k < 2; ++k) dst[n][k] = *(const LAS bf16x8*)(lds + PG8_SB(b, h) + boff + n * 2048 + k * 1024); } while (0)
; #define PG8_MMA(ai, bj, At, Bt) do { __builtin_amdgcn_s_setprio(1); _Pragma("unroll") for (int m = 0; m < 4; ++m) _Pragma("unroll") for (int n = 0; n < 2; ++n) _Pragma("unroll") for (int k = 0; k < 2; ++k) \
;         acc[ai][bj][m][n] = __builtin_amdgcn_mfma_f32_16x16x32_bf16(Bt[n][k], At[m][k], acc[ai][bj][m][n], 0, 0, 0); __builtin_amdgcn_s_setprio(0); } while (0)
; #define PG8_WAIT_V(n) asm volatile("s_waitcnt vmcnt(" #n ")" ::: "memory")
; #define PG8_WAIT_L(n) asm volatile("s_waitcnt lgkmcnt(" #n ")" ::: "memory")
; #define PG8_BAR __builtin_amdgcn_s_barrier()
; #define PG8_SCHED __builtin_amdgcn_sched_barrier(0)
; template <class Epi, class Ptrs>
; __device__ __forceinline__ void gemm_phase(LAS unsigned char* lds, const int K, const StaticOrder& S, const Ptrs& P, const Epi& E) {
;     ...
;             PG8_WAIT_L(8); PG8_BAR; PG8_WAIT_L(0); PG8_MMA(0, 0, At, B0); PG8_BAR; PG8_SCHED;
;             PG8_LDB(B1, 1, 1); PG8_STAGE(PG8_SB(1, 0), b3, voffB);
;             PG8_BAR; PG8_WAIT_L(0); PG8_MMA(0, 1, At, B1); PG8_BAR;
;             PG8_LDA(At, 1, 1); PG8_STAGE(PG8_SA(1, 0), a3, voffA);
;             PG8_BAR; PG8_WAIT_L(0); PG8_MMA(1, 0, At, B0); PG8_BAR; PG8_SCHED;
;             PG8_STAGE(PG8_SB(1, 1), b3 + hstep, voffB);
;             PG8_WAIT_V(6); PG8_BAR; PG8_MMA(1, 1, At, B1); PG8_BAR;
	s_waitcnt lgkmcnt(0)
	v_mfma_f32_16x16x32_bf16 v[120:123], v[150:153], v[166:169], v[120:123]
	v_mfma_f32_16x16x32_bf16 v[120:123], v[154:157], v[170:173], v[120:123]
	v_mfma_f32_16x16x32_bf16 v[116:119], v[162:165], v[170:173], v[116:119]
	v_mfma_f32_16x16x32_bf16 v[116:119], v[158:161], v[166:169], v[116:119]
	v_mfma_f32_16x16x32_bf16 v[100:103], v[158:161], v[174:177], v[100:103]
	v_mfma_f32_16x16x32_bf16 v[100:103], v[162:165], v[178:181], v[100:103]
	v_mfma_f32_16x16x32_bf16 v[104:107], v[154:157], v[178:181], v[104:107]
	v_mfma_f32_16x16x32_bf16 v[104:107], v[150:153], v[174:177], v[104:107]
	v_mfma_f32_16x16x32_bf16 v[88:91], v[150:153], v[182:185], v[88:91]
	v_mfma_f32_16x16x32_bf16 v[88:91], v[154:157], v[186:189], v[88:91]
	v_mfma_f32_16x16x32_bf16 v[84:87], v[162:165], v[186:189], v[84:87]
	v_mfma_f32_16x16x32_bf16 v[84:87], v[158:161], v[182:185], v[84:87]
	v_mfma_f32_16x16x32_bf16 v[68:71], v[158:161], v[190:193], v[68:71]
	v_mfma_f32_16x16x32_bf16 v[68:71], v[162:165], v[194:197], v[68:71]
	v_mfma_f32_16x16x32_bf16 v[72:75], v[154:157], v[194:197], v[72:75]
	v_mfma_f32_16x16x32_bf16 v[72:75], v[150:153], v[190:193], v[72:75]
	s_barrier
	s_add_i32 s71, 0, 0x1c000
	s_add_i32 s69, s69, s65
	v_add_u32_e32 v140, s71, v131
	v_lshl_add_u64 v[202:203], v[202:203], 0, s[58:59]
	s_mov_b32 m0, s69
	ds_read_b128 v[198:201], v140
	ds_read_b128 v[210:213], v140 offset:1024
	ds_read_b128 v[214:217], v140 offset:2048
	ds_read_b128 v[218:221], v140 offset:3072
	global_load_lds_dwordx4 v[202:203], off
	v_lshl_add_u64 v[202:203], v[222:223], 0, s[58:59]
	s_add_i32 m0, s69, 0x2000
	s_nop 0
	global_load_lds_dwordx4 v[202:203], off
	s_barrier
	s_waitcnt lgkmcnt(0)
	v_mfma_f32_16x16x32_bf16 v[124:127], v[198:201], v[166:169], v[124:127]
	v_mfma_f32_16x16x32_bf16 v[124:127], v[210:213], v[170:173], v[124:127]
	v_mfma_f32_16x16x32_bf16 v[112:115], v[218:221], v[170:173], v[112:115]
	v_mfma_f32_16x16x32_bf16 v[112:115], v[214:217], v[166:169], v[112:115]
	v_mfma_f32_16x16x32_bf16 v[96:99], v[214:217], v[174:177], v[96:99]
	v_mfma_f32_16x16x32_bf16 v[96:99], v[218:221], v[178:181], v[96:99]
	v_mfma_f32_16x16x32_bf16 v[108:111], v[210:213], v[178:181], v[108:111]
	v_mfma_f32_16x16x32_bf16 v[108:111], v[198:201], v[174:177], v[108:111]
	v_mfma_f32_16x16x32_bf16 v[92:95], v[198:201], v[182:185], v[92:95]
	v_mfma_f32_16x16x32_bf16 v[92:95], v[210:213], v[186:189], v[92:95]
	v_mfma_f32_16x16x32_bf16 v[80:83], v[218:221], v[186:189], v[80:83]
	v_mfma_f32_16x16x32_bf16 v[80:83], v[214:217], v[182:185], v[80:83]
	v_mfma_f32_16x16x32_bf16 v[64:67], v[214:217], v[190:193], v[64:67]
	v_mfma_f32_16x16x32_bf16 v[64:67], v[218:221], v[194:197], v[64:67]
	v_mfma_f32_16x16x32_bf16 v[76:79], v[210:213], v[194:197], v[76:79]
	v_mfma_f32_16x16x32_bf16 v[76:79], v[198:201], v[190:193], v[76:79]
	s_mov_b32 m0, s89
	v_lshl_add_u64 v[202:203], v[224:225], 0, s[58:59]
	s_barrier
	ds_read_b128 v[166:169], v206 offset:49152
	ds_read_b128 v[170:173], v206 offset:50176
	ds_read_b128 v[174:177], v206 offset:51200
	ds_read_b128 v[178:181], v206 offset:52224
	ds_read_b128 v[182:185], v206 offset:53248
	ds_read_b128 v[186:189], v206 offset:54272
	ds_read_b128 v[190:193], v206 offset:55296
	ds_read_b128 v[194:197], v206 offset:56320
	global_load_lds_dwordx4 v[202:203], off
	v_lshl_add_u64 v[202:203], v[226:227], 0, s[58:59]
	s_mov_b32 m0, s90
	s_nop 0
	global_load_lds_dwordx4 v[202:203], off
	s_barrier
	s_waitcnt lgkmcnt(0)
	v_mfma_f32_16x16x32_bf16 v[56:59], v[150:153], v[166:169], v[56:59]
	v_mfma_f32_16x16x32_bf16 v[56:59], v[154:157], v[170:173], v[56:59]
	v_mfma_f32_16x16x32_bf16 v[52:55], v[162:165], v[170:173], v[52:55]
	v_mfma_f32_16x16x32_bf16 v[52:55], v[158:161], v[166:169], v[52:55]
	v_mfma_f32_16x16x32_bf16 v[36:39], v[158:161], v[174:177], v[36:39]
	v_mfma_f32_16x16x32_bf16 v[36:39], v[162:165], v[178:181], v[36:39]
	v_mfma_f32_16x16x32_bf16 v[40:43], v[154:157], v[178:181], v[40:43]
	v_mfma_f32_16x16x32_bf16 v[40:43], v[150:153], v[174:177], v[40:43]
	v_mfma_f32_16x16x32_bf16 v[24:27], v[150:153], v[182:185], v[24:27]
	v_mfma_f32_16x16x32_bf16 v[24:27], v[154:157], v[186:189], v[24:27]
	v_mfma_f32_16x16x32_bf16 v[20:23], v[162:165], v[186:189], v[20:23]
	v_mfma_f32_16x16x32_bf16 v[20:23], v[158:161], v[182:185], v[20:23]
	v_mfma_f32_16x16x32_bf16 v[4:7], v[158:161], v[190:193], v[4:7]
	v_mfma_f32_16x16x32_bf16 v[4:7], v[162:165], v[194:197], v[4:7]
	v_mfma_f32_16x16x32_bf16 v[8:11], v[154:157], v[194:197], v[8:11]
	v_mfma_f32_16x16x32_bf16 v[8:11], v[150:153], v[190:193], v[8:11]
	s_barrier
	s_add_u32 s78, s78, 0x40080
	s_addc_u32 s79, s79, 0
	s_add_i32 s69, s71, s65
	s_mov_b32 m0, s69
	s_nop 0
	global_load_lds_dwordx4 v134, s[78:79]
	s_add_i32 m0, s69, 0x2000
	s_nop 0
	global_load_lds_dwordx4 v138, s[78:79]
	s_waitcnt vmcnt(6)
	s_barrier
	v_mfma_f32_16x16x32_bf16 v[60:63], v[198:201], v[166:169], v[60:63]
	v_mfma_f32_16x16x32_bf16 v[60:63], v[210:213], v[170:173], v[60:63]
	v_mfma_f32_16x16x32_bf16 v[48:51], v[218:221], v[170:173], v[48:51]
	v_mfma_f32_16x16x32_bf16 v[48:51], v[214:217], v[166:169], v[48:51]
	v_mfma_f32_16x16x32_bf16 v[32:35], v[214:217], v[174:177], v[32:35]
	v_mfma_f32_16x16x32_bf16 v[32:35], v[218:221], v[178:181], v[32:35]
	v_mfma_f32_16x16x32_bf16 v[44:47], v[210:213], v[178:181], v[44:47]
	v_mfma_f32_16x16x32_bf16 v[44:47], v[198:201], v[174:177], v[44:47]
	v_mfma_f32_16x16x32_bf16 v[28:31], v[198:201], v[182:185], v[28:31]
	v_mfma_f32_16x16x32_bf16 v[28:31], v[210:213], v[186:189], v[28:31]
	v_mfma_f32_16x16x32_bf16 v[16:19], v[218:221], v[186:189], v[16:19]
	v_mfma_f32_16x16x32_bf16 v[16:19], v[214:217], v[182:185], v[16:19]
	v_mfma_f32_16x16x32_bf16 v[0:3], v[214:217], v[190:193], v[0:3]
	v_mfma_f32_16x16x32_bf16 v[0:3], v[218:221], v[194:197], v[0:3]
	v_mfma_f32_16x16x32_bf16 v[12:15], v[210:213], v[194:197], v[12:15]
	v_mfma_f32_16x16x32_bf16 v[12:15], v[198:201], v[190:193], v[12:15]
	s_add_i32 s63, s63, 2
	s_add_u32 s6, s6, 0x100
	s_addc_u32 s7, s7, 0
	s_add_u32 s20, s20, 0x100
	s_addc_u32 s25, s25, 0
	s_cmp_gt_u32 s63, 13
	s_barrier
	s_cbranch_scc0 .LBB0_127
	s_nop 0
	s_nop 0
	s_nop 0
	s_nop 0
	s_nop 0
	s_nop 0
	s_nop 0
	s_nop 0
	s_nop 0
	s_nop 0
	s_nop 0
	s_nop 0
	s_nop 0
	s_nop 0
	s_nop 0
	s_nop 0
	s_nop 0
	s_nop 0
	s_nop 0
	s_nop 0
	s_nop 0
	s_nop 0
	s_nop 0
	s_nop 0
	s_nop 0
	s_nop 0
	s_nop 0
	s_nop 0
	s_nop 0
	s_nop 0
	s_nop 0
	s_nop 0
	s_nop 0
	s_nop 0
	s_nop 0
	s_nop 0
	s_nop 0
	s_nop 0
	s_cmp_gt_i32 s74, 7
	s_mov_b64 s[6:7], -1
	s_cbranch_scc0 .LBB0_188
	s_sub_i32 s25, s74, 17
	s_cmp_gt_u32 s25, 3
	s_cbranch_scc0 .LBB0_170
	s_lshl_b32 s69, s76, 8
	s_cmp_gt_u32 s74, 11
	s_cbranch_scc0 .LBB0_135
	s_cmp_eq_u32 s74, 12
	s_mov_b64 s[6:7], 0
	s_cbranch_scc1 .LBB0_134
	s_cmp_gt_u32 s74, 16
	s_cbranch_scc1 .LBB0_191
	s_lshl_b32 s20, s74, 8
	v_readlane_b32 s80, v254, 2
	s_addk_i32 s20, 0xf300
	s_mov_b64 s[78:79], 0x400
	s_mov_b64 s[82:83], -1
	s_mov_b32 s63, s69
	v_readlane_b32 s81, v254, 3
	s_andn2_b64 vcc, exec, s[6:7]
	s_cbranch_vccz .LBB0_136
	s_branch .LBB0_137

; __device__ __forceinline__ unsigned xb_ld(unsigned* p)              { return __hip_atomic_load(p, __ATOMIC_RELAXED, __HIP_MEMORY_SCOPE_AGENT); }
; __device__ __forceinline__ void xcd_barrier_complete(unsigned* bar, unsigned x, unsigned& nloc, unsigned& nx) {
;     const unsigned G = gridDim.x * gridDim.y * gridDim.z;
;     unsigned sum, cnt, mine, sp = 0u;
;     for (;;) {
;         sum = 0u; cnt = 0u; mine = 0u;
; #pragma unroll
;         for (unsigned j = 0; j < 16; ++j) { const unsigned c = xb_ld(&bar[XB_XCNT(j)]); sum += c; cnt += (c > 0u) ? 1u : 0u; mine = (j == x) ? c : mine; }
; __device__ __forceinline__ void xcd_barrier(const XcdBarrier& b) {
;     asm volatile("s_waitcnt vmcnt(0)" ::: "memory");
;     __syncthreads();
;     if (threadIdx.x == 0) {
;         unsigned* bar = b.bar;
;         __builtin_amdgcn_s_waitcnt(0);
;         unsigned nloc = b.st[0], nx = b.st[1];
;         if (nloc == 0u) { xcd_barrier_complete(bar, b.x, nloc, nx); b.st[0] = nloc; b.st[1] = nx; }
.LBB0_195:
	s_nop 0
	s_nop 0
	s_nop 0
	s_nop 0
	s_nop 0
	s_nop 0
	s_nop 0
	s_nop 0
	s_nop 0
	s_nop 0
	s_nop 0
	s_nop 0
	s_nop 0
	s_nop 0
	s_nop 0
	s_nop 0
	s_nop 0
	s_nop 0
	s_nop 0
	s_nop 0
	s_nop 0
	s_nop 0
	s_nop 0
	s_nop 0
	s_nop 0
	s_nop 0
	s_nop 0
	s_nop 0
	s_nop 0
	s_nop 0
	s_nop 0
	s_nop 0
	s_nop 0
	s_nop 0
	s_nop 0
	s_nop 0
	s_nop 0
	s_nop 0
	s_nop 0
	s_nop 0
	s_nop 0
	s_nop 0
	s_nop 0
	s_nop 0
	s_nop 0
	s_nop 0
	s_nop 0
	s_nop 0
	s_nop 0
	s_nop 0
	s_nop 0
	s_nop 0
	s_nop 0
	s_nop 0
	s_nop 0
	s_nop 0
	s_nop 0
	s_nop 0
	s_nop 0
	s_nop 0
	s_nop 0
	s_nop 0
	s_nop 0
	s_cmp_gt_i32 s31, 2
	s_cselect_b64 s[0:1], -1, 0
	s_and_b64 s[4:5], s[18:19], s[0:1]
	s_andn2_b64 vcc, exec, s[4:5]
	s_cbranch_vccnz .LBB0_245
	s_waitcnt vmcnt(0)
	s_waitcnt vmcnt(0) lgkmcnt(0)
	s_barrier
	s_and_saveexec_b64 s[4:5], s[8:9]
	s_cbranch_execz .LBB0_244
	s_add_i32 s6, 0, 0x25ff0
	v_mov_b32_e32 v0, s6
	s_waitcnt vmcnt(0) expcnt(0) lgkmcnt(0)
	ds_read_b32 v2, v0
	s_add_i32 s6, 0, 0x25ff4
	v_mov_b32_e32 v0, s6
	ds_read_b32 v0, v0
	s_waitcnt lgkmcnt(1)
	v_cmp_ne_u32_e32 vcc, 0, v2
	s_cbranch_vccnz .LBB0_212
	s_load_dwordx2 s[18:19], s[52:53], 0x4
	s_add_u32 s6, s28, 0x3e800200
	s_addc_u32 s7, s29, 0
	s_add_u32 s10, s28, 0x3e800400
	s_addc_u32 s11, s29, 0
	s_waitcnt lgkmcnt(0)
	s_mul_i32 s76, s18, s3
	s_add_u32 s18, s28, 0x3e800500
	s_mul_i32 s76, s76, s19
	s_addc_u32 s19, s29, 0
	s_add_u32 s20, s28, 0x3e800600
	s_addc_u32 s21, s29, 0
	s_add_u32 s22, s28, 0x3e800700
	s_addc_u32 s23, s29, 0
	s_add_u32 s24, s28, 0x3e800800
	s_addc_u32 s25, s29, 0
	s_add_u32 s42, s28, 0x3e800900
	s_addc_u32 s43, s29, 0
	s_add_u32 s44, s28, 0x3e800a00
	s_addc_u32 s45, s29, 0
	s_add_u32 s48, s28, 0x3e800b00
	s_addc_u32 s49, s29, 0
	s_add_u32 s54, s28, 0x3e800c00
	s_addc_u32 s55, s29, 0
	s_add_u32 s56, s28, 0x3e800d00
	s_addc_u32 s57, s29, 0
	s_add_u32 s58, s28, 0x3e800e00
	s_addc_u32 s59, s29, 0
	s_add_u32 s60, s28, 0x3e800f00
	s_addc_u32 s61, s29, 0
	s_add_u32 s62, s28, 0x3e801000
	s_addc_u32 s63, s29, 0
	s_add_u32 s64, s28, 0x3e801100
	s_addc_u32 s65, s29, 0
	s_add_u32 s66, s28, 0x3e801200
	s_addc_u32 s67, s29, 0
	s_add_u32 s68, s28, 0x3e801300
	s_addc_u32 s69, s29, 0
	s_mov_b32 s77, 1
	v_mov_b32_e32 v16, 0
	s_branch .LBB0_200

; #define PG8_STAGE(bufoff, gbase, voff) do { _Pragma("unroll") for (int _i = 0; _i < 2; ++_i) \
;         __builtin_amdgcn_global_load_lds((const unsigned*)((const char*)(gbase) + (voff)[_i]), (LAS unsigned*)(lds + (bufoff) + ldsw + _i * 8192), 16, 0, 0); } while (0)
; #define PG8_LDA(dst, b, h) do { _Pragma("unroll") for (int m = 0; m < 4; ++m) _Pragma("unroll") for (int k = 0; k < 2; ++k) dst[m][k] = *(const LAS bf16x8*)(lds + PG8_SA(b, h) + aoff + m * 2048 + k * 1024); } while (0)
; #define PG8_LDB(dst, b, h) do { _Pragma("unroll") for (int n = 0; n < 2; ++n) _Pragma("unroll") for (int k = 0; k < 2; ++k) dst[n][k] = *(const LAS bf16x8*)(lds + PG8_SB(b, h) + boff + n * 2048 + k * 1024); } while (0)
; #define PG8_MMA(ai, bj, At, Bt) do { __builtin_amdgcn_s_setprio(1); _Pragma("unroll") for (int m = 0; m < 4; ++m) _Pragma("unroll") for (int n = 0; n < 2; ++n) _Pragma("unroll") for (int k = 0; k < 2; ++k) \
;         acc[ai][bj][m][n] = __builtin_amdgcn_mfma_f32_16x16x32_bf16(Bt[n][k], At[m][k], acc[ai][bj][m][n], 0, 0, 0); __builtin_amdgcn_s_setprio(0); } while (0)
; #define PG8_WAIT_L(n) asm volatile("s_waitcnt lgkmcnt(" #n ")" ::: "memory")
; #define PG8_BAR __builtin_amdgcn_s_barrier()
; #define PG8_SCHED __builtin_amdgcn_sched_barrier(0)
; template <class Epi, class Ptrs>
; __device__ __forceinline__ void gemm_phase(LAS unsigned char* lds, const int K, const StaticOrder& S, const Ptrs& P, const Epi& E) {
;     ...
;         for (int t = 0; t < nt; t += 2) {
;             const bool last = (t == nt - 2);
;             const char* a1 = cA + (size_t)(t + 1) * kstep;
;             const char* a2 = last ? nA : cA + (size_t)(t + 2) * kstep; const char* b2 = last ? nB : cB + (size_t)(t + 2) * kstep;
;             const char* a3 = a2 + kstep; const char* b3 = b2 + kstep;
;             PG8_LDB(B0, 0, 0); PG8_SCHED; PG8_LDA(At, 0, 0); PG8_STAGE(PG8_SA(1, 1), a1 + hstep, voffA);
;             PG8_WAIT_L(8); PG8_BAR; PG8_WAIT_L(0); PG8_MMA(0, 0, At, B0); PG8_BAR; PG8_SCHED;
;     ...
; #pragma unroll
;         for (int a = 0; a < 2; ++a)
; #pragma unroll
;             for (int b = 0; b < 2; ++b)
; #pragma unroll
;                 for (int m = 0; m < 4; ++m)
; #pragma unroll
;                     for (int n = 0; n < 2; ++n) acc[a][b][m][n] = (f32x4){0.f, 0.f, 0.f, 0.f};
.LBB0_352:
	s_add_u32 s38, s44, 0x40080
	s_nop 0
	s_nop 0
	s_nop 0
	s_nop 0
	s_nop 0
	s_nop 0
	s_nop 0
	s_nop 0
	s_nop 0
	s_nop 0
	s_nop 0
	s_nop 0
	s_nop 0
	s_nop 0
	s_nop 0
	s_nop 0
	s_nop 0
	s_nop 0
	s_nop 0
	s_nop 0
	s_nop 0
	s_nop 0
	s_nop 0
	s_nop 0
	s_nop 0
	s_nop 0
	s_nop 0
	s_nop 0
	s_nop 0
	s_nop 0
	s_nop 0
	s_nop 0
	s_nop 0
	s_nop 0
	s_nop 0
	s_nop 0
	s_nop 0
	s_nop 0
	s_nop 0
	s_nop 0
	s_nop 0
	s_nop 0
	s_nop 0
	s_nop 0
	s_nop 0
	s_nop 0
	s_nop 0
	s_nop 0
	s_nop 0
	s_nop 0
	s_nop 0
	s_nop 0
	s_nop 0
	s_nop 0
	s_nop 0
	s_nop 0
	s_nop 0
	s_nop 0
	s_nop 0
	s_nop 0
	s_nop 0
	s_addc_u32 s39, s45, 0
	s_add_u32 s21, s42, 0x100
	v_mov_b32_e32 v0, 0
	s_addc_u32 s23, s43, 0
	s_mov_b32 s41, -2
	v_mov_b32_e32 v1, v0
	v_mov_b32_e32 v2, v0
	v_mov_b32_e32 v3, v0
	v_mov_b32_e32 v4, v0
	v_mov_b32_e32 v5, v0
	v_mov_b32_e32 v6, v0
	v_mov_b32_e32 v7, v0
	v_mov_b32_e32 v16, v0
	v_mov_b32_e32 v17, v0
	v_mov_b32_e32 v18, v0
	v_mov_b32_e32 v19, v0
	v_mov_b32_e32 v20, v0
	v_mov_b32_e32 v21, v0
	v_mov_b32_e32 v22, v0
	v_mov_b32_e32 v23, v0
	v_mov_b32_e32 v32, v0
	v_mov_b32_e32 v33, v0
	v_mov_b32_e32 v34, v0
	v_mov_b32_e32 v35, v0
	v_mov_b32_e32 v36, v0
	v_mov_b32_e32 v37, v0
	v_mov_b32_e32 v38, v0
	v_mov_b32_e32 v39, v0
	v_mov_b32_e32 v48, v0
	v_mov_b32_e32 v49, v0
	v_mov_b32_e32 v50, v0
	v_mov_b32_e32 v51, v0
	v_mov_b32_e32 v52, v0
	v_mov_b32_e32 v53, v0
	v_mov_b32_e32 v54, v0
	v_mov_b32_e32 v55, v0
	v_mov_b32_e32 v8, v0
	v_mov_b32_e32 v9, v0
	v_mov_b32_e32 v10, v0
	v_mov_b32_e32 v11, v0
	v_mov_b32_e32 v12, v0
	v_mov_b32_e32 v13, v0
	v_mov_b32_e32 v14, v0
	v_mov_b32_e32 v15, v0
	v_mov_b32_e32 v24, v0
	v_mov_b32_e32 v25, v0
	v_mov_b32_e32 v26, v0
	v_mov_b32_e32 v27, v0
	v_mov_b32_e32 v28, v0
	v_mov_b32_e32 v29, v0
	v_mov_b32_e32 v30, v0
	v_mov_b32_e32 v31, v0
	v_mov_b32_e32 v40, v0
	v_mov_b32_e32 v41, v0
	v_mov_b32_e32 v42, v0
	v_mov_b32_e32 v43, v0
	v_mov_b32_e32 v44, v0
	v_mov_b32_e32 v45, v0
	v_mov_b32_e32 v46, v0
	v_mov_b32_e32 v47, v0
	v_mov_b32_e32 v56, v0
	v_mov_b32_e32 v57, v0
	v_mov_b32_e32 v58, v0
	v_mov_b32_e32 v59, v0
	v_mov_b32_e32 v60, v0
	v_mov_b32_e32 v61, v0
	v_mov_b32_e32 v62, v0
	v_mov_b32_e32 v63, v0
	v_mov_b32_e32 v64, v0
	v_mov_b32_e32 v65, v0
	v_mov_b32_e32 v66, v0
	v_mov_b32_e32 v67, v0
	v_mov_b32_e32 v68, v0
	v_mov_b32_e32 v69, v0
	v_mov_b32_e32 v70, v0
	v_mov_b32_e32 v71, v0
	v_mov_b32_e32 v80, v0
	v_mov_b32_e32 v81, v0
	v_mov_b32_e32 v82, v0
	v_mov_b32_e32 v83, v0
	v_mov_b32_e32 v84, v0
	v_mov_b32_e32 v85, v0
	v_mov_b32_e32 v86, v0
	v_mov_b32_e32 v87, v0
	v_mov_b32_e32 v96, v0
	v_mov_b32_e32 v97, v0
	v_mov_b32_e32 v98, v0
	v_mov_b32_e32 v99, v0
	v_mov_b32_e32 v100, v0
	v_mov_b32_e32 v101, v0
	v_mov_b32_e32 v102, v0
	v_mov_b32_e32 v103, v0
	v_mov_b32_e32 v112, v0
	v_mov_b32_e32 v113, v0
	v_mov_b32_e32 v114, v0
	v_mov_b32_e32 v115, v0
	v_mov_b32_e32 v116, v0
	v_mov_b32_e32 v117, v0
	v_mov_b32_e32 v118, v0
	v_mov_b32_e32 v119, v0
	v_mov_b32_e32 v72, v0
	v_mov_b32_e32 v73, v0
	v_mov_b32_e32 v74, v0
	v_mov_b32_e32 v75, v0
	v_mov_b32_e32 v76, v0
	v_mov_b32_e32 v77, v0
	v_mov_b32_e32 v78, v0
	v_mov_b32_e32 v79, v0
	v_mov_b32_e32 v88, v0
	v_mov_b32_e32 v89, v0
	v_mov_b32_e32 v90, v0
	v_mov_b32_e32 v91, v0
	v_mov_b32_e32 v92, v0
	v_mov_b32_e32 v93, v0
	v_mov_b32_e32 v94, v0
	v_mov_b32_e32 v95, v0
	v_mov_b32_e32 v104, v0
	v_mov_b32_e32 v105, v0
	v_mov_b32_e32 v106, v0
	v_mov_b32_e32 v107, v0
	v_mov_b32_e32 v108, v0
	v_mov_b32_e32 v109, v0
	v_mov_b32_e32 v110, v0
	v_mov_b32_e32 v111, v0
	v_mov_b32_e32 v120, v0
	v_mov_b32_e32 v121, v0
	v_mov_b32_e32 v122, v0
	v_mov_b32_e32 v123, v0
	v_mov_b32_e32 v124, v0
	v_mov_b32_e32 v125, v0
	v_mov_b32_e32 v126, v0
	v_mov_b32_e32 v127, v0
.LBB0_353:
	ds_read_b128 v[128:131], v207
	ds_read_b128 v[132:135], v207 offset:1024
	ds_read_b128 v[136:139], v207 offset:2048
	ds_read_b128 v[140:143], v207 offset:3072
	s_add_u32 s42, s38, 0xfffc0080
	s_addc_u32 s43, s39, -1
	s_cmp_eq_u32 s41, 12
	s_cselect_b32 s45, s1, s43
	s_cselect_b32 s44, s0, s42
	s_cselect_b32 s43, s25, s23
	s_cselect_b32 s42, s24, s21
	s_add_i32 m0, s54, 0xc000
	ds_read_b128 v[144:147], v209
	ds_read_b128 v[148:151], v209 offset:1024
	ds_read_b128 v[152:155], v209 offset:2048
	ds_read_b128 v[156:159], v209 offset:3072
	ds_read_b128 v[160:163], v209 offset:4096
	ds_read_b128 v[164:167], v209 offset:5120
	ds_read_b128 v[168:171], v209 offset:6144
	ds_read_b128 v[172:175], v209 offset:7168
	global_load_lds_dwordx4 v184, s[38:39]
	s_add_i32 m0, s54, 0xe000
	s_nop 0
	global_load_lds_dwordx4 v186, s[38:39]
	s_waitcnt lgkmcnt(8)
	s_barrier
	s_waitcnt lgkmcnt(0)
	v_mfma_f32_16x16x32_bf16 v[124:127], v[128:131], v[144:147], v[124:127]
	v_mfma_f32_16x16x32_bf16 v[124:127], v[132:135], v[148:151], v[124:127]
	v_mfma_f32_16x16x32_bf16 v[120:123], v[140:143], v[148:151], v[120:123]
	v_mfma_f32_16x16x32_bf16 v[120:123], v[136:139], v[144:147], v[120:123]
	v_mfma_f32_16x16x32_bf16 v[104:107], v[136:139], v[152:155], v[104:107]
	v_mfma_f32_16x16x32_bf16 v[104:107], v[140:143], v[156:159], v[104:107]
	v_mfma_f32_16x16x32_bf16 v[108:111], v[132:135], v[156:159], v[108:111]
	v_mfma_f32_16x16x32_bf16 v[108:111], v[128:131], v[152:155], v[108:111]
	v_mfma_f32_16x16x32_bf16 v[92:95], v[128:131], v[160:163], v[92:95]
	v_mfma_f32_16x16x32_bf16 v[92:95], v[132:135], v[164:167], v[92:95]
	v_mfma_f32_16x16x32_bf16 v[88:91], v[140:143], v[164:167], v[88:91]
	v_mfma_f32_16x16x32_bf16 v[88:91], v[136:139], v[160:163], v[88:91]
	v_mfma_f32_16x16x32_bf16 v[72:75], v[136:139], v[168:171], v[72:75]
	v_mfma_f32_16x16x32_bf16 v[72:75], v[140:143], v[172:175], v[72:75]
	v_mfma_f32_16x16x32_bf16 v[76:79], v[132:135], v[172:175], v[76:79]
	v_mfma_f32_16x16x32_bf16 v[76:79], v[128:131], v[168:171], v[76:79]
	s_barrier
; #define PG8_STAGE(bufoff, gbase, voff) do { _Pragma("unroll") for (int _i = 0; _i < 2; ++_i) \
;         __builtin_amdgcn_global_load_lds((const unsigned*)((const char*)(gbase) + (voff)[_i]), (LAS unsigned*)(lds + (bufoff) + ldsw + _i * 8192), 16, 0, 0); } while (0)
; #define PG8_LDA(dst, b, h) do { _Pragma("unroll") for (int m = 0; m < 4; ++m) _Pragma("unroll") for (int k = 0; k < 2; ++k) dst[m][k] = *(const LAS bf16x8*)(lds + PG8_SA(b, h) + aoff + m * 2048 + k * 1024); } while (0)
; #define PG8_LDB(dst, b, h) do { _Pragma("unroll") for (int n = 0; n < 2; ++n) _Pragma("unroll") for (int k = 0; k < 2; ++k) dst[n][k] = *(const LAS bf16x8*)(lds + PG8_SB(b, h) + boff + n * 2048 + k * 1024); } while (0)
; #define PG8_MMA(ai, bj, At, Bt) do { __builtin_amdgcn_s_setprio(1); _Pragma("unroll") for (int m = 0; m < 4; ++m) _Pragma("unroll") for (int n = 0; n < 2; ++n) _Pragma("unroll") for (int k = 0; k < 2; ++k) \
;         acc[ai][bj][m][n] = __builtin_amdgcn_mfma_f32_16x16x32_bf16(Bt[n][k], At[m][k], acc[ai][bj][m][n], 0, 0, 0); __builtin_amdgcn_s_setprio(0); } while (0)
; #define PG8_WAIT_V(n) asm volatile("s_waitcnt vmcnt(" #n ")" ::: "memory")
; #define PG8_WAIT_L(n) asm volatile("s_waitcnt lgkmcnt(" #n ")" ::: "memory")
; #define PG8_BAR __builtin_amdgcn_s_barrier()
; #define PG8_SCHED __builtin_amdgcn_sched_barrier(0)
; template <class Epi, class Ptrs>
; __device__ __forceinline__ void gemm_phase(LAS unsigned char* lds, const int K, const StaticOrder& S, const Ptrs& P, const Epi& E) {
;     ...
;             PG8_LDB(B1, 0, 1); PG8_STAGE(PG8_SB(0, 0), b2, voffB);
;             PG8_BAR; PG8_WAIT_L(0); PG8_MMA(0, 1, At, B1); PG8_BAR;
;             PG8_LDA(At, 0, 1); PG8_STAGE(PG8_SA(0, 0), a2, voffA);
;             PG8_BAR; PG8_WAIT_L(0); PG8_MMA(1, 0, At, B0); PG8_BAR; PG8_SCHED;
;             PG8_STAGE(PG8_SB(0, 1), b2 + hstep, voffB);
;             PG8_WAIT_V(6); PG8_BAR; PG8_MMA(1, 1, At, B1); PG8_BAR;
;             PG8_LDB(B0, 1, 0); PG8_SCHED; PG8_LDA(At, 1, 0); PG8_STAGE(PG8_SA(0, 1), a2 + hstep, voffA);
;             PG8_WAIT_L(8); PG8_BAR; PG8_WAIT_L(0); PG8_MMA(0, 0, At, B0); PG8_BAR; PG8_SCHED;
	s_add_i32 s69, s66, s51
	v_lshl_add_u64 v[216:217], s[42:43], 0, v[178:179]
	s_mov_b32 m0, s69
	ds_read_b128 v[192:195], v210
	ds_read_b128 v[196:199], v210 offset:1024
	ds_read_b128 v[200:203], v210 offset:2048
	ds_read_b128 v[212:215], v210 offset:3072
	global_load_lds_dwordx4 v[216:217], off
	v_lshl_add_u64 v[218:219], s[42:43], 0, v[182:183]
	s_add_i32 m0, s69, 0x2000
	s_nop 0
	global_load_lds_dwordx4 v[218:219], off
	s_barrier
	s_waitcnt lgkmcnt(0)
	v_mfma_f32_16x16x32_bf16 v[116:119], v[192:195], v[144:147], v[116:119]
	v_mfma_f32_16x16x32_bf16 v[116:119], v[196:199], v[148:151], v[116:119]
	v_mfma_f32_16x16x32_bf16 v[112:115], v[212:215], v[148:151], v[112:115]
	v_mfma_f32_16x16x32_bf16 v[112:115], v[200:203], v[144:147], v[112:115]
	v_mfma_f32_16x16x32_bf16 v[96:99], v[200:203], v[152:155], v[96:99]
	v_mfma_f32_16x16x32_bf16 v[96:99], v[212:215], v[156:159], v[96:99]
	v_mfma_f32_16x16x32_bf16 v[100:103], v[196:199], v[156:159], v[100:103]
	v_mfma_f32_16x16x32_bf16 v[100:103], v[192:195], v[152:155], v[100:103]
	v_mfma_f32_16x16x32_bf16 v[84:87], v[192:195], v[160:163], v[84:87]
	v_mfma_f32_16x16x32_bf16 v[84:87], v[196:199], v[164:167], v[84:87]
	v_mfma_f32_16x16x32_bf16 v[80:83], v[212:215], v[164:167], v[80:83]
	v_mfma_f32_16x16x32_bf16 v[80:83], v[200:203], v[160:163], v[80:83]
	v_mfma_f32_16x16x32_bf16 v[64:67], v[200:203], v[168:171], v[64:67]
	v_mfma_f32_16x16x32_bf16 v[64:67], v[212:215], v[172:175], v[64:67]
	v_mfma_f32_16x16x32_bf16 v[68:71], v[196:199], v[172:175], v[68:71]
	v_mfma_f32_16x16x32_bf16 v[68:71], v[192:195], v[168:171], v[68:71]
	s_mov_b32 m0, s54
	v_lshl_add_u64 v[220:221], s[44:45], 0, v[176:177]
	s_barrier
	ds_read_b128 v[144:147], v209 offset:16384
	ds_read_b128 v[148:151], v209 offset:17408
	ds_read_b128 v[152:155], v209 offset:18432
	ds_read_b128 v[156:159], v209 offset:19456
	ds_read_b128 v[160:163], v209 offset:20480
	ds_read_b128 v[164:167], v209 offset:21504
	ds_read_b128 v[168:171], v209 offset:22528
	ds_read_b128 v[172:175], v209 offset:23552
	global_load_lds_dwordx4 v[220:221], off
	v_lshl_add_u64 v[222:223], s[44:45], 0, v[180:181]
	s_mov_b32 m0, s55
	s_nop 0
	global_load_lds_dwordx4 v[222:223], off
	s_barrier
	s_waitcnt lgkmcnt(0)
	v_mfma_f32_16x16x32_bf16 v[60:63], v[128:131], v[144:147], v[60:63]
	v_mfma_f32_16x16x32_bf16 v[60:63], v[132:135], v[148:151], v[60:63]
	v_mfma_f32_16x16x32_bf16 v[56:59], v[140:143], v[148:151], v[56:59]
	v_mfma_f32_16x16x32_bf16 v[56:59], v[136:139], v[144:147], v[56:59]
	v_mfma_f32_16x16x32_bf16 v[40:43], v[136:139], v[152:155], v[40:43]
	v_mfma_f32_16x16x32_bf16 v[40:43], v[140:143], v[156:159], v[40:43]
	v_mfma_f32_16x16x32_bf16 v[44:47], v[132:135], v[156:159], v[44:47]
	v_mfma_f32_16x16x32_bf16 v[44:47], v[128:131], v[152:155], v[44:47]
	v_mfma_f32_16x16x32_bf16 v[28:31], v[128:131], v[160:163], v[28:31]
	v_mfma_f32_16x16x32_bf16 v[28:31], v[132:135], v[164:167], v[28:31]
	v_mfma_f32_16x16x32_bf16 v[24:27], v[140:143], v[164:167], v[24:27]
	v_mfma_f32_16x16x32_bf16 v[24:27], v[136:139], v[160:163], v[24:27]
	v_mfma_f32_16x16x32_bf16 v[8:11], v[136:139], v[168:171], v[8:11]
	v_mfma_f32_16x16x32_bf16 v[8:11], v[140:143], v[172:175], v[8:11]
	v_mfma_f32_16x16x32_bf16 v[12:15], v[132:135], v[172:175], v[12:15]
	v_mfma_f32_16x16x32_bf16 v[12:15], v[128:131], v[168:171], v[12:15]
	s_barrier
	s_add_u32 s70, s42, 0x40000
	s_addc_u32 s71, s43, 0
	s_add_i32 s69, s67, s51
	s_mov_b32 m0, s69
	s_nop 0
	global_load_lds_dwordx4 v178, s[70:71]
	s_add_i32 m0, s69, 0x2000
	s_nop 0
	global_load_lds_dwordx4 v182, s[70:71]
	s_waitcnt vmcnt(6)
	s_barrier
	v_mfma_f32_16x16x32_bf16 v[52:55], v[192:195], v[144:147], v[52:55]
	v_mfma_f32_16x16x32_bf16 v[52:55], v[196:199], v[148:151], v[52:55]
	v_mfma_f32_16x16x32_bf16 v[48:51], v[212:215], v[148:151], v[48:51]
	v_mfma_f32_16x16x32_bf16 v[48:51], v[200:203], v[144:147], v[48:51]
	v_mfma_f32_16x16x32_bf16 v[32:35], v[200:203], v[152:155], v[32:35]
	v_mfma_f32_16x16x32_bf16 v[32:35], v[212:215], v[156:159], v[32:35]
	v_mfma_f32_16x16x32_bf16 v[36:39], v[196:199], v[156:159], v[36:39]
	v_mfma_f32_16x16x32_bf16 v[36:39], v[192:195], v[152:155], v[36:39]
	v_mfma_f32_16x16x32_bf16 v[20:23], v[192:195], v[160:163], v[20:23]
	v_mfma_f32_16x16x32_bf16 v[20:23], v[196:199], v[164:167], v[20:23]
	v_mfma_f32_16x16x32_bf16 v[16:19], v[212:215], v[164:167], v[16:19]
	v_mfma_f32_16x16x32_bf16 v[16:19], v[200:203], v[160:163], v[16:19]
	v_mfma_f32_16x16x32_bf16 v[0:3], v[200:203], v[168:171], v[0:3]
	v_mfma_f32_16x16x32_bf16 v[0:3], v[212:215], v[172:175], v[0:3]
	v_mfma_f32_16x16x32_bf16 v[4:7], v[196:199], v[172:175], v[4:7]
	v_mfma_f32_16x16x32_bf16 v[4:7], v[192:195], v[168:171], v[4:7]
	s_add_i32 s69, 0, 0x18000
	v_add_u32_e32 v140, s69, v205
	s_barrier
	ds_read_b128 v[128:131], v140
	ds_read_b128 v[132:135], v140 offset:1024
	ds_read_b128 v[136:139], v140 offset:2048
	ds_read_b128 v[140:143], v140 offset:3072
	s_add_u32 s44, s44, 0x40000
	s_addc_u32 s45, s45, 0
	s_mov_b32 m0, s56
	ds_read_b128 v[144:147], v209 offset:32768
	ds_read_b128 v[148:151], v209 offset:33792
	ds_read_b128 v[152:155], v209 offset:34816
	ds_read_b128 v[156:159], v209 offset:35840
	ds_read_b128 v[160:163], v209 offset:36864
	ds_read_b128 v[164:167], v209 offset:37888
	ds_read_b128 v[168:171], v209 offset:38912
	ds_read_b128 v[172:175], v209 offset:39936
	global_load_lds_dwordx4 v176, s[44:45]
	s_mov_b32 m0, s57
	s_nop 0
	global_load_lds_dwordx4 v180, s[44:45]
	s_waitcnt lgkmcnt(8)
	s_barrier
; #define PG8_STAGE(bufoff, gbase, voff) do { _Pragma("unroll") for (int _i = 0; _i < 2; ++_i) \
;         __builtin_amdgcn_global_load_lds((const unsigned*)((const char*)(gbase) + (voff)[_i]), (LAS unsigned*)(lds + (bufoff) + ldsw + _i * 8192), 16, 0, 0); } while (0)
; #define PG8_LDA(dst, b, h) do { _Pragma("unroll") for (int m = 0; m < 4; ++m) _Pragma("unroll") for (int k = 0; k < 2; ++k) dst[m][k] = *(const LAS bf16x8*)(lds + PG8_SA(b, h) + aoff + m * 2048 + k * 1024); } while (0)
; #define PG8_LDB(dst, b, h) do { _Pragma("unroll") for (int n = 0; n < 2; ++n) _Pragma("unroll") for (int k = 0; k < 2; ++k) dst[n][k] = *(const LAS bf16x8*)(lds + PG8_SB(b, h) + boff + n * 2048 + k * 1024); } while (0)
; #define PG8_MMA(ai, bj, At, Bt) do { __builtin_amdgcn_s_setprio(1); _Pragma("unroll") for (int m = 0; m < 4; ++m) _Pragma("unroll") for (int n = 0; n < 2; ++n) _Pragma("unroll") for (int k = 0; k < 2; ++k) \
;         acc[ai][bj][m][n] = __builtin_amdgcn_mfma_f32_16x16x32_bf16(Bt[n][k], At[m][k], acc[ai][bj][m][n], 0, 0, 0); __builtin_amdgcn_s_setprio(0); } while (0)
; #define PG8_WAIT_L(n) asm volatile("s_waitcnt lgkmcnt(" #n ")" ::: "memory")
; #define PG8_BAR __builtin_amdgcn_s_barrier()
; #define PG8_SCHED __builtin_amdgcn_sched_barrier(0)
; template <class Epi, class Ptrs>
; __device__ __forceinline__ void gemm_phase(LAS unsigned char* lds, const int K, const StaticOrder& S, const Ptrs& P, const Epi& E) {
;     ...
;             PG8_WAIT_L(8); PG8_BAR; PG8_WAIT_L(0); PG8_MMA(0, 0, At, B0); PG8_BAR; PG8_SCHED;
;             PG8_LDB(B1, 1, 1); PG8_STAGE(PG8_SB(1, 0), b3, voffB);
;             PG8_BAR; PG8_WAIT_L(0); PG8_MMA(0, 1, At, B1); PG8_BAR;
;             PG8_LDA(At, 1, 1); PG8_STAGE(PG8_SA(1, 0), a3, voffA);
;             PG8_BAR; PG8_WAIT_L(0); PG8_MMA(1, 0, At, B0); PG8_BAR; PG8_SCHED;
	s_waitcnt lgkmcnt(0)
	v_mfma_f32_16x16x32_bf16 v[124:127], v[128:131], v[144:147], v[124:127]
	v_mfma_f32_16x16x32_bf16 v[124:127], v[132:135], v[148:151], v[124:127]
	v_mfma_f32_16x16x32_bf16 v[120:123], v[140:143], v[148:151], v[120:123]
	v_mfma_f32_16x16x32_bf16 v[120:123], v[136:139], v[144:147], v[120:123]
	v_mfma_f32_16x16x32_bf16 v[104:107], v[136:139], v[152:155], v[104:107]
	v_mfma_f32_16x16x32_bf16 v[104:107], v[140:143], v[156:159], v[104:107]
	v_mfma_f32_16x16x32_bf16 v[108:111], v[132:135], v[156:159], v[108:111]
	v_mfma_f32_16x16x32_bf16 v[108:111], v[128:131], v[152:155], v[108:111]
	v_mfma_f32_16x16x32_bf16 v[92:95], v[128:131], v[160:163], v[92:95]
	v_mfma_f32_16x16x32_bf16 v[92:95], v[132:135], v[164:167], v[92:95]
	v_mfma_f32_16x16x32_bf16 v[88:91], v[140:143], v[164:167], v[88:91]
	v_mfma_f32_16x16x32_bf16 v[88:91], v[136:139], v[160:163], v[88:91]
	v_mfma_f32_16x16x32_bf16 v[72:75], v[136:139], v[168:171], v[72:75]
	v_mfma_f32_16x16x32_bf16 v[72:75], v[140:143], v[172:175], v[72:75]
	v_mfma_f32_16x16x32_bf16 v[76:79], v[132:135], v[172:175], v[76:79]
	v_mfma_f32_16x16x32_bf16 v[76:79], v[128:131], v[168:171], v[76:79]
	s_barrier
	s_add_i32 s44, 0, 0x1c000
	s_add_i32 s45, s69, s51
	v_add_u32_e32 v211, s44, v205
	v_lshl_add_u64 v[216:217], v[216:217], 0, s[18:19]
	s_mov_b32 m0, s45
	ds_read_b128 v[192:195], v211
	ds_read_b128 v[196:199], v211 offset:1024
	ds_read_b128 v[200:203], v211 offset:2048
	ds_read_b128 v[212:215], v211 offset:3072
	global_load_lds_dwordx4 v[216:217], off
	v_lshl_add_u64 v[216:217], v[218:219], 0, s[18:19]
	s_add_i32 m0, s45, 0x2000
	s_nop 0
	global_load_lds_dwordx4 v[216:217], off
	s_barrier
	s_waitcnt lgkmcnt(0)
	v_mfma_f32_16x16x32_bf16 v[116:119], v[192:195], v[144:147], v[116:119]
	v_mfma_f32_16x16x32_bf16 v[116:119], v[196:199], v[148:151], v[116:119]
	v_mfma_f32_16x16x32_bf16 v[112:115], v[212:215], v[148:151], v[112:115]
	v_mfma_f32_16x16x32_bf16 v[112:115], v[200:203], v[144:147], v[112:115]
	v_mfma_f32_16x16x32_bf16 v[96:99], v[200:203], v[152:155], v[96:99]
	v_mfma_f32_16x16x32_bf16 v[96:99], v[212:215], v[156:159], v[96:99]
	v_mfma_f32_16x16x32_bf16 v[100:103], v[196:199], v[156:159], v[100:103]
	v_mfma_f32_16x16x32_bf16 v[100:103], v[192:195], v[152:155], v[100:103]
	v_mfma_f32_16x16x32_bf16 v[84:87], v[192:195], v[160:163], v[84:87]
	v_mfma_f32_16x16x32_bf16 v[84:87], v[196:199], v[164:167], v[84:87]
	v_mfma_f32_16x16x32_bf16 v[80:83], v[212:215], v[164:167], v[80:83]
	v_mfma_f32_16x16x32_bf16 v[80:83], v[200:203], v[160:163], v[80:83]
	v_mfma_f32_16x16x32_bf16 v[64:67], v[200:203], v[168:171], v[64:67]
	v_mfma_f32_16x16x32_bf16 v[64:67], v[212:215], v[172:175], v[64:67]
	v_mfma_f32_16x16x32_bf16 v[68:71], v[196:199], v[172:175], v[68:71]
	v_mfma_f32_16x16x32_bf16 v[68:71], v[192:195], v[168:171], v[68:71]
	s_mov_b32 m0, s63
	v_lshl_add_u64 v[216:217], v[220:221], 0, s[18:19]
	s_barrier
	ds_read_b128 v[144:147], v209 offset:49152
	ds_read_b128 v[148:151], v209 offset:50176
	ds_read_b128 v[152:155], v209 offset:51200
	ds_read_b128 v[156:159], v209 offset:52224
	ds_read_b128 v[160:163], v209 offset:53248
	ds_read_b128 v[164:167], v209 offset:54272
	ds_read_b128 v[168:171], v209 offset:55296
	ds_read_b128 v[172:175], v209 offset:56320
	global_load_lds_dwordx4 v[216:217], off
	v_lshl_add_u64 v[216:217], v[222:223], 0, s[18:19]
	s_mov_b32 m0, s64
	s_nop 0
	global_load_lds_dwordx4 v[216:217], off
	s_barrier
	s_waitcnt lgkmcnt(0)
	v_mfma_f32_16x16x32_bf16 v[60:63], v[128:131], v[144:147], v[60:63]
	v_mfma_f32_16x16x32_bf16 v[60:63], v[132:135], v[148:151], v[60:63]
	v_mfma_f32_16x16x32_bf16 v[56:59], v[140:143], v[148:151], v[56:59]
	v_mfma_f32_16x16x32_bf16 v[56:59], v[136:139], v[144:147], v[56:59]
	v_mfma_f32_16x16x32_bf16 v[40:43], v[136:139], v[152:155], v[40:43]
	v_mfma_f32_16x16x32_bf16 v[40:43], v[140:143], v[156:159], v[40:43]
	v_mfma_f32_16x16x32_bf16 v[44:47], v[132:135], v[156:159], v[44:47]
	v_mfma_f32_16x16x32_bf16 v[44:47], v[128:131], v[152:155], v[44:47]
	v_mfma_f32_16x16x32_bf16 v[28:31], v[128:131], v[160:163], v[28:31]
	v_mfma_f32_16x16x32_bf16 v[28:31], v[132:135], v[164:167], v[28:31]
	v_mfma_f32_16x16x32_bf16 v[24:27], v[140:143], v[164:167], v[24:27]
	v_mfma_f32_16x16x32_bf16 v[24:27], v[136:139], v[160:163], v[24:27]
	v_mfma_f32_16x16x32_bf16 v[8:11], v[136:139], v[168:171], v[8:11]
	v_mfma_f32_16x16x32_bf16 v[8:11], v[140:143], v[172:175], v[8:11]
	v_mfma_f32_16x16x32_bf16 v[12:15], v[132:135], v[172:175], v[12:15]
	v_mfma_f32_16x16x32_bf16 v[12:15], v[128:131], v[168:171], v[12:15]
	s_barrier
	s_add_u32 s42, s42, 0x40080
	s_addc_u32 s43, s43, 0
	s_add_i32 s44, s44, s51
	s_mov_b32 m0, s44
	s_nop 0
	global_load_lds_dwordx4 v178, s[42:43]
	s_add_i32 m0, s44, 0x2000
	s_nop 0
	global_load_lds_dwordx4 v182, s[42:43]
	s_waitcnt vmcnt(6)
	s_barrier
; __device__ __forceinline__ unsigned cvt_pk_bf16(float lo, float hi) { unsigned r; asm volatile("v_cvt_pk_bf16_f32 %0, %1, %2" : "=v"(r) : "v"(lo), "v"(hi)); return r; }
; __device__ __forceinline__ float x16_sum(float x) { auto s = __builtin_amdgcn_permlane16_swap(__float_as_uint(x), __float_as_uint(x), false, false); return __uint_as_float(s[0]) + __uint_as_float(s[1]); }
; __device__ __forceinline__ float x32_sum(float x) { auto s = __builtin_amdgcn_permlane32_swap(__float_as_uint(x), __float_as_uint(x), false, false); return __uint_as_float(s[0]) + __uint_as_float(s[1]); }
; template <class Epi, class Ptrs>
; __device__ __forceinline__ void gemm_phase(LAS unsigned char* lds, const int K, const StaticOrder& S, const Ptrs& P, const Epi& E) {
;     ...
;             PG8_WAIT_V(6); PG8_BAR; PG8_MMA(1, 1, At, B1); PG8_BAR;
;     __device__ __forceinline__ void operator()(const f32x4 (&acc)[2][2][4][2], const Unit& u, int ui, int wr, int wc, int fr, int fq) const {
;         const int row0 = u.pm * 256 + wr * 64 + fr, col0 = u.pn * 256 + wc * 32 + 8 * fq;
;         const float* xb0 = (u.pm * 256 < MP) ? xp : xs - (size_t)MP * DM;
; #pragma unroll
;         for (int ai = 0; ai < 2; ++ai) {
;             f32x4 xv[4][2][2];
; #pragma unroll
;             for (int m = 0; m < 4; ++m)
; #pragma unroll
;                 for (int bj = 0; bj < 2; ++bj) { const float* p = xb0 + (size_t)(row0 + ai * 128 + m * 16) * DM + col0 + bj * 128; xv[m][bj][0] = *(const f32x4*)p; xv[m][bj][1] = *(const f32x4*)(p + 4); }
; #pragma unroll
;             for (int m = 0; m < 4; ++m) { const int row = row0 + ai * 128 + m * 16; const size_t off = (size_t)row * DM + col0; float ss = 0.f;
; #pragma unroll
;                 for (int bj = 0; bj < 2; ++bj) {
;                     const f32x4 v0 = acc[ai][bj][m][0] + xv[m][bj][0], v1 = acc[ai][bj][m][1] + xv[m][bj][1];
;                     u32x4 w; w.x = cvt_pk_bf16(v0[0], v0[1]); w.y = cvt_pk_bf16(v0[2], v0[3]); w.z = cvt_pk_bf16(v1[0], v1[1]); w.w = cvt_pk_bf16(v1[2], v1[3]);
;                     *(u32x4*)(xb + off + bj * 128) = w;
;                     ss += (v0[0] * v0[0] + v0[1] * v0[1]) + (v0[2] * v0[2] + v0[3] * v0[3]) + (v1[0] * v1[0] + v1[1] * v1[1]) + (v1[2] * v1[2] + v1[3] * v1[3]); }
;                 ss = x32_sum(x16_sum(ss));
;                 if (fq == 0) part[(size_t)row * 16 + u.pn * 4 + wc] = ss; }
	v_mfma_f32_16x16x32_bf16 v[52:55], v[192:195], v[144:147], v[52:55]
	v_mfma_f32_16x16x32_bf16 v[52:55], v[196:199], v[148:151], v[52:55]
	v_mfma_f32_16x16x32_bf16 v[48:51], v[212:215], v[148:151], v[48:51]
	v_mfma_f32_16x16x32_bf16 v[48:51], v[200:203], v[144:147], v[48:51]
	v_mfma_f32_16x16x32_bf16 v[32:35], v[200:203], v[152:155], v[32:35]
	v_mfma_f32_16x16x32_bf16 v[32:35], v[212:215], v[156:159], v[32:35]
	v_mfma_f32_16x16x32_bf16 v[36:39], v[196:199], v[156:159], v[36:39]
	v_mfma_f32_16x16x32_bf16 v[36:39], v[192:195], v[152:155], v[36:39]
	v_mfma_f32_16x16x32_bf16 v[20:23], v[192:195], v[160:163], v[20:23]
	v_mfma_f32_16x16x32_bf16 v[20:23], v[196:199], v[164:167], v[20:23]
	v_mfma_f32_16x16x32_bf16 v[16:19], v[212:215], v[164:167], v[16:19]
	v_mfma_f32_16x16x32_bf16 v[16:19], v[200:203], v[160:163], v[16:19]
	v_mfma_f32_16x16x32_bf16 v[0:3], v[200:203], v[168:171], v[0:3]
	v_mfma_f32_16x16x32_bf16 v[0:3], v[212:215], v[172:175], v[0:3]
	v_mfma_f32_16x16x32_bf16 v[4:7], v[196:199], v[172:175], v[4:7]
	v_mfma_f32_16x16x32_bf16 v[4:7], v[192:195], v[168:171], v[4:7]
	s_add_i32 s41, s41, 2
	s_add_u32 s38, s38, 0x100
	s_addc_u32 s39, s39, 0
	s_add_u32 s21, s21, 0x100
	s_addc_u32 s23, s23, 0
	s_cmp_gt_u32 s41, 13
	s_barrier
	s_cbranch_scc0 .LBB0_353
	s_nop 0
	s_nop 0
	s_nop 0
	s_nop 0
	s_nop 0
	s_nop 0
	s_nop 0
	s_nop 0
	s_nop 0
	s_nop 0
	s_nop 0
	s_nop 0
	s_nop 0
	s_nop 0
	s_nop 0
	s_nop 0
	s_nop 0
	s_nop 0
	s_nop 0
	s_nop 0
	s_nop 0
	s_nop 0
	s_nop 0
	s_nop 0
	s_nop 0
	s_nop 0
	s_nop 0
	s_nop 0
	s_nop 0
	s_nop 0
	s_nop 0
	s_nop 0
	s_nop 0
	s_nop 0
	s_nop 0
	s_nop 0
	s_nop 0
	s_nop 0
	s_cmpk_lt_i32 s40, 0x80
	v_lshl_add_u32 v194, s40, 8, v204
	v_lshl_or_b32 v192, s12, 8, v206
	s_cselect_b32 s21, s37, s61
	s_cselect_b32 s23, s36, s60
	v_mov_b32_e32 v128, s23
	v_mov_b32_e32 v129, s21
	v_ashrrev_i32_e32 v193, 31, v192
	v_ashrrev_i32_e32 v195, 31, v194
	v_lshl_add_u64 v[196:197], v[192:193], 2, v[128:129]
	v_lshlrev_b64 v[128:129], 12, v[194:195]
	v_or_b32_e32 v202, 16, v194
	v_or_b32_e32 v200, 32, v194
	v_or_b32_e32 v198, 48, v194
	v_lshl_add_u64 v[128:129], v[196:197], 0, v[128:129]
	v_ashrrev_i32_e32 v203, 31, v202
	v_ashrrev_i32_e32 v201, 31, v200
	v_ashrrev_i32_e32 v199, 31, v198
	global_load_dwordx4 v[212:215], v[128:129], off
	global_load_dwordx4 v[216:219], v[128:129], off offset:16
	global_load_dwordx4 v[220:223], v[128:129], off offset:512
	global_load_dwordx4 v[224:227], v[128:129], off offset:528
	v_lshlrev_b64 v[128:129], 12, v[202:203]
	v_lshlrev_b64 v[130:131], 12, v[200:201]
	v_lshlrev_b64 v[132:133], 12, v[198:199]
	v_lshl_add_u64 v[128:129], v[196:197], 0, v[128:129]
	v_lshl_add_u64 v[130:131], v[196:197], 0, v[130:131]
	v_lshl_add_u64 v[132:133], v[196:197], 0, v[132:133]
	global_load_dwordx4 v[168:171], v[128:129], off offset:16
	global_load_dwordx4 v[172:175], v[128:129], off
	global_load_dwordx4 v[160:163], v[128:129], off offset:528
	global_load_dwordx4 v[164:167], v[128:129], off offset:512
	global_load_dwordx4 v[152:155], v[130:131], off offset:16
	global_load_dwordx4 v[156:159], v[130:131], off
	global_load_dwordx4 v[144:147], v[130:131], off offset:528
	global_load_dwordx4 v[148:151], v[130:131], off offset:512
	global_load_dwordx4 v[136:139], v[132:133], off offset:16
	global_load_dwordx4 v[140:143], v[132:133], off
	s_nop 0
	global_load_dwordx4 v[128:131], v[132:133], off offset:528
	s_nop 0
	global_load_dwordx4 v[132:135], v[132:133], off offset:512
	v_lshlrev_b64 v[228:229], 11, v[194:195]
	v_lshl_add_u64 v[228:229], s[14:15], 0, v[228:229]
	v_lshl_add_u64 v[228:229], v[192:193], 1, v[228:229]
	s_lshl_b32 s38, s12, 2
	s_ashr_i32 s39, s38, 31
	s_waitcnt vmcnt(0)
	v_pk_add_f32 v[126:127], v[126:127], v[214:215]
	v_pk_add_f32 v[124:125], v[124:125], v[212:213]
	v_pk_add_f32 v[118:119], v[118:119], v[222:223]
	v_pk_add_f32 v[116:117], v[116:117], v[220:221]
	v_pk_add_f32 v[120:121], v[120:121], v[216:217]
	v_pk_add_f32 v[214:215], v[112:113], v[224:225]
	v_cvt_pk_bf16_f32 v112, v124, v125
	v_cvt_pk_bf16_f32 v113, v126, v127
	v_mul_f32_e32 v125, v125, v125
	v_mul_f32_e32 v127, v127, v127
	v_mul_f32_e32 v211, v117, v117
	v_mul_f32_e32 v216, v119, v119
	v_pk_add_f32 v[122:123], v[122:123], v[218:219]
	v_pk_add_f32 v[212:213], v[114:115], v[226:227]
	v_cvt_pk_bf16_f32 v114, v120, v121
	v_cvt_pk_bf16_f32 v115, v122, v123
	v_mul_f32_e32 v121, v121, v121
	v_mul_f32_e32 v217, v215, v215
	global_store_dwordx4 v[228:229], v[112:115], off
	v_fmac_f32_e32 v125, v124, v124
	v_fmac_f32_e32 v127, v126, v126
	v_cvt_pk_bf16_f32 v112, v116, v117
	v_fmac_f32_e32 v211, v116, v116
	v_fmac_f32_e32 v216, v118, v118
	v_mul_f32_e32 v123, v123, v123
	v_mul_f32_e32 v218, v213, v213
	v_fmac_f32_e32 v121, v120, v120
	v_cvt_pk_bf16_f32 v113, v118, v119
	v_cvt_pk_bf16_f32 v114, v214, v215
	v_cvt_pk_bf16_f32 v115, v212, v213
	v_fmac_f32_e32 v217, v214, v214
	v_add_f32_e32 v116, v125, v127
	global_store_dwordx4 v[228:229], v[112:115], off offset:256
	v_fmac_f32_e32 v123, v122, v122
	v_fmac_f32_e32 v218, v212, v212
	v_add_f32_e32 v112, v211, v216
	v_add_f32_e32 v113, v116, v121
	v_add_f32_e32 v112, v112, v217
	v_add_f32_e32 v113, v123, v113
	v_add_f32_e32 v112, v218, v112
	v_add_f32_e32 v112, v113, v112
	v_mov_b32_e32 v113, v112
	s_nop 1
	v_permlane16_swap_b32_e32 v112, v113
	v_add_f32_e32 v112, v112, v113
	v_mov_b32_e32 v113, v112
	s_nop 1
	v_permlane32_swap_b32_e32 v112, v113
	s_and_saveexec_b64 s[40:41], s[6:7]
	s_cbranch_execz .LBB0_356
	v_lshlrev_b64 v[114:115], 6, v[194:195]
	v_lshl_add_u64 v[114:115], s[16:17], 0, v[114:115]
	v_lshl_add_u64 v[114:115], s[38:39], 2, v[114:115]
	s_lshl_b32 s12, s62, 2
	v_lshl_add_u64 v[114:115], v[114:115], 0, s[12:13]
	v_add_f32_e32 v112, v112, v113
	global_store_dword v[114:115], v112, off

; __device__ __forceinline__ unsigned xb_ld(unsigned* p)              { return __hip_atomic_load(p, __ATOMIC_RELAXED, __HIP_MEMORY_SCOPE_AGENT); }
; __device__ __forceinline__ void xcd_barrier_complete(unsigned* bar, unsigned x, unsigned& nloc, unsigned& nx) {
;     const unsigned G = gridDim.x * gridDim.y * gridDim.z;
;     unsigned sum, cnt, mine, sp = 0u;
;     for (;;) {
;         sum = 0u; cnt = 0u; mine = 0u;
; #pragma unroll
;         for (unsigned j = 0; j < 16; ++j) { const unsigned c = xb_ld(&bar[XB_XCNT(j)]); sum += c; cnt += (c > 0u) ? 1u : 0u; mine = (j == x) ? c : mine; }
; __device__ __forceinline__ void xcd_barrier(const XcdBarrier& b) {
;     asm volatile("s_waitcnt vmcnt(0)" ::: "memory");
;     __syncthreads();
;     if (threadIdx.x == 0) {
;         unsigned* bar = b.bar;
;         __builtin_amdgcn_s_waitcnt(0);
;         unsigned nloc = b.st[0], nx = b.st[1];
;         if (nloc == 0u) { xcd_barrier_complete(bar, b.x, nloc, nx); b.st[0] = nloc; b.st[1] = nx; }
.LBB0_373:
	s_nop 0
	s_nop 0
	s_nop 0
	s_nop 0
	s_nop 0
	s_nop 0
	s_nop 0
	s_nop 0
	s_nop 0
	s_nop 0
	s_nop 0
	s_nop 0
	s_nop 0
	s_nop 0
	s_nop 0
	s_nop 0
	s_nop 0
	s_nop 0
	s_nop 0
	s_nop 0
	s_nop 0
	s_nop 0
	s_nop 0
	s_nop 0
	s_nop 0
	s_nop 0
	s_nop 0
	s_nop 0
	s_nop 0
	s_nop 0
	s_nop 0
	s_nop 0
	s_nop 0
	s_nop 0
	s_nop 0
	s_nop 0
	s_nop 0
	s_nop 0
	s_nop 0
	s_nop 0
	s_nop 0
	s_nop 0
	s_nop 0
	s_nop 0
	s_nop 0
	s_nop 0
	s_nop 0
	s_nop 0
	s_nop 0
	s_nop 0
	s_nop 0
	s_nop 0
	s_nop 0
	s_nop 0
	s_nop 0
	s_nop 0
	s_nop 0
	s_nop 0
	s_nop 0
	s_nop 0
	s_nop 0
	s_nop 0
	s_nop 0
	s_cmp_gt_i32 s31, 4
	s_cselect_b64 s[0:1], -1, 0
	s_and_b64 s[4:5], s[10:11], s[0:1]
	s_andn2_b64 vcc, exec, s[4:5]
	s_cbranch_vccnz .LBB0_423
	s_waitcnt vmcnt(0)
	s_waitcnt vmcnt(0) lgkmcnt(0)
	s_barrier
	s_and_saveexec_b64 s[4:5], s[8:9]
	s_cbranch_execz .LBB0_422
	s_add_i32 s6, 0, 0x25ff0
	v_mov_b32_e32 v0, s6
	s_waitcnt vmcnt(0) expcnt(0) lgkmcnt(0)
	ds_read_b32 v2, v0
	s_add_i32 s6, 0, 0x25ff4
	v_mov_b32_e32 v0, s6
	ds_read_b32 v0, v0
	s_waitcnt lgkmcnt(1)
	v_cmp_ne_u32_e32 vcc, 0, v2
	s_cbranch_vccnz .LBB0_390
	s_load_dwordx2 s[12:13], s[52:53], 0x4
	s_add_u32 s6, s28, 0x3e800200
	s_addc_u32 s7, s29, 0
	s_add_u32 s10, s28, 0x3e800400
	s_addc_u32 s11, s29, 0
	s_waitcnt lgkmcnt(0)
	s_mul_i32 s60, s12, s3
	s_add_u32 s12, s28, 0x3e800500
	s_mul_i32 s60, s60, s13
	s_addc_u32 s13, s29, 0
	s_add_u32 s14, s28, 0x3e800600
	s_addc_u32 s15, s29, 0
	s_add_u32 s16, s28, 0x3e800700
	s_addc_u32 s17, s29, 0
	s_add_u32 s18, s28, 0x3e800800
	s_addc_u32 s19, s29, 0
	s_add_u32 s20, s28, 0x3e800900
	s_addc_u32 s21, s29, 0
	s_add_u32 s22, s28, 0x3e800a00
	s_addc_u32 s23, s29, 0
	s_add_u32 s24, s28, 0x3e800b00
	s_addc_u32 s25, s29, 0
	s_add_u32 s36, s28, 0x3e800c00
	s_addc_u32 s37, s29, 0
	s_add_u32 s38, s28, 0x3e800d00
	s_addc_u32 s39, s29, 0
	s_add_u32 s40, s28, 0x3e800e00
	s_addc_u32 s41, s29, 0
	s_add_u32 s42, s28, 0x3e800f00
	s_addc_u32 s43, s29, 0
	s_add_u32 s44, s28, 0x3e801000
	s_addc_u32 s45, s29, 0
	s_add_u32 s46, s28, 0x3e801100
	s_addc_u32 s47, s29, 0
	s_add_u32 s48, s28, 0x3e801200
	s_addc_u32 s49, s29, 0
	s_add_u32 s50, s28, 0x3e801300
	s_addc_u32 s51, s29, 0
	s_mov_b32 s61, 1
	v_mov_b32_e32 v16, 0
	s_branch .LBB0_378

; #define PG8_STAGE(bufoff, gbase, voff) do { _Pragma("unroll") for (int _i = 0; _i < 2; ++_i) \
;         __builtin_amdgcn_global_load_lds((const unsigned*)((const char*)(gbase) + (voff)[_i]), (LAS unsigned*)(lds + (bufoff) + ldsw + _i * 8192), 16, 0, 0); } while (0)
; #define PG8_WAIT_V(n) asm volatile("s_waitcnt vmcnt(" #n ")" ::: "memory")
; #define PG8_BAR __builtin_amdgcn_s_barrier()
; template <class Epi, class Ptrs>
; __device__ __forceinline__ void gemm_phase(LAS unsigned char* lds, const int K, const StaticOrder& S, const Ptrs& P, const Epi& E) {
;     const int tid = threadIdx.x, wid = __builtin_amdgcn_readfirstlane(tid >> 6), lane = tid & 63, wr = wid >> 2, wc = wid & 3, fr = lane & 15, fq = lane >> 4;
;     const int nt = K / BK;
;     unsigned voffA[2], voffB[2];
; #pragma unroll
;     for (int i = 0; i < 2; ++i) { int R, C; stage_rc(tid * 16 + i * 8192, R, C); const int Rb = (R & ~31) + perm32(R & 31);
;         voffA[i] = (unsigned)(R * K + C) * 2u; voffB[i] = (unsigned)(Rb * K + C) * 2u; }
;     const size_t kstep = (size_t)(BK * 2);
;     const size_t hstep = (size_t)HALF * K * 2;
;     const unsigned ldsw = (unsigned)wid * 1024u;
;     const int aoff = lds_byte(wr * 64 + fr, fq * 8), boff = lds_byte(wc * 32 + fr, fq * 8);
;     ...
;     Unit cur, nxt; int ui = 0;
;     if (!S.next(0, cur)) return;
;     f32x4 acc[2][2][4][2];
; #pragma unroll
;     for (int a = 0; a < 2; ++a)
; #pragma unroll
;         for (int b = 0; b < 2; ++b)
; #pragma unroll
;             for (int m = 0; m < 4; ++m)
; #pragma unroll
;                 for (int n = 0; n < 2; ++n) acc[a][b][m][n] = (f32x4){0.f, 0.f, 0.f, 0.f};
;     bf16x8 At[4][2], B0[2][2], B1[2][2];
;     const char* cA; const char* cB; P.get(cur, cA, cB);
;     PG8_STAGE(PG8_SB(0, 0), cB, voffB); PG8_STAGE(PG8_SA(0, 0), cA, voffA); PG8_STAGE(PG8_SB(0, 1), cB + hstep, voffB); PG8_STAGE(PG8_SA(0, 1), cA + hstep, voffA);
;     if (wr == 1) PG8_BAR;
;     PG8_WAIT_V(4); PG8_BAR;
;     PG8_STAGE(PG8_SB(1, 0), cB + kstep, voffB); PG8_STAGE(PG8_SA(1, 0), cA + kstep, voffA); PG8_STAGE(PG8_SB(1, 1), cB + hstep + kstep, voffB);
;     PG8_WAIT_V(6); PG8_BAR;
.LBB0_427:
	s_nop 0
	s_nop 0
	s_nop 0
	s_nop 0
	s_nop 0
	s_nop 0
	s_nop 0
	s_nop 0
	s_nop 0
	s_nop 0
	s_nop 0
	s_nop 0
	s_nop 0
	s_nop 0
	s_nop 0
	s_nop 0
	s_nop 0
	s_nop 0
	s_nop 0
	s_nop 0
	s_nop 0
	s_nop 0
	s_nop 0
	s_nop 0
	s_nop 0
	s_nop 0
	s_nop 0
	s_nop 0
	s_nop 0
	s_nop 0
	s_nop 0
	s_nop 0
	s_nop 0
	s_nop 0
	s_nop 0
	s_nop 0
	s_nop 0
	s_nop 0
	s_nop 0
	s_nop 0
	s_nop 0
	s_nop 0
	s_nop 0
	s_nop 0
	s_nop 0
	s_nop 0
	s_nop 0
	s_nop 0
	s_nop 0
	s_nop 0
	s_nop 0
	s_nop 0
	s_nop 0
	s_nop 0
	s_add_u32 s10, s28, 0xe000000
	s_addc_u32 s11, s29, 0
	s_lshl_b32 s4, s4, 5
	s_mov_b64 s[12:13], 0x80
	s_and_b32 s15, s4, 0x60
	s_add_i32 m0, s39, 0x18000
	v_lshl_add_u64 v[6:7], v[6:7], 0, s[12:13]
	s_ashr_i32 s60, s3, 31
	s_lshl_b32 s14, s1, 13
	s_lshl_b32 s16, s15, 7
	s_waitcnt vmcnt(4)
	s_barrier
	global_load_lds_dwordx4 v[6:7], off
	v_lshl_add_u64 v[4:5], v[4:5], 0, s[12:13]
	s_add_i32 m0, s39, 0x1a000
	s_add_i32 s61, s39, 0x8000
	s_add_i32 s62, s39, 0xa000
	global_load_lds_dwordx4 v[4:5], off
	v_lshl_add_u64 v[2:3], v[2:3], 0, s[12:13]
	s_mov_b32 m0, s61
	s_add_u32 s4, s42, 0x40080
	global_load_lds_dwordx4 v[2:3], off
	v_lshl_add_u64 v[0:1], v[0:1], 0, s[12:13]
	s_mov_b32 m0, s62
	s_addc_u32 s5, s43, 0
	global_load_lds_dwordx4 v[0:1], off
	s_add_i32 m0, s39, 0x1c000
	v_lshl_add_u64 v[0:1], s[4:5], 0, v[130:131]
	global_load_lds_dwordx4 v[0:1], off
	v_lshl_add_u64 v[0:1], s[4:5], 0, v[134:135]
	s_add_i32 m0, s39, 0x1e000
	s_sext_i32_i8 s69, s0
	global_load_lds_dwordx4 v[0:1], off
	v_and_b32_e32 v0, 15, v208
	v_lshlrev_b32_e32 v1, 1, v11
	v_lshlrev_b32_e32 v2, 6, v208
	s_movk_i32 s0, 0x3c0
	v_lshlrev_b32_e32 v3, 2, v208
	v_and_or_b32 v2, v2, s0, v1
	v_and_b32_e32 v3, 32, v3
	v_lshl_or_b32 v146, s1, 6, v0
	v_lshl_or_b32 v0, v0, 6, v1
	v_lshlrev_b32_e32 v1, 8, v208
	v_bitop3_b32 v147, s16, v2, v3 bitop3:0xf6
	v_and_b32_e32 v1, 0x38000, v1
	v_lshlrev_b32_e32 v2, 11, v10
	v_or3_b32 v1, v8, v1, v2
	v_add_u32_e32 v136, v1, v9
	v_lshlrev_b32_e32 v1, 4, v12
	s_waitcnt vmcnt(6)
	v_and_b32_e32 v1, 0x78000, v1
	v_bitop3_b32 v0, v0, s14, v3 bitop3:0xde
	v_or3_b32 v1, v8, v1, v2
	s_add_i32 s63, 0, 0x10000
	s_add_i32 s64, 0, 0x14000
	v_or_b32_e32 v148, s15, v11
	v_mov_b32_e32 v137, v131
	v_add_u32_e32 v138, v1, v9
	v_mov_b32_e32 v139, v131
	v_mov_b64_e32 v[140:141], 0x1800
	v_mov_b64_e32 v[142:143], 0x17ff
	v_add_u32_e32 v149, s63, v147
	v_add_u32_e32 v150, 0, v0
	v_add_u32_e32 v151, s64, v147
	s_mov_b64 s[14:15], 0x100000
	s_mov_b32 s65, 0x100000
	s_mov_b64 s[16:17], 0x120000
	s_mov_b32 s66, 0x120000
	s_mov_b64 s[18:19], 0x140000
	s_mov_b32 s67, 0x140000
	s_mov_b64 s[20:21], 0x160000
	s_mov_b32 s68, 0x160000
	s_cmpk_lt_u32 s46, 0x100
	s_cbranch_scc1 .Lsprio_2
	s_setprio 1

; #define PG8_STAGE(bufoff, gbase, voff) do { _Pragma("unroll") for (int _i = 0; _i < 2; ++_i) \
;         __builtin_amdgcn_global_load_lds((const unsigned*)((const char*)(gbase) + (voff)[_i]), (LAS unsigned*)(lds + (bufoff) + ldsw + _i * 8192), 16, 0, 0); } while (0)
; #define PG8_LDA(dst, b, h) do { _Pragma("unroll") for (int m = 0; m < 4; ++m) _Pragma("unroll") for (int k = 0; k < 2; ++k) dst[m][k] = *(const LAS bf16x8*)(lds + PG8_SA(b, h) + aoff + m * 2048 + k * 1024); } while (0)
; #define PG8_LDB(dst, b, h) do { _Pragma("unroll") for (int n = 0; n < 2; ++n) _Pragma("unroll") for (int k = 0; k < 2; ++k) dst[n][k] = *(const LAS bf16x8*)(lds + PG8_SB(b, h) + boff + n * 2048 + k * 1024); } while (0)
; #define PG8_MMA(ai, bj, At, Bt) do { __builtin_amdgcn_s_setprio(1); _Pragma("unroll") for (int m = 0; m < 4; ++m) _Pragma("unroll") for (int n = 0; n < 2; ++n) _Pragma("unroll") for (int k = 0; k < 2; ++k) \
;         acc[ai][bj][m][n] = __builtin_amdgcn_mfma_f32_16x16x32_bf16(Bt[n][k], At[m][k], acc[ai][bj][m][n], 0, 0, 0); __builtin_amdgcn_s_setprio(0); } while (0)
; #define PG8_WAIT_V(n) asm volatile("s_waitcnt vmcnt(" #n ")" ::: "memory")
; #define PG8_WAIT_L(n) asm volatile("s_waitcnt lgkmcnt(" #n ")" ::: "memory")
; #define PG8_BAR __builtin_amdgcn_s_barrier()
; #define PG8_SCHED __builtin_amdgcn_sched_barrier(0)
; template <class Epi, class Ptrs>
; __device__ __forceinline__ void gemm_phase(LAS unsigned char* lds, const int K, const StaticOrder& S, const Ptrs& P, const Epi& E) {
;     ...
;             PG8_LDB(B0, 0, 0); PG8_SCHED; PG8_LDA(At, 0, 0); PG8_STAGE(PG8_SA(1, 1), a1 + hstep, voffA);
;             PG8_WAIT_L(8); PG8_BAR; PG8_WAIT_L(0); PG8_MMA(0, 0, At, B0); PG8_BAR; PG8_SCHED;
;             PG8_LDB(B1, 0, 1); PG8_STAGE(PG8_SB(0, 0), b2, voffB);
;             PG8_BAR; PG8_WAIT_L(0); PG8_MMA(0, 1, At, B1); PG8_BAR;
;             PG8_LDA(At, 0, 1); PG8_STAGE(PG8_SA(0, 0), a2, voffA);
;             PG8_BAR; PG8_WAIT_L(0); PG8_MMA(1, 0, At, B0); PG8_BAR; PG8_SCHED;
;             PG8_STAGE(PG8_SB(0, 1), b2 + hstep, voffB);
;             PG8_WAIT_V(6); PG8_BAR; PG8_MMA(1, 1, At, B1); PG8_BAR;
.LBB0_433:
	ds_read_b128 v[152:155], v149
	ds_read_b128 v[156:159], v149 offset:1024
	ds_read_b128 v[160:163], v149 offset:2048
	ds_read_b128 v[164:167], v149 offset:3072
	s_add_u32 s42, s40, 0xfffc0080
	s_addc_u32 s43, s41, -1
	s_cmp_eq_u32 s70, 12
	s_cselect_b32 s45, s1, s43
	s_cselect_b32 s44, s0, s42
	s_cselect_b32 s43, s37, s25
	s_cselect_b32 s42, s36, s23
	s_add_i32 m0, s39, 0xc000
	ds_read_b128 v[168:171], v150
	ds_read_b128 v[172:175], v150 offset:1024
	ds_read_b128 v[176:179], v150 offset:2048
	ds_read_b128 v[180:183], v150 offset:3072
	ds_read_b128 v[184:187], v150 offset:4096
	ds_read_b128 v[188:191], v150 offset:5120
	ds_read_b128 v[192:195], v150 offset:6144
	ds_read_b128 v[196:199], v150 offset:7168
	global_load_lds_dwordx4 v136, s[40:41]
	s_add_i32 m0, s39, 0xe000
	s_nop 0
	global_load_lds_dwordx4 v138, s[40:41]
	s_waitcnt lgkmcnt(8)
	s_barrier
	s_waitcnt lgkmcnt(0)
	v_mfma_f32_16x16x32_bf16 v[124:127], v[152:155], v[168:171], v[124:127]
	v_mfma_f32_16x16x32_bf16 v[124:127], v[156:159], v[172:175], v[124:127]
	v_mfma_f32_16x16x32_bf16 v[120:123], v[164:167], v[172:175], v[120:123]
	v_mfma_f32_16x16x32_bf16 v[120:123], v[160:163], v[168:171], v[120:123]
	v_mfma_f32_16x16x32_bf16 v[104:107], v[160:163], v[176:179], v[104:107]
	v_mfma_f32_16x16x32_bf16 v[104:107], v[164:167], v[180:183], v[104:107]
	v_mfma_f32_16x16x32_bf16 v[108:111], v[156:159], v[180:183], v[108:111]
	v_mfma_f32_16x16x32_bf16 v[108:111], v[152:155], v[176:179], v[108:111]
	v_mfma_f32_16x16x32_bf16 v[92:95], v[152:155], v[184:187], v[92:95]
	v_mfma_f32_16x16x32_bf16 v[92:95], v[156:159], v[188:191], v[92:95]
	v_mfma_f32_16x16x32_bf16 v[88:91], v[164:167], v[188:191], v[88:91]
	v_mfma_f32_16x16x32_bf16 v[88:91], v[160:163], v[184:187], v[88:91]
	v_mfma_f32_16x16x32_bf16 v[72:75], v[160:163], v[192:195], v[72:75]
	v_mfma_f32_16x16x32_bf16 v[72:75], v[164:167], v[196:199], v[72:75]
	v_mfma_f32_16x16x32_bf16 v[76:79], v[156:159], v[196:199], v[76:79]
	v_mfma_f32_16x16x32_bf16 v[76:79], v[152:155], v[192:195], v[76:79]
	s_barrier
	s_add_i32 s71, s63, s51
	v_lshl_add_u64 v[144:145], s[42:43], 0, v[130:131]
	s_mov_b32 m0, s71
	ds_read_b128 v[200:203], v151
	ds_read_b128 v[204:207], v151 offset:1024
	ds_read_b128 v[210:213], v151 offset:2048
	ds_read_b128 v[214:217], v151 offset:3072
	global_load_lds_dwordx4 v[144:145], off
	v_lshl_add_u64 v[218:219], s[42:43], 0, v[134:135]
	s_add_i32 m0, s71, 0x2000
	s_nop 0
	global_load_lds_dwordx4 v[218:219], off
	s_barrier
	s_waitcnt lgkmcnt(0)
	v_mfma_f32_16x16x32_bf16 v[116:119], v[200:203], v[168:171], v[116:119]
	v_mfma_f32_16x16x32_bf16 v[116:119], v[204:207], v[172:175], v[116:119]
	v_mfma_f32_16x16x32_bf16 v[112:115], v[214:217], v[172:175], v[112:115]
	v_mfma_f32_16x16x32_bf16 v[112:115], v[210:213], v[168:171], v[112:115]
	v_mfma_f32_16x16x32_bf16 v[96:99], v[210:213], v[176:179], v[96:99]
	v_mfma_f32_16x16x32_bf16 v[96:99], v[214:217], v[180:183], v[96:99]
	v_mfma_f32_16x16x32_bf16 v[100:103], v[204:207], v[180:183], v[100:103]
	v_mfma_f32_16x16x32_bf16 v[100:103], v[200:203], v[176:179], v[100:103]
	v_mfma_f32_16x16x32_bf16 v[84:87], v[200:203], v[184:187], v[84:87]
	v_mfma_f32_16x16x32_bf16 v[84:87], v[204:207], v[188:191], v[84:87]
	v_mfma_f32_16x16x32_bf16 v[80:83], v[214:217], v[188:191], v[80:83]
	v_mfma_f32_16x16x32_bf16 v[80:83], v[210:213], v[184:187], v[80:83]
	v_mfma_f32_16x16x32_bf16 v[64:67], v[210:213], v[192:195], v[64:67]
	v_mfma_f32_16x16x32_bf16 v[64:67], v[214:217], v[196:199], v[64:67]
	v_mfma_f32_16x16x32_bf16 v[68:71], v[204:207], v[196:199], v[68:71]
	v_mfma_f32_16x16x32_bf16 v[68:71], v[200:203], v[192:195], v[68:71]
	s_mov_b32 m0, s39
	v_lshl_add_u64 v[220:221], s[44:45], 0, v[128:129]
	s_barrier
	ds_read_b128 v[168:171], v150 offset:16384
	ds_read_b128 v[172:175], v150 offset:17408
	ds_read_b128 v[176:179], v150 offset:18432
	ds_read_b128 v[180:183], v150 offset:19456
	ds_read_b128 v[184:187], v150 offset:20480
	ds_read_b128 v[188:191], v150 offset:21504
	ds_read_b128 v[192:195], v150 offset:22528
	ds_read_b128 v[196:199], v150 offset:23552
	global_load_lds_dwordx4 v[220:221], off
	v_lshl_add_u64 v[222:223], s[44:45], 0, v[132:133]
	s_mov_b32 m0, s56
	s_nop 0
	global_load_lds_dwordx4 v[222:223], off
	s_barrier
	s_waitcnt lgkmcnt(0)
	v_mfma_f32_16x16x32_bf16 v[60:63], v[152:155], v[168:171], v[60:63]
	v_mfma_f32_16x16x32_bf16 v[60:63], v[156:159], v[172:175], v[60:63]
	v_mfma_f32_16x16x32_bf16 v[56:59], v[164:167], v[172:175], v[56:59]
	v_mfma_f32_16x16x32_bf16 v[56:59], v[160:163], v[168:171], v[56:59]
	v_mfma_f32_16x16x32_bf16 v[40:43], v[160:163], v[176:179], v[40:43]
	v_mfma_f32_16x16x32_bf16 v[40:43], v[164:167], v[180:183], v[40:43]
	v_mfma_f32_16x16x32_bf16 v[44:47], v[156:159], v[180:183], v[44:47]
	v_mfma_f32_16x16x32_bf16 v[44:47], v[152:155], v[176:179], v[44:47]
	v_mfma_f32_16x16x32_bf16 v[28:31], v[152:155], v[184:187], v[28:31]
	v_mfma_f32_16x16x32_bf16 v[28:31], v[156:159], v[188:191], v[28:31]
	v_mfma_f32_16x16x32_bf16 v[24:27], v[164:167], v[188:191], v[24:27]
	v_mfma_f32_16x16x32_bf16 v[24:27], v[160:163], v[184:187], v[24:27]
	v_mfma_f32_16x16x32_bf16 v[8:11], v[160:163], v[192:195], v[8:11]
	v_mfma_f32_16x16x32_bf16 v[8:11], v[164:167], v[196:199], v[8:11]
	v_mfma_f32_16x16x32_bf16 v[12:15], v[156:159], v[196:199], v[12:15]
	v_mfma_f32_16x16x32_bf16 v[12:15], v[152:155], v[192:195], v[12:15]
	s_barrier
	s_add_u32 s72, s42, 0x40000
	s_addc_u32 s73, s43, 0
	s_add_i32 s71, s64, s51
	s_mov_b32 m0, s71
	s_nop 0
	global_load_lds_dwordx4 v130, s[72:73]
	s_add_i32 m0, s71, 0x2000
	s_nop 0
	global_load_lds_dwordx4 v134, s[72:73]
	s_waitcnt vmcnt(6)
	s_barrier
; #define PG8_STAGE(bufoff, gbase, voff) do { _Pragma("unroll") for (int _i = 0; _i < 2; ++_i) \
;         __builtin_amdgcn_global_load_lds((const unsigned*)((const char*)(gbase) + (voff)[_i]), (LAS unsigned*)(lds + (bufoff) + ldsw + _i * 8192), 16, 0, 0); } while (0)
; #define PG8_LDA(dst, b, h) do { _Pragma("unroll") for (int m = 0; m < 4; ++m) _Pragma("unroll") for (int k = 0; k < 2; ++k) dst[m][k] = *(const LAS bf16x8*)(lds + PG8_SA(b, h) + aoff + m * 2048 + k * 1024); } while (0)
; #define PG8_LDB(dst, b, h) do { _Pragma("unroll") for (int n = 0; n < 2; ++n) _Pragma("unroll") for (int k = 0; k < 2; ++k) dst[n][k] = *(const LAS bf16x8*)(lds + PG8_SB(b, h) + boff + n * 2048 + k * 1024); } while (0)
; #define PG8_MMA(ai, bj, At, Bt) do { __builtin_amdgcn_s_setprio(1); _Pragma("unroll") for (int m = 0; m < 4; ++m) _Pragma("unroll") for (int n = 0; n < 2; ++n) _Pragma("unroll") for (int k = 0; k < 2; ++k) \
;         acc[ai][bj][m][n] = __builtin_amdgcn_mfma_f32_16x16x32_bf16(Bt[n][k], At[m][k], acc[ai][bj][m][n], 0, 0, 0); __builtin_amdgcn_s_setprio(0); } while (0)
; #define PG8_WAIT_V(n) asm volatile("s_waitcnt vmcnt(" #n ")" ::: "memory")
; #define PG8_WAIT_L(n) asm volatile("s_waitcnt lgkmcnt(" #n ")" ::: "memory")
; #define PG8_BAR __builtin_amdgcn_s_barrier()
; #define PG8_SCHED __builtin_amdgcn_sched_barrier(0)
; template <class Epi, class Ptrs>
; __device__ __forceinline__ void gemm_phase(LAS unsigned char* lds, const int K, const StaticOrder& S, const Ptrs& P, const Epi& E) {
;     ...
;             PG8_WAIT_V(6); PG8_BAR; PG8_MMA(1, 1, At, B1); PG8_BAR;
;             PG8_LDB(B0, 1, 0); PG8_SCHED; PG8_LDA(At, 1, 0); PG8_STAGE(PG8_SA(0, 1), a2 + hstep, voffA);
;             PG8_WAIT_L(8); PG8_BAR; PG8_WAIT_L(0); PG8_MMA(0, 0, At, B0); PG8_BAR; PG8_SCHED;
;             PG8_LDB(B1, 1, 1); PG8_STAGE(PG8_SB(1, 0), b3, voffB);
;             PG8_BAR; PG8_WAIT_L(0); PG8_MMA(0, 1, At, B1); PG8_BAR;
;             PG8_LDA(At, 1, 1); PG8_STAGE(PG8_SA(1, 0), a3, voffA);
;             PG8_BAR; PG8_WAIT_L(0); PG8_MMA(1, 0, At, B0); PG8_BAR; PG8_SCHED;
	v_mfma_f32_16x16x32_bf16 v[52:55], v[200:203], v[168:171], v[52:55]
	v_mfma_f32_16x16x32_bf16 v[52:55], v[204:207], v[172:175], v[52:55]
	v_mfma_f32_16x16x32_bf16 v[48:51], v[214:217], v[172:175], v[48:51]
	v_mfma_f32_16x16x32_bf16 v[48:51], v[210:213], v[168:171], v[48:51]
	v_mfma_f32_16x16x32_bf16 v[32:35], v[210:213], v[176:179], v[32:35]
	v_mfma_f32_16x16x32_bf16 v[32:35], v[214:217], v[180:183], v[32:35]
	v_mfma_f32_16x16x32_bf16 v[36:39], v[204:207], v[180:183], v[36:39]
	v_mfma_f32_16x16x32_bf16 v[36:39], v[200:203], v[176:179], v[36:39]
	v_mfma_f32_16x16x32_bf16 v[20:23], v[200:203], v[184:187], v[20:23]
	v_mfma_f32_16x16x32_bf16 v[20:23], v[204:207], v[188:191], v[20:23]
	v_mfma_f32_16x16x32_bf16 v[16:19], v[214:217], v[188:191], v[16:19]
	v_mfma_f32_16x16x32_bf16 v[16:19], v[210:213], v[184:187], v[16:19]
	v_mfma_f32_16x16x32_bf16 v[0:3], v[210:213], v[192:195], v[0:3]
	v_mfma_f32_16x16x32_bf16 v[0:3], v[214:217], v[196:199], v[0:3]
	v_mfma_f32_16x16x32_bf16 v[4:7], v[204:207], v[196:199], v[4:7]
	v_mfma_f32_16x16x32_bf16 v[4:7], v[200:203], v[192:195], v[4:7]
	s_add_i32 s71, 0, 0x18000
	v_add_u32_e32 v164, s71, v147
	s_barrier
	ds_read_b128 v[152:155], v164
	ds_read_b128 v[156:159], v164 offset:1024
	ds_read_b128 v[160:163], v164 offset:2048
	ds_read_b128 v[164:167], v164 offset:3072
	s_add_u32 s44, s44, 0x40000
	s_addc_u32 s45, s45, 0
	s_mov_b32 m0, s57
	ds_read_b128 v[168:171], v150 offset:32768
	ds_read_b128 v[172:175], v150 offset:33792
	ds_read_b128 v[176:179], v150 offset:34816
	ds_read_b128 v[180:183], v150 offset:35840
	ds_read_b128 v[184:187], v150 offset:36864
	ds_read_b128 v[188:191], v150 offset:37888
	ds_read_b128 v[192:195], v150 offset:38912
	ds_read_b128 v[196:199], v150 offset:39936
	global_load_lds_dwordx4 v128, s[44:45]
	s_mov_b32 m0, s58
	s_nop 0
	global_load_lds_dwordx4 v132, s[44:45]
	s_waitcnt lgkmcnt(8)
	s_barrier
	s_waitcnt lgkmcnt(0)
	v_mfma_f32_16x16x32_bf16 v[124:127], v[152:155], v[168:171], v[124:127]
	v_mfma_f32_16x16x32_bf16 v[124:127], v[156:159], v[172:175], v[124:127]
	v_mfma_f32_16x16x32_bf16 v[120:123], v[164:167], v[172:175], v[120:123]
	v_mfma_f32_16x16x32_bf16 v[120:123], v[160:163], v[168:171], v[120:123]
	v_mfma_f32_16x16x32_bf16 v[104:107], v[160:163], v[176:179], v[104:107]
	v_mfma_f32_16x16x32_bf16 v[104:107], v[164:167], v[180:183], v[104:107]
	v_mfma_f32_16x16x32_bf16 v[108:111], v[156:159], v[180:183], v[108:111]
	v_mfma_f32_16x16x32_bf16 v[108:111], v[152:155], v[176:179], v[108:111]
	v_mfma_f32_16x16x32_bf16 v[92:95], v[152:155], v[184:187], v[92:95]
	v_mfma_f32_16x16x32_bf16 v[92:95], v[156:159], v[188:191], v[92:95]
	v_mfma_f32_16x16x32_bf16 v[88:91], v[164:167], v[188:191], v[88:91]
	v_mfma_f32_16x16x32_bf16 v[88:91], v[160:163], v[184:187], v[88:91]
	v_mfma_f32_16x16x32_bf16 v[72:75], v[160:163], v[192:195], v[72:75]
	v_mfma_f32_16x16x32_bf16 v[72:75], v[164:167], v[196:199], v[72:75]
	v_mfma_f32_16x16x32_bf16 v[76:79], v[156:159], v[196:199], v[76:79]
	v_mfma_f32_16x16x32_bf16 v[76:79], v[152:155], v[192:195], v[76:79]
	s_barrier
	s_add_i32 s44, 0, 0x1c000
	s_add_i32 s45, s71, s51
	v_add_u32_e32 v209, s44, v147
	v_lshl_add_u64 v[144:145], v[144:145], 0, s[12:13]
	s_mov_b32 m0, s45
	ds_read_b128 v[200:203], v209
	ds_read_b128 v[204:207], v209 offset:1024
	ds_read_b128 v[210:213], v209 offset:2048
	ds_read_b128 v[214:217], v209 offset:3072
	global_load_lds_dwordx4 v[144:145], off
	v_lshl_add_u64 v[144:145], v[218:219], 0, s[12:13]
	s_add_i32 m0, s45, 0x2000
	s_nop 0
	global_load_lds_dwordx4 v[144:145], off
	s_barrier
	s_waitcnt lgkmcnt(0)
	v_mfma_f32_16x16x32_bf16 v[116:119], v[200:203], v[168:171], v[116:119]
	v_mfma_f32_16x16x32_bf16 v[116:119], v[204:207], v[172:175], v[116:119]
	v_mfma_f32_16x16x32_bf16 v[112:115], v[214:217], v[172:175], v[112:115]
	v_mfma_f32_16x16x32_bf16 v[112:115], v[210:213], v[168:171], v[112:115]
	v_mfma_f32_16x16x32_bf16 v[96:99], v[210:213], v[176:179], v[96:99]
	v_mfma_f32_16x16x32_bf16 v[96:99], v[214:217], v[180:183], v[96:99]
	v_mfma_f32_16x16x32_bf16 v[100:103], v[204:207], v[180:183], v[100:103]
	v_mfma_f32_16x16x32_bf16 v[100:103], v[200:203], v[176:179], v[100:103]
	v_mfma_f32_16x16x32_bf16 v[84:87], v[200:203], v[184:187], v[84:87]
	v_mfma_f32_16x16x32_bf16 v[84:87], v[204:207], v[188:191], v[84:87]
	v_mfma_f32_16x16x32_bf16 v[80:83], v[214:217], v[188:191], v[80:83]
	v_mfma_f32_16x16x32_bf16 v[80:83], v[210:213], v[184:187], v[80:83]
	v_mfma_f32_16x16x32_bf16 v[64:67], v[210:213], v[192:195], v[64:67]
	v_mfma_f32_16x16x32_bf16 v[64:67], v[214:217], v[196:199], v[64:67]
	v_mfma_f32_16x16x32_bf16 v[68:71], v[204:207], v[196:199], v[68:71]
	v_mfma_f32_16x16x32_bf16 v[68:71], v[200:203], v[192:195], v[68:71]
	s_mov_b32 m0, s61
	v_lshl_add_u64 v[144:145], v[220:221], 0, s[12:13]
	s_barrier
	ds_read_b128 v[168:171], v150 offset:49152
	ds_read_b128 v[172:175], v150 offset:50176
	ds_read_b128 v[176:179], v150 offset:51200
	ds_read_b128 v[180:183], v150 offset:52224
	ds_read_b128 v[184:187], v150 offset:53248
	ds_read_b128 v[188:191], v150 offset:54272
	ds_read_b128 v[192:195], v150 offset:55296
	ds_read_b128 v[196:199], v150 offset:56320
	global_load_lds_dwordx4 v[144:145], off
	v_lshl_add_u64 v[144:145], v[222:223], 0, s[12:13]
	s_mov_b32 m0, s62
	s_nop 0
	global_load_lds_dwordx4 v[144:145], off
	s_barrier
; __device__ __forceinline__ unsigned cvt_pk_bf16(float lo, float hi) { unsigned r; asm volatile("v_cvt_pk_bf16_f32 %0, %1, %2" : "=v"(r) : "v"(lo), "v"(hi)); return r; }
; #define PG8_STAGE(bufoff, gbase, voff) do { _Pragma("unroll") for (int _i = 0; _i < 2; ++_i) \
;         __builtin_amdgcn_global_load_lds((const unsigned*)((const char*)(gbase) + (voff)[_i]), (LAS unsigned*)(lds + (bufoff) + ldsw + _i * 8192), 16, 0, 0); } while (0)
; #define PG8_LDA(dst, b, h) do { _Pragma("unroll") for (int m = 0; m < 4; ++m) _Pragma("unroll") for (int k = 0; k < 2; ++k) dst[m][k] = *(const LAS bf16x8*)(lds + PG8_SA(b, h) + aoff + m * 2048 + k * 1024); } while (0)
; #define PG8_WAIT_V(n) asm volatile("s_waitcnt vmcnt(" #n ")" ::: "memory")
; #define PG8_WAIT_L(n) asm volatile("s_waitcnt lgkmcnt(" #n ")" ::: "memory")
; #define PG8_BAR __builtin_amdgcn_s_barrier()
; #define PG8_SCHED __builtin_amdgcn_sched_barrier(0)
; template <class Epi, class Ptrs>
; __device__ __forceinline__ void gemm_phase(LAS unsigned char* lds, const int K, const StaticOrder& S, const Ptrs& P, const Epi& E) {
;     ...
;             PG8_BAR; PG8_WAIT_L(0); PG8_MMA(0, 1, At, B1); PG8_BAR;
;             PG8_LDA(At, 1, 1); PG8_STAGE(PG8_SA(1, 0), a3, voffA);
;             PG8_BAR; PG8_WAIT_L(0); PG8_MMA(1, 0, At, B0); PG8_BAR; PG8_SCHED;
;             PG8_STAGE(PG8_SB(1, 1), b3 + hstep, voffB);
;             PG8_WAIT_V(6); PG8_BAR; PG8_MMA(1, 1, At, B1); PG8_BAR;
;     __device__ __forceinline__ void operator()(const f32x4 (&acc)[2][2][4][2], const Unit& u, int ui, int wr, int wc, int fr, int fq) const {
;         const int row0 = u.pm * 256 + wr * 64 + fr, col0 = u.pn * 256 + wc * 32 + 8 * fq;
; #pragma unroll
;         for (int ai = 0; ai < 2; ++ai)
; #pragma unroll
;             for (int m = 0; m < 4; ++m) { bf16_t* rowp = hid + (size_t)(row0 + ai * 128 + m * 16) * DFF + col0;
; #pragma unroll
;                 for (int bj = 0; bj < 2; ++bj) { f32x4 v0 = acc[ai][bj][m][0], v1 = acc[ai][bj][m][1];
; #pragma unroll
;                     for (int j = 0; j < 4; ++j) { const float a = fmaxf(v0[j], 0.f), b = fmaxf(v1[j], 0.f); v0[j] = a * a; v1[j] = b * b; }
;                     u32x4 w; w.x = cvt_pk_bf16(v0[0], v0[1]); w.y = cvt_pk_bf16(v0[2], v0[3]); w.z = cvt_pk_bf16(v1[0], v1[1]); w.w = cvt_pk_bf16(v1[2], v1[3]);
;                     *(u32x4*)(rowp + bj * 128) = w; } }
	s_waitcnt lgkmcnt(0)
	v_mfma_f32_16x16x32_bf16 v[60:63], v[152:155], v[168:171], v[60:63]
	v_mfma_f32_16x16x32_bf16 v[60:63], v[156:159], v[172:175], v[60:63]
	v_mfma_f32_16x16x32_bf16 v[56:59], v[164:167], v[172:175], v[56:59]
	v_mfma_f32_16x16x32_bf16 v[56:59], v[160:163], v[168:171], v[56:59]
	v_mfma_f32_16x16x32_bf16 v[40:43], v[160:163], v[176:179], v[40:43]
	v_mfma_f32_16x16x32_bf16 v[40:43], v[164:167], v[180:183], v[40:43]
	v_mfma_f32_16x16x32_bf16 v[44:47], v[156:159], v[180:183], v[44:47]
	v_mfma_f32_16x16x32_bf16 v[44:47], v[152:155], v[176:179], v[44:47]
	v_mfma_f32_16x16x32_bf16 v[28:31], v[152:155], v[184:187], v[28:31]
	v_mfma_f32_16x16x32_bf16 v[28:31], v[156:159], v[188:191], v[28:31]
	v_mfma_f32_16x16x32_bf16 v[24:27], v[164:167], v[188:191], v[24:27]
	v_mfma_f32_16x16x32_bf16 v[24:27], v[160:163], v[184:187], v[24:27]
	v_mfma_f32_16x16x32_bf16 v[8:11], v[160:163], v[192:195], v[8:11]
	v_mfma_f32_16x16x32_bf16 v[8:11], v[164:167], v[196:199], v[8:11]
	v_mfma_f32_16x16x32_bf16 v[12:15], v[156:159], v[196:199], v[12:15]
	v_mfma_f32_16x16x32_bf16 v[12:15], v[152:155], v[192:195], v[12:15]
	s_barrier
	s_add_u32 s42, s42, 0x40080
	s_addc_u32 s43, s43, 0
	s_add_i32 s44, s44, s51
	s_mov_b32 m0, s44
	s_nop 0
	global_load_lds_dwordx4 v130, s[42:43]
	s_add_i32 m0, s44, 0x2000
	s_nop 0
	global_load_lds_dwordx4 v134, s[42:43]
	s_waitcnt vmcnt(6)
	s_barrier
	v_mfma_f32_16x16x32_bf16 v[52:55], v[200:203], v[168:171], v[52:55]
	v_mfma_f32_16x16x32_bf16 v[52:55], v[204:207], v[172:175], v[52:55]
	v_mfma_f32_16x16x32_bf16 v[48:51], v[214:217], v[172:175], v[48:51]
	v_mfma_f32_16x16x32_bf16 v[48:51], v[210:213], v[168:171], v[48:51]
	v_mfma_f32_16x16x32_bf16 v[32:35], v[210:213], v[176:179], v[32:35]
	v_mfma_f32_16x16x32_bf16 v[32:35], v[214:217], v[180:183], v[32:35]
	v_mfma_f32_16x16x32_bf16 v[36:39], v[204:207], v[180:183], v[36:39]
	v_mfma_f32_16x16x32_bf16 v[36:39], v[200:203], v[176:179], v[36:39]
	v_mfma_f32_16x16x32_bf16 v[20:23], v[200:203], v[184:187], v[20:23]
	v_mfma_f32_16x16x32_bf16 v[20:23], v[204:207], v[188:191], v[20:23]
	v_mfma_f32_16x16x32_bf16 v[16:19], v[214:217], v[188:191], v[16:19]
	v_mfma_f32_16x16x32_bf16 v[16:19], v[210:213], v[184:187], v[16:19]
	v_mfma_f32_16x16x32_bf16 v[0:3], v[210:213], v[192:195], v[0:3]
	v_mfma_f32_16x16x32_bf16 v[0:3], v[214:217], v[196:199], v[0:3]
	v_mfma_f32_16x16x32_bf16 v[4:7], v[204:207], v[196:199], v[4:7]
	v_mfma_f32_16x16x32_bf16 v[4:7], v[200:203], v[192:195], v[4:7]
	s_add_i32 s70, s70, 2
	s_add_u32 s40, s40, 0x100
	s_addc_u32 s41, s41, 0
	s_add_u32 s23, s23, 0x100
	s_addc_u32 s25, s25, 0
	s_cmp_gt_u32 s70, 13
	s_barrier
	s_cbranch_scc0 .LBB0_433
	s_nop 0
	s_nop 0
	s_nop 0
	s_nop 0
	s_nop 0
	s_nop 0
	s_nop 0
	s_nop 0
	s_nop 0
	s_nop 0
	s_nop 0
	s_nop 0
	s_nop 0
	s_nop 0
	s_nop 0
	s_nop 0
	s_nop 0
	s_nop 0
	s_nop 0
	s_nop 0
	s_nop 0
	s_nop 0
	s_nop 0
	s_nop 0
	s_nop 0
	s_nop 0
	s_nop 0
	s_nop 0
	s_nop 0
	s_nop 0
	s_nop 0
	s_nop 0
	s_nop 0
	s_nop 0
	s_nop 0
	s_nop 0
	s_nop 0
	s_nop 0
	v_lshl_add_u32 v152, s38, 8, v146
	v_max_f32_e32 v120, 0, v120
	v_ashrrev_i32_e32 v153, 31, v152
	v_max_f32_e32 v121, 0, v121
	v_max_f32_e32 v122, 0, v122
	v_lshl_or_b32 v144, s69, 8, v148
	v_lshlrev_b64 v[154:155], 13, v[152:153]
	v_mul_f32_e32 v153, v120, v120
	v_max_f32_e32 v120, 0, v125
	v_ashrrev_i32_e32 v145, 31, v144
	v_max_f32_e32 v124, 0, v124
	v_mul_f32_e32 v125, v121, v121
	v_max_f32_e32 v121, 0, v126
	v_mul_f32_e32 v126, v122, v122
	v_max_f32_e32 v122, 0, v127
	v_max_f32_e32 v123, 0, v123
	v_lshl_add_u64 v[154:155], s[10:11], 0, v[154:155]
	v_lshlrev_b64 v[156:157], 1, v[144:145]
	v_mul_f32_e32 v120, v120, v120
	v_max_f32_e32 v112, 0, v112
	v_lshl_add_u64 v[144:145], v[154:155], 0, v[156:157]
	v_mul_f32_e32 v124, v124, v124
	v_mul_f32_e32 v121, v121, v121
	v_mul_f32_e32 v122, v122, v122
	v_mul_f32_e32 v123, v123, v123
	v_cvt_pk_bf16_f32 v120, v124, v120
	v_max_f32_e32 v113, 0, v113
	v_max_f32_e32 v114, 0, v114
	v_cvt_pk_bf16_f32 v121, v121, v122
	v_cvt_pk_bf16_f32 v122, v153, v125
	v_cvt_pk_bf16_f32 v123, v126, v123
	global_store_dwordx4 v[144:145], v[120:123], off
	s_nop 1
	v_mul_f32_e32 v120, v112, v112
	v_max_f32_e32 v112, 0, v117
	v_max_f32_e32 v116, 0, v116
	v_mul_f32_e32 v117, v113, v113
	v_max_f32_e32 v113, 0, v118
	v_mul_f32_e32 v118, v114, v114
	v_max_f32_e32 v114, 0, v119
	v_max_f32_e32 v115, 0, v115
	v_mul_f32_e32 v112, v112, v112
	v_mul_f32_e32 v116, v116, v116
	v_mul_f32_e32 v113, v113, v113
	v_mul_f32_e32 v114, v114, v114
	v_mul_f32_e32 v115, v115, v115
	v_cvt_pk_bf16_f32 v112, v116, v112
	v_max_f32_e32 v104, 0, v104
	v_cvt_pk_bf16_f32 v113, v113, v114
	v_cvt_pk_bf16_f32 v114, v120, v117
	v_cvt_pk_bf16_f32 v115, v118, v115
	global_store_dwordx4 v[144:145], v[112:115], off offset:256
	s_nop 0
	v_max_f32_e32 v105, 0, v105
	v_or_b32_e32 v112, 16, v152
	v_max_f32_e32 v106, 0, v106
	v_ashrrev_i32_e32 v113, 31, v112
	v_mul_f32_e32 v114, v104, v104
	v_max_f32_e32 v104, 0, v109
	v_lshlrev_b64 v[112:113], 13, v[112:113]
	v_max_f32_e32 v108, 0, v108
	v_mul_f32_e32 v109, v105, v105
	v_max_f32_e32 v105, 0, v110
	v_mul_f32_e32 v110, v106, v106
	v_max_f32_e32 v106, 0, v111
	v_max_f32_e32 v107, 0, v107
	v_lshl_add_u64 v[112:113], s[10:11], 0, v[112:113]
	v_mul_f32_e32 v104, v104, v104
	v_max_f32_e32 v96, 0, v96
	v_lshl_add_u64 v[112:113], v[112:113], 0, v[156:157]
	v_mul_f32_e32 v108, v108, v108
	v_mul_f32_e32 v105, v105, v105
	v_mul_f32_e32 v106, v106, v106
	v_mul_f32_e32 v107, v107, v107
	v_cvt_pk_bf16_f32 v104, v108, v104
	v_max_f32_e32 v97, 0, v97
	v_max_f32_e32 v98, 0, v98
	v_cvt_pk_bf16_f32 v105, v105, v106
	v_cvt_pk_bf16_f32 v106, v114, v109
	v_cvt_pk_bf16_f32 v107, v110, v107
; __device__ __forceinline__ unsigned cvt_pk_bf16(float lo, float hi) { unsigned r; asm volatile("v_cvt_pk_bf16_f32 %0, %1, %2" : "=v"(r) : "v"(lo), "v"(hi)); return r; }
;     __device__ __forceinline__ void operator()(const f32x4 (&acc)[2][2][4][2], const Unit& u, int ui, int wr, int wc, int fr, int fq) const {
;     ...
;         for (int ai = 0; ai < 2; ++ai)
; #pragma unroll
;             for (int m = 0; m < 4; ++m) { bf16_t* rowp = hid + (size_t)(row0 + ai * 128 + m * 16) * DFF + col0;
; #pragma unroll
;                 for (int bj = 0; bj < 2; ++bj) { f32x4 v0 = acc[ai][bj][m][0], v1 = acc[ai][bj][m][1];
; #pragma unroll
;                     for (int j = 0; j < 4; ++j) { const float a = fmaxf(v0[j], 0.f), b = fmaxf(v1[j], 0.f); v0[j] = a * a; v1[j] = b * b; }
;                     u32x4 w; w.x = cvt_pk_bf16(v0[0], v0[1]); w.y = cvt_pk_bf16(v0[2], v0[3]); w.z = cvt_pk_bf16(v1[0], v1[1]); w.w = cvt_pk_bf16(v1[2], v1[3]);
;                     *(u32x4*)(rowp + bj * 128) = w; } }
	global_store_dwordx4 v[112:113], v[104:107], off
	s_nop 1
	v_mul_f32_e32 v104, v96, v96
	v_max_f32_e32 v96, 0, v101
	v_max_f32_e32 v100, 0, v100
	v_mul_f32_e32 v101, v97, v97
	v_max_f32_e32 v97, 0, v102
	v_mul_f32_e32 v102, v98, v98
	v_max_f32_e32 v98, 0, v103
	v_max_f32_e32 v99, 0, v99
	v_mul_f32_e32 v96, v96, v96
	v_mul_f32_e32 v100, v100, v100
	v_mul_f32_e32 v97, v97, v97
	v_mul_f32_e32 v98, v98, v98
	v_mul_f32_e32 v99, v99, v99
	v_cvt_pk_bf16_f32 v96, v100, v96
	v_max_f32_e32 v88, 0, v88
	v_cvt_pk_bf16_f32 v97, v97, v98
	v_cvt_pk_bf16_f32 v98, v104, v101
	v_cvt_pk_bf16_f32 v99, v102, v99
	global_store_dwordx4 v[112:113], v[96:99], off offset:256
	s_nop 0
	v_max_f32_e32 v89, 0, v89
	v_or_b32_e32 v96, 32, v152
	v_max_f32_e32 v90, 0, v90
	v_ashrrev_i32_e32 v97, 31, v96
	v_mul_f32_e32 v98, v88, v88
	v_max_f32_e32 v88, 0, v93
	v_lshlrev_b64 v[96:97], 13, v[96:97]
	v_max_f32_e32 v92, 0, v92
	v_mul_f32_e32 v93, v89, v89
	v_max_f32_e32 v89, 0, v94
	v_mul_f32_e32 v94, v90, v90
	v_max_f32_e32 v90, 0, v95
	v_max_f32_e32 v91, 0, v91
	v_lshl_add_u64 v[96:97], s[10:11], 0, v[96:97]
	v_mul_f32_e32 v88, v88, v88
	v_max_f32_e32 v80, 0, v80
	v_lshl_add_u64 v[96:97], v[96:97], 0, v[156:157]
	v_mul_f32_e32 v92, v92, v92
	v_mul_f32_e32 v89, v89, v89
	v_mul_f32_e32 v90, v90, v90
	v_mul_f32_e32 v91, v91, v91
	v_cvt_pk_bf16_f32 v88, v92, v88
	v_max_f32_e32 v81, 0, v81
	v_max_f32_e32 v82, 0, v82
	v_cvt_pk_bf16_f32 v89, v89, v90
	v_cvt_pk_bf16_f32 v90, v98, v93
	v_cvt_pk_bf16_f32 v91, v94, v91
	global_store_dwordx4 v[96:97], v[88:91], off
	s_nop 1
	v_mul_f32_e32 v88, v80, v80
	v_max_f32_e32 v80, 0, v85
	v_max_f32_e32 v84, 0, v84
	v_mul_f32_e32 v85, v81, v81
	v_max_f32_e32 v81, 0, v86
	v_mul_f32_e32 v86, v82, v82
	v_max_f32_e32 v82, 0, v87
	v_max_f32_e32 v83, 0, v83
	v_mul_f32_e32 v80, v80, v80
	v_mul_f32_e32 v84, v84, v84
	v_mul_f32_e32 v81, v81, v81
	v_mul_f32_e32 v82, v82, v82
	v_mul_f32_e32 v83, v83, v83
	v_cvt_pk_bf16_f32 v80, v84, v80
	v_max_f32_e32 v72, 0, v72
	v_cvt_pk_bf16_f32 v81, v81, v82
	v_cvt_pk_bf16_f32 v82, v88, v85
	v_cvt_pk_bf16_f32 v83, v86, v83
	global_store_dwordx4 v[96:97], v[80:83], off offset:256
	s_nop 0
	v_max_f32_e32 v73, 0, v73
	v_or_b32_e32 v80, 48, v152
	v_max_f32_e32 v74, 0, v74
	v_ashrrev_i32_e32 v81, 31, v80
	v_mul_f32_e32 v82, v72, v72
	v_max_f32_e32 v72, 0, v77
	v_lshlrev_b64 v[80:81], 13, v[80:81]
	v_max_f32_e32 v76, 0, v76
	v_mul_f32_e32 v77, v73, v73
	v_max_f32_e32 v73, 0, v78
	v_mul_f32_e32 v78, v74, v74
	v_max_f32_e32 v74, 0, v79
	v_max_f32_e32 v75, 0, v75
	v_lshl_add_u64 v[80:81], s[10:11], 0, v[80:81]
	v_mul_f32_e32 v72, v72, v72
	v_max_f32_e32 v64, 0, v64
	v_max_f32_e32 v65, 0, v65
	v_max_f32_e32 v66, 0, v66
	v_lshl_add_u64 v[80:81], v[80:81], 0, v[156:157]
	v_mul_f32_e32 v76, v76, v76
	v_mul_f32_e32 v73, v73, v73
	v_mul_f32_e32 v74, v74, v74
	v_mul_f32_e32 v75, v75, v75
	v_cvt_pk_bf16_f32 v72, v76, v72
	v_cvt_pk_bf16_f32 v73, v73, v74
	v_cvt_pk_bf16_f32 v74, v82, v77
	v_cvt_pk_bf16_f32 v75, v78, v75
	global_store_dwordx4 v[80:81], v[72:75], off
	v_max_f32_e32 v68, 0, v68
	v_max_f32_e32 v67, 0, v67
	v_mul_f32_e32 v72, v64, v64
	v_max_f32_e32 v64, 0, v69
	v_mul_f32_e32 v69, v65, v65
	v_max_f32_e32 v65, 0, v70
	v_mul_f32_e32 v70, v66, v66
	v_max_f32_e32 v66, 0, v71
	v_mul_f32_e32 v64, v64, v64
	v_mul_f32_e32 v65, v65, v65
	v_mul_f32_e32 v66, v66, v66
	v_max_f32_e32 v56, 0, v56
	v_mul_f32_e32 v68, v68, v68
	v_mul_f32_e32 v67, v67, v67
	v_cvt_pk_bf16_f32 v64, v68, v64
	v_cvt_pk_bf16_f32 v65, v65, v66
	v_cvt_pk_bf16_f32 v66, v72, v69
	v_max_f32_e32 v57, 0, v57
	v_max_f32_e32 v58, 0, v58
	v_cvt_pk_bf16_f32 v67, v70, v67
	global_store_dwordx4 v[80:81], v[64:67], off offset:256
	s_nop 0
	v_max_f32_e32 v60, 0, v60
	v_mul_f32_e32 v66, v56, v56
	v_max_f32_e32 v56, 0, v61
	v_mul_f32_e32 v61, v57, v57
	v_max_f32_e32 v57, 0, v62
	v_mul_f32_e32 v62, v58, v58
	v_max_f32_e32 v58, 0, v63
	v_mul_f32_e32 v60, v60, v60
	v_mul_f32_e32 v56, v56, v56
	v_max_f32_e32 v59, 0, v59
	v_mul_f32_e32 v57, v57, v57
	v_mul_f32_e32 v58, v58, v58
	v_cvt_pk_bf16_f32 v56, v60, v56
	v_add_co_u32_e32 v60, vcc, s65, v144
	v_max_f32_e32 v48, 0, v48
	v_max_f32_e32 v49, 0, v49
	v_max_f32_e32 v50, 0, v50
	v_mul_f32_e32 v59, v59, v59
	v_cvt_pk_bf16_f32 v57, v57, v58
	v_cvt_pk_bf16_f32 v58, v66, v61
	v_addc_co_u32_e32 v61, vcc, 0, v145, vcc
	v_cvt_pk_bf16_f32 v59, v62, v59
	global_store_dwordx4 v[60:61], v[56:59], off
	v_max_f32_e32 v52, 0, v52
	v_max_f32_e32 v51, 0, v51
	v_mul_f32_e32 v56, v48, v48
	v_max_f32_e32 v48, 0, v53
	v_mul_f32_e32 v53, v49, v49
	v_max_f32_e32 v49, 0, v54
	v_mul_f32_e32 v54, v50, v50
	v_max_f32_e32 v50, 0, v55
	v_mul_f32_e32 v48, v48, v48
	v_mul_f32_e32 v49, v49, v49
	v_mul_f32_e32 v50, v50, v50
; __device__ __forceinline__ unsigned cvt_pk_bf16(float lo, float hi) { unsigned r; asm volatile("v_cvt_pk_bf16_f32 %0, %1, %2" : "=v"(r) : "v"(lo), "v"(hi)); return r; }
; #define PG8_WAIT_V(n) asm volatile("s_waitcnt vmcnt(" #n ")" ::: "memory")
; #define PG8_BAR __builtin_amdgcn_s_barrier()
; template <class Epi, class Ptrs>
; __device__ __forceinline__ void gemm_phase(LAS unsigned char* lds, const int K, const StaticOrder& S, const Ptrs& P, const Epi& E) {
;     ...
;         if (!has_next) break;
; #pragma unroll
;         for (int a = 0; a < 2; ++a)
; #pragma unroll
;             for (int b = 0; b < 2; ++b)
; #pragma unroll
;                 for (int m = 0; m < 4; ++m)
; #pragma unroll
;                     for (int n = 0; n < 2; ++n) acc[a][b][m][n] = (f32x4){0.f, 0.f, 0.f, 0.f};
;         cur = nxt; cA = nA; cB = nB; ++ui;
;     }
;     PG8_WAIT_V(0);
;     if (wr == 0) PG8_BAR;
;     __device__ __forceinline__ void operator()(const f32x4 (&acc)[2][2][4][2], const Unit& u, int ui, int wr, int wc, int fr, int fq) const {
;     ...
;         for (int ai = 0; ai < 2; ++ai)
; #pragma unroll
;             for (int m = 0; m < 4; ++m) { bf16_t* rowp = hid + (size_t)(row0 + ai * 128 + m * 16) * DFF + col0;
; #pragma unroll
;                 for (int bj = 0; bj < 2; ++bj) { f32x4 v0 = acc[ai][bj][m][0], v1 = acc[ai][bj][m][1];
; #pragma unroll
;                     for (int j = 0; j < 4; ++j) { const float a = fmaxf(v0[j], 0.f), b = fmaxf(v1[j], 0.f); v0[j] = a * a; v1[j] = b * b; }
;                     u32x4 w; w.x = cvt_pk_bf16(v0[0], v0[1]); w.y = cvt_pk_bf16(v0[2], v0[3]); w.z = cvt_pk_bf16(v1[0], v1[1]); w.w = cvt_pk_bf16(v1[2], v1[3]);
;                     *(u32x4*)(rowp + bj * 128) = w; } }
	v_max_f32_e32 v40, 0, v40
	v_lshl_add_u64 v[64:65], v[144:145], 0, s[14:15]
	v_mul_f32_e32 v52, v52, v52
	v_mul_f32_e32 v51, v51, v51
	v_cvt_pk_bf16_f32 v48, v52, v48
	v_cvt_pk_bf16_f32 v49, v49, v50
	v_cvt_pk_bf16_f32 v50, v56, v53
	v_max_f32_e32 v41, 0, v41
	v_max_f32_e32 v42, 0, v42
	v_cvt_pk_bf16_f32 v51, v54, v51
	global_store_dwordx4 v[64:65], v[48:51], off offset:256
	s_nop 0
	v_max_f32_e32 v44, 0, v44
	v_mul_f32_e32 v50, v40, v40
	v_max_f32_e32 v40, 0, v45
	v_mul_f32_e32 v45, v41, v41
	v_max_f32_e32 v41, 0, v46
	v_mul_f32_e32 v46, v42, v42
	v_max_f32_e32 v42, 0, v47
	v_mul_f32_e32 v44, v44, v44
	v_mul_f32_e32 v40, v40, v40
	v_max_f32_e32 v43, 0, v43
	v_mul_f32_e32 v41, v41, v41
	v_mul_f32_e32 v42, v42, v42
	v_cvt_pk_bf16_f32 v40, v44, v40
	v_add_co_u32_e32 v44, vcc, s66, v144
	v_max_f32_e32 v32, 0, v32
	v_max_f32_e32 v33, 0, v33
	v_max_f32_e32 v34, 0, v34
	v_mul_f32_e32 v43, v43, v43
	v_cvt_pk_bf16_f32 v41, v41, v42
	v_cvt_pk_bf16_f32 v42, v50, v45
	v_addc_co_u32_e32 v45, vcc, 0, v145, vcc
	v_cvt_pk_bf16_f32 v43, v46, v43
	global_store_dwordx4 v[44:45], v[40:43], off
	v_max_f32_e32 v36, 0, v36
	v_max_f32_e32 v35, 0, v35
	v_mul_f32_e32 v40, v32, v32
	v_max_f32_e32 v32, 0, v37
	v_mul_f32_e32 v37, v33, v33
	v_max_f32_e32 v33, 0, v38
	v_mul_f32_e32 v38, v34, v34
	v_max_f32_e32 v34, 0, v39
	v_mul_f32_e32 v32, v32, v32
	v_mul_f32_e32 v33, v33, v33
	v_mul_f32_e32 v34, v34, v34
	v_max_f32_e32 v24, 0, v24
	v_lshl_add_u64 v[48:49], v[144:145], 0, s[16:17]
	v_mul_f32_e32 v36, v36, v36
	v_mul_f32_e32 v35, v35, v35
	v_cvt_pk_bf16_f32 v32, v36, v32
	v_cvt_pk_bf16_f32 v33, v33, v34
	v_cvt_pk_bf16_f32 v34, v40, v37
	v_max_f32_e32 v25, 0, v25
	v_max_f32_e32 v26, 0, v26
	v_cvt_pk_bf16_f32 v35, v38, v35
	global_store_dwordx4 v[48:49], v[32:35], off offset:256
	s_nop 0
	v_max_f32_e32 v28, 0, v28
	v_mul_f32_e32 v34, v24, v24
	v_max_f32_e32 v24, 0, v29
	v_mul_f32_e32 v29, v25, v25
	v_max_f32_e32 v25, 0, v30
	v_mul_f32_e32 v30, v26, v26
	v_max_f32_e32 v26, 0, v31
	v_mul_f32_e32 v28, v28, v28
	v_mul_f32_e32 v24, v24, v24
	v_max_f32_e32 v27, 0, v27
	v_mul_f32_e32 v25, v25, v25
	v_mul_f32_e32 v26, v26, v26
	v_cvt_pk_bf16_f32 v24, v28, v24
	v_add_co_u32_e32 v28, vcc, s67, v144
	v_max_f32_e32 v16, 0, v16
	v_max_f32_e32 v17, 0, v17
	v_max_f32_e32 v18, 0, v18
	v_mul_f32_e32 v27, v27, v27
	v_cvt_pk_bf16_f32 v25, v25, v26
	v_cvt_pk_bf16_f32 v26, v34, v29
	v_addc_co_u32_e32 v29, vcc, 0, v145, vcc
	v_cvt_pk_bf16_f32 v27, v30, v27
	global_store_dwordx4 v[28:29], v[24:27], off
	v_max_f32_e32 v20, 0, v20
	v_max_f32_e32 v19, 0, v19
	v_mul_f32_e32 v24, v16, v16
	v_max_f32_e32 v16, 0, v21
	v_mul_f32_e32 v21, v17, v17
	v_max_f32_e32 v17, 0, v22
	v_mul_f32_e32 v22, v18, v18
	v_max_f32_e32 v18, 0, v23
	v_mul_f32_e32 v16, v16, v16
	v_mul_f32_e32 v17, v17, v17
	v_mul_f32_e32 v18, v18, v18
	v_max_f32_e32 v8, 0, v8
	v_lshl_add_u64 v[32:33], v[144:145], 0, s[18:19]
	v_mul_f32_e32 v20, v20, v20
	v_mul_f32_e32 v19, v19, v19
	v_cvt_pk_bf16_f32 v16, v20, v16
	v_cvt_pk_bf16_f32 v17, v17, v18
	v_cvt_pk_bf16_f32 v18, v24, v21
	v_max_f32_e32 v9, 0, v9
	v_max_f32_e32 v10, 0, v10
	v_cvt_pk_bf16_f32 v19, v22, v19
	global_store_dwordx4 v[32:33], v[16:19], off offset:256
	s_nop 0
	v_max_f32_e32 v12, 0, v12
	v_mul_f32_e32 v18, v8, v8
	v_max_f32_e32 v8, 0, v13
	v_mul_f32_e32 v13, v9, v9
	v_max_f32_e32 v9, 0, v14
	v_mul_f32_e32 v14, v10, v10
	v_max_f32_e32 v10, 0, v15
	v_mul_f32_e32 v12, v12, v12
	v_mul_f32_e32 v8, v8, v8
	v_max_f32_e32 v11, 0, v11
	v_mul_f32_e32 v9, v9, v9
	v_mul_f32_e32 v10, v10, v10
	v_cvt_pk_bf16_f32 v8, v12, v8
	v_add_co_u32_e32 v12, vcc, s68, v144
	v_max_f32_e32 v0, 0, v0
	v_max_f32_e32 v1, 0, v1
	v_max_f32_e32 v2, 0, v2
	v_mul_f32_e32 v11, v11, v11
	v_cvt_pk_bf16_f32 v9, v9, v10
	v_cvt_pk_bf16_f32 v10, v18, v13
	v_addc_co_u32_e32 v13, vcc, 0, v145, vcc
	v_cvt_pk_bf16_f32 v11, v14, v11
	global_store_dwordx4 v[12:13], v[8:11], off
	v_max_f32_e32 v3, 0, v3
	v_max_f32_e32 v4, 0, v4
	v_mul_f32_e32 v8, v0, v0
	v_max_f32_e32 v0, 0, v5
	v_mul_f32_e32 v5, v1, v1
	v_max_f32_e32 v1, 0, v6
	v_mul_f32_e32 v6, v2, v2
	v_max_f32_e32 v2, 0, v7
	v_lshl_add_u64 v[16:17], v[144:145], 0, s[20:21]
	v_mul_f32_e32 v0, v0, v0
	v_mul_f32_e32 v1, v1, v1
	v_mul_f32_e32 v2, v2, v2
	v_mul_f32_e32 v3, v3, v3
	s_and_b64 vcc, exec, s[4:5]
	s_mov_b32 s69, s22
	s_mov_b32 s38, s24
	s_mov_b64 s[40:41], s[0:1]
	s_mov_b64 s[42:43], s[36:37]
	v_mul_f32_e32 v4, v4, v4
	v_cvt_pk_bf16_f32 v0, v4, v0
	v_cvt_pk_bf16_f32 v1, v1, v2
	v_cvt_pk_bf16_f32 v2, v8, v5
	v_cvt_pk_bf16_f32 v3, v6, v3
	global_store_dwordx4 v[16:17], v[0:3], off offset:256
	s_cbranch_vccz .LBB0_428
	s_waitcnt vmcnt(0)
	s_setprio 0
	s_cmpk_gt_u32 s46, 0xff
	s_cbranch_scc1 .LBB0_437
	s_barrier

; #define PG8_STAGE(bufoff, gbase, voff) do { _Pragma("unroll") for (int _i = 0; _i < 2; ++_i) \
;         __builtin_amdgcn_global_load_lds((const unsigned*)((const char*)(gbase) + (voff)[_i]), (LAS unsigned*)(lds + (bufoff) + ldsw + _i * 8192), 16, 0, 0); } while (0)
; #define PG8_LDA(dst, b, h) do { _Pragma("unroll") for (int m = 0; m < 4; ++m) _Pragma("unroll") for (int k = 0; k < 2; ++k) dst[m][k] = *(const LAS bf16x8*)(lds + PG8_SA(b, h) + aoff + m * 2048 + k * 1024); } while (0)
; #define PG8_LDB(dst, b, h) do { _Pragma("unroll") for (int n = 0; n < 2; ++n) _Pragma("unroll") for (int k = 0; k < 2; ++k) dst[n][k] = *(const LAS bf16x8*)(lds + PG8_SB(b, h) + boff + n * 2048 + k * 1024); } while (0)
; #define PG8_MMA(ai, bj, At, Bt) do { __builtin_amdgcn_s_setprio(1); _Pragma("unroll") for (int m = 0; m < 4; ++m) _Pragma("unroll") for (int n = 0; n < 2; ++n) _Pragma("unroll") for (int k = 0; k < 2; ++k) \
;         acc[ai][bj][m][n] = __builtin_amdgcn_mfma_f32_16x16x32_bf16(Bt[n][k], At[m][k], acc[ai][bj][m][n], 0, 0, 0); __builtin_amdgcn_s_setprio(0); } while (0)
; #define PG8_WAIT_L(n) asm volatile("s_waitcnt lgkmcnt(" #n ")" ::: "memory")
; #define PG8_BAR __builtin_amdgcn_s_barrier()
; #define PG8_SCHED __builtin_amdgcn_sched_barrier(0)
; template <class Epi, class Ptrs>
; __device__ __forceinline__ void gemm_phase(LAS unsigned char* lds, const int K, const StaticOrder& S, const Ptrs& P, const Epi& E) {
;     ...
;         for (int t = 0; t < nt; t += 2) {
;             const bool last = (t == nt - 2);
;             const char* a1 = cA + (size_t)(t + 1) * kstep;
;             const char* a2 = last ? nA : cA + (size_t)(t + 2) * kstep; const char* b2 = last ? nB : cB + (size_t)(t + 2) * kstep;
;             const char* a3 = a2 + kstep; const char* b3 = b2 + kstep;
;             PG8_LDB(B0, 0, 0); PG8_SCHED; PG8_LDA(At, 0, 0); PG8_STAGE(PG8_SA(1, 1), a1 + hstep, voffA);
;             PG8_WAIT_L(8); PG8_BAR; PG8_WAIT_L(0); PG8_MMA(0, 0, At, B0); PG8_BAR; PG8_SCHED;
;     ...
; #pragma unroll
;         for (int a = 0; a < 2; ++a)
; #pragma unroll
;             for (int b = 0; b < 2; ++b)
; #pragma unroll
;                 for (int m = 0; m < 4; ++m)
; #pragma unroll
;                     for (int n = 0; n < 2; ++n) acc[a][b][m][n] = (f32x4){0.f, 0.f, 0.f, 0.f};
.LBB0_521:
	s_add_u32 s20, s20, 0x100080
	s_nop 0
	s_nop 0
	s_nop 0
	s_nop 0
	s_nop 0
	s_nop 0
	s_nop 0
	s_nop 0
	s_nop 0
	s_nop 0
	s_nop 0
	s_nop 0
	s_nop 0
	s_nop 0
	s_nop 0
	s_nop 0
	s_nop 0
	s_nop 0
	s_nop 0
	s_nop 0
	s_nop 0
	s_nop 0
	s_nop 0
	s_nop 0
	s_nop 0
	s_nop 0
	s_nop 0
	s_nop 0
	s_nop 0
	s_nop 0
	s_nop 0
	s_nop 0
	s_nop 0
	s_nop 0
	s_nop 0
	s_nop 0
	s_nop 0
	s_nop 0
	s_nop 0
	s_nop 0
	s_nop 0
	s_nop 0
	s_nop 0
	s_nop 0
	s_nop 0
	s_nop 0
	s_nop 0
	s_nop 0
	s_nop 0
	s_nop 0
	s_nop 0
	s_nop 0
	s_nop 0
	s_nop 0
	s_nop 0
	s_nop 0
	s_nop 0
	s_nop 0
	s_nop 0
	s_nop 0
	s_nop 0
	s_addc_u32 s21, s21, 0
	s_add_u32 s11, s22, 0x100
	v_mov_b32_e32 v0, 0
	s_addc_u32 s13, s23, 0
	s_mov_b32 s46, -2
	v_mov_b32_e32 v1, v0
	v_mov_b32_e32 v2, v0
	v_mov_b32_e32 v3, v0
	v_mov_b32_e32 v4, v0
	v_mov_b32_e32 v5, v0
	v_mov_b32_e32 v6, v0
	v_mov_b32_e32 v7, v0
	v_mov_b32_e32 v12, v0
	v_mov_b32_e32 v13, v0
	v_mov_b32_e32 v14, v0
	v_mov_b32_e32 v15, v0
	v_mov_b32_e32 v20, v0
	v_mov_b32_e32 v21, v0
	v_mov_b32_e32 v22, v0
	v_mov_b32_e32 v23, v0
	v_mov_b32_e32 v28, v0
	v_mov_b32_e32 v29, v0
	v_mov_b32_e32 v30, v0
	v_mov_b32_e32 v31, v0
	v_mov_b32_e32 v36, v0
	v_mov_b32_e32 v37, v0
	v_mov_b32_e32 v38, v0
	v_mov_b32_e32 v39, v0
	v_mov_b32_e32 v44, v0
	v_mov_b32_e32 v45, v0
	v_mov_b32_e32 v46, v0
	v_mov_b32_e32 v47, v0
	v_mov_b32_e32 v52, v0
	v_mov_b32_e32 v53, v0
	v_mov_b32_e32 v54, v0
	v_mov_b32_e32 v55, v0
	v_mov_b32_e32 v8, v0
	v_mov_b32_e32 v9, v0
	v_mov_b32_e32 v10, v0
	v_mov_b32_e32 v11, v0
	v_mov_b32_e32 v16, v0
	v_mov_b32_e32 v17, v0
	v_mov_b32_e32 v18, v0
	v_mov_b32_e32 v19, v0
	v_mov_b32_e32 v24, v0
	v_mov_b32_e32 v25, v0
	v_mov_b32_e32 v26, v0
	v_mov_b32_e32 v27, v0
	v_mov_b32_e32 v32, v0
	v_mov_b32_e32 v33, v0
	v_mov_b32_e32 v34, v0
	v_mov_b32_e32 v35, v0
	v_mov_b32_e32 v40, v0
	v_mov_b32_e32 v41, v0
	v_mov_b32_e32 v42, v0
	v_mov_b32_e32 v43, v0
	v_mov_b32_e32 v48, v0
	v_mov_b32_e32 v49, v0
	v_mov_b32_e32 v50, v0
	v_mov_b32_e32 v51, v0
	v_mov_b32_e32 v56, v0
	v_mov_b32_e32 v57, v0
	v_mov_b32_e32 v58, v0
	v_mov_b32_e32 v59, v0
	v_mov_b32_e32 v60, v0
	v_mov_b32_e32 v61, v0
	v_mov_b32_e32 v62, v0
	v_mov_b32_e32 v63, v0
	v_mov_b32_e32 v64, v0
	v_mov_b32_e32 v65, v0
	v_mov_b32_e32 v66, v0
	v_mov_b32_e32 v67, v0
	v_mov_b32_e32 v68, v0
	v_mov_b32_e32 v69, v0
	v_mov_b32_e32 v70, v0
	v_mov_b32_e32 v71, v0
	v_mov_b32_e32 v80, v0
	v_mov_b32_e32 v81, v0
	v_mov_b32_e32 v82, v0
	v_mov_b32_e32 v83, v0
	v_mov_b32_e32 v84, v0
	v_mov_b32_e32 v85, v0
	v_mov_b32_e32 v86, v0
	v_mov_b32_e32 v87, v0
	v_mov_b32_e32 v96, v0
	v_mov_b32_e32 v97, v0
	v_mov_b32_e32 v98, v0
	v_mov_b32_e32 v99, v0
	v_mov_b32_e32 v100, v0
	v_mov_b32_e32 v101, v0
	v_mov_b32_e32 v102, v0
	v_mov_b32_e32 v103, v0
	v_mov_b32_e32 v108, v0
	v_mov_b32_e32 v109, v0
	v_mov_b32_e32 v110, v0
	v_mov_b32_e32 v111, v0
	v_mov_b32_e32 v116, v0
	v_mov_b32_e32 v117, v0
	v_mov_b32_e32 v118, v0
	v_mov_b32_e32 v119, v0
	v_mov_b32_e32 v72, v0
	v_mov_b32_e32 v73, v0
	v_mov_b32_e32 v74, v0
	v_mov_b32_e32 v75, v0
	v_mov_b32_e32 v76, v0
	v_mov_b32_e32 v77, v0
	v_mov_b32_e32 v78, v0
	v_mov_b32_e32 v79, v0
	v_mov_b32_e32 v88, v0
	v_mov_b32_e32 v89, v0
	v_mov_b32_e32 v90, v0
	v_mov_b32_e32 v91, v0
	v_mov_b32_e32 v92, v0
	v_mov_b32_e32 v93, v0
	v_mov_b32_e32 v94, v0
	v_mov_b32_e32 v95, v0
	v_mov_b32_e32 v104, v0
	v_mov_b32_e32 v105, v0
	v_mov_b32_e32 v106, v0
	v_mov_b32_e32 v107, v0
	v_mov_b32_e32 v112, v0
	v_mov_b32_e32 v113, v0
	v_mov_b32_e32 v114, v0
	v_mov_b32_e32 v115, v0
	v_mov_b32_e32 v120, v0
	v_mov_b32_e32 v121, v0
	v_mov_b32_e32 v122, v0
	v_mov_b32_e32 v123, v0
	v_mov_b32_e32 v124, v0
	v_mov_b32_e32 v125, v0
	v_mov_b32_e32 v126, v0
	v_mov_b32_e32 v127, v0
.LBB0_522:
	ds_read_b128 v[128:131], v193
	ds_read_b128 v[132:135], v193 offset:1024
	ds_read_b128 v[136:139], v193 offset:2048
	ds_read_b128 v[140:143], v193 offset:3072
	s_add_u32 s22, s20, 0xfff00080
	s_addc_u32 s23, s21, -1
	s_cmp_eq_u32 s46, 60
	s_cselect_b32 s25, s5, s23
	s_cselect_b32 s24, s4, s22
	s_cselect_b32 s23, s15, s13
	s_cselect_b32 s22, s14, s11
	s_add_i32 m0, s17, 0xc000
	ds_read_b128 v[144:147], v194
	ds_read_b128 v[148:151], v194 offset:1024
	ds_read_b128 v[152:155], v194 offset:2048
	ds_read_b128 v[156:159], v194 offset:3072
	ds_read_b128 v[176:179], v194 offset:4096
	ds_read_b128 v[180:183], v194 offset:5120
	ds_read_b128 v[196:199], v194 offset:6144
	ds_read_b128 v[200:203], v194 offset:7168
	global_load_lds_dwordx4 v168, s[20:21]
	s_add_i32 m0, s17, 0xe000
	s_nop 0
	global_load_lds_dwordx4 v170, s[20:21]
	s_waitcnt lgkmcnt(8)
	s_barrier
	s_waitcnt lgkmcnt(0)
	v_mfma_f32_16x16x32_bf16 v[124:127], v[128:131], v[144:147], v[124:127]
	v_mfma_f32_16x16x32_bf16 v[124:127], v[132:135], v[148:151], v[124:127]
	v_mfma_f32_16x16x32_bf16 v[120:123], v[140:143], v[148:151], v[120:123]
	v_mfma_f32_16x16x32_bf16 v[120:123], v[136:139], v[144:147], v[120:123]
	v_mfma_f32_16x16x32_bf16 v[104:107], v[136:139], v[152:155], v[104:107]
	v_mfma_f32_16x16x32_bf16 v[104:107], v[140:143], v[156:159], v[104:107]
	v_mfma_f32_16x16x32_bf16 v[112:115], v[132:135], v[156:159], v[112:115]
	v_mfma_f32_16x16x32_bf16 v[112:115], v[128:131], v[152:155], v[112:115]
	v_mfma_f32_16x16x32_bf16 v[92:95], v[128:131], v[176:179], v[92:95]
	v_mfma_f32_16x16x32_bf16 v[92:95], v[132:135], v[180:183], v[92:95]
	v_mfma_f32_16x16x32_bf16 v[88:91], v[140:143], v[180:183], v[88:91]
	v_mfma_f32_16x16x32_bf16 v[88:91], v[136:139], v[176:179], v[88:91]
	v_mfma_f32_16x16x32_bf16 v[72:75], v[136:139], v[196:199], v[72:75]
	v_mfma_f32_16x16x32_bf16 v[72:75], v[140:143], v[200:203], v[72:75]
	v_mfma_f32_16x16x32_bf16 v[76:79], v[132:135], v[200:203], v[76:79]
	v_mfma_f32_16x16x32_bf16 v[76:79], v[128:131], v[196:199], v[76:79]
	s_barrier
; #define PG8_STAGE(bufoff, gbase, voff) do { _Pragma("unroll") for (int _i = 0; _i < 2; ++_i) \
;         __builtin_amdgcn_global_load_lds((const unsigned*)((const char*)(gbase) + (voff)[_i]), (LAS unsigned*)(lds + (bufoff) + ldsw + _i * 8192), 16, 0, 0); } while (0)
; #define PG8_LDA(dst, b, h) do { _Pragma("unroll") for (int m = 0; m < 4; ++m) _Pragma("unroll") for (int k = 0; k < 2; ++k) dst[m][k] = *(const LAS bf16x8*)(lds + PG8_SA(b, h) + aoff + m * 2048 + k * 1024); } while (0)
; #define PG8_LDB(dst, b, h) do { _Pragma("unroll") for (int n = 0; n < 2; ++n) _Pragma("unroll") for (int k = 0; k < 2; ++k) dst[n][k] = *(const LAS bf16x8*)(lds + PG8_SB(b, h) + boff + n * 2048 + k * 1024); } while (0)
; #define PG8_MMA(ai, bj, At, Bt) do { __builtin_amdgcn_s_setprio(1); _Pragma("unroll") for (int m = 0; m < 4; ++m) _Pragma("unroll") for (int n = 0; n < 2; ++n) _Pragma("unroll") for (int k = 0; k < 2; ++k) \
;         acc[ai][bj][m][n] = __builtin_amdgcn_mfma_f32_16x16x32_bf16(Bt[n][k], At[m][k], acc[ai][bj][m][n], 0, 0, 0); __builtin_amdgcn_s_setprio(0); } while (0)
; #define PG8_WAIT_V(n) asm volatile("s_waitcnt vmcnt(" #n ")" ::: "memory")
; #define PG8_WAIT_L(n) asm volatile("s_waitcnt lgkmcnt(" #n ")" ::: "memory")
; #define PG8_BAR __builtin_amdgcn_s_barrier()
; #define PG8_SCHED __builtin_amdgcn_sched_barrier(0)
; template <class Epi, class Ptrs>
; __device__ __forceinline__ void gemm_phase(LAS unsigned char* lds, const int K, const StaticOrder& S, const Ptrs& P, const Epi& E) {
;     ...
;             PG8_LDB(B1, 0, 1); PG8_STAGE(PG8_SB(0, 0), b2, voffB);
;             PG8_BAR; PG8_WAIT_L(0); PG8_MMA(0, 1, At, B1); PG8_BAR;
;             PG8_LDA(At, 0, 1); PG8_STAGE(PG8_SA(0, 0), a2, voffA);
;             PG8_BAR; PG8_WAIT_L(0); PG8_MMA(1, 0, At, B0); PG8_BAR; PG8_SCHED;
;             PG8_STAGE(PG8_SB(0, 1), b2 + hstep, voffB);
;             PG8_WAIT_V(6); PG8_BAR; PG8_MMA(1, 1, At, B1); PG8_BAR;
;             PG8_LDB(B0, 1, 0); PG8_SCHED; PG8_LDA(At, 1, 0); PG8_STAGE(PG8_SA(0, 1), a2 + hstep, voffA);
;             PG8_WAIT_L(8); PG8_BAR; PG8_WAIT_L(0); PG8_MMA(0, 0, At, B0); PG8_BAR; PG8_SCHED;
	s_add_i32 s47, s42, s34
	v_lshl_add_u64 v[184:185], s[22:23], 0, v[162:163]
	s_mov_b32 m0, s47
	ds_read_b128 v[204:207], v195
	ds_read_b128 v[208:211], v195 offset:1024
	ds_read_b128 v[212:215], v195 offset:2048
	ds_read_b128 v[216:219], v195 offset:3072
	global_load_lds_dwordx4 v[184:185], off
	v_lshl_add_u64 v[220:221], s[22:23], 0, v[166:167]
	s_add_i32 m0, s47, 0x2000
	s_nop 0
	global_load_lds_dwordx4 v[220:221], off
	s_barrier
	s_waitcnt lgkmcnt(0)
	v_mfma_f32_16x16x32_bf16 v[116:119], v[204:207], v[144:147], v[116:119]
	v_mfma_f32_16x16x32_bf16 v[116:119], v[208:211], v[148:151], v[116:119]
	v_mfma_f32_16x16x32_bf16 v[108:111], v[216:219], v[148:151], v[108:111]
	v_mfma_f32_16x16x32_bf16 v[108:111], v[212:215], v[144:147], v[108:111]
	v_mfma_f32_16x16x32_bf16 v[96:99], v[212:215], v[152:155], v[96:99]
	v_mfma_f32_16x16x32_bf16 v[96:99], v[216:219], v[156:159], v[96:99]
	v_mfma_f32_16x16x32_bf16 v[100:103], v[208:211], v[156:159], v[100:103]
	v_mfma_f32_16x16x32_bf16 v[100:103], v[204:207], v[152:155], v[100:103]
	v_mfma_f32_16x16x32_bf16 v[84:87], v[204:207], v[176:179], v[84:87]
	v_mfma_f32_16x16x32_bf16 v[84:87], v[208:211], v[180:183], v[84:87]
	v_mfma_f32_16x16x32_bf16 v[80:83], v[216:219], v[180:183], v[80:83]
	v_mfma_f32_16x16x32_bf16 v[80:83], v[212:215], v[176:179], v[80:83]
	v_mfma_f32_16x16x32_bf16 v[64:67], v[212:215], v[196:199], v[64:67]
	v_mfma_f32_16x16x32_bf16 v[64:67], v[216:219], v[200:203], v[64:67]
	v_mfma_f32_16x16x32_bf16 v[68:71], v[208:211], v[200:203], v[68:71]
	v_mfma_f32_16x16x32_bf16 v[68:71], v[204:207], v[196:199], v[68:71]
	s_mov_b32 m0, s17
	v_lshl_add_u64 v[222:223], s[24:25], 0, v[160:161]
	s_barrier
	ds_read_b128 v[144:147], v194 offset:16384
	ds_read_b128 v[148:151], v194 offset:17408
	ds_read_b128 v[152:155], v194 offset:18432
	ds_read_b128 v[156:159], v194 offset:19456
	ds_read_b128 v[176:179], v194 offset:20480
	ds_read_b128 v[180:183], v194 offset:21504
	ds_read_b128 v[196:199], v194 offset:22528
	ds_read_b128 v[200:203], v194 offset:23552
	global_load_lds_dwordx4 v[222:223], off
	v_lshl_add_u64 v[224:225], s[24:25], 0, v[164:165]
	s_mov_b32 m0, s19
	s_nop 0
	global_load_lds_dwordx4 v[224:225], off
	s_barrier
	s_waitcnt lgkmcnt(0)
	v_mfma_f32_16x16x32_bf16 v[60:63], v[128:131], v[144:147], v[60:63]
	v_mfma_f32_16x16x32_bf16 v[60:63], v[132:135], v[148:151], v[60:63]
	v_mfma_f32_16x16x32_bf16 v[56:59], v[140:143], v[148:151], v[56:59]
	v_mfma_f32_16x16x32_bf16 v[56:59], v[136:139], v[144:147], v[56:59]
	v_mfma_f32_16x16x32_bf16 v[40:43], v[136:139], v[152:155], v[40:43]
	v_mfma_f32_16x16x32_bf16 v[40:43], v[140:143], v[156:159], v[40:43]
	v_mfma_f32_16x16x32_bf16 v[48:51], v[132:135], v[156:159], v[48:51]
	v_mfma_f32_16x16x32_bf16 v[48:51], v[128:131], v[152:155], v[48:51]
	v_mfma_f32_16x16x32_bf16 v[32:35], v[128:131], v[176:179], v[32:35]
	v_mfma_f32_16x16x32_bf16 v[32:35], v[132:135], v[180:183], v[32:35]
	v_mfma_f32_16x16x32_bf16 v[24:27], v[140:143], v[180:183], v[24:27]
	v_mfma_f32_16x16x32_bf16 v[24:27], v[136:139], v[176:179], v[24:27]
	v_mfma_f32_16x16x32_bf16 v[8:11], v[136:139], v[196:199], v[8:11]
	v_mfma_f32_16x16x32_bf16 v[8:11], v[140:143], v[200:203], v[8:11]
	v_mfma_f32_16x16x32_bf16 v[16:19], v[132:135], v[200:203], v[16:19]
	v_mfma_f32_16x16x32_bf16 v[16:19], v[128:131], v[196:199], v[16:19]
	s_barrier
	s_add_u32 s48, s22, 0x100000
	s_addc_u32 s49, s23, 0
	s_add_i32 s47, s43, s34
	s_mov_b32 m0, s47
	s_nop 0
	global_load_lds_dwordx4 v162, s[48:49]
	s_add_i32 m0, s47, 0x2000
	s_nop 0
	global_load_lds_dwordx4 v166, s[48:49]
	s_waitcnt vmcnt(6)
	s_barrier
	v_mfma_f32_16x16x32_bf16 v[52:55], v[204:207], v[144:147], v[52:55]
	v_mfma_f32_16x16x32_bf16 v[52:55], v[208:211], v[148:151], v[52:55]
	v_mfma_f32_16x16x32_bf16 v[44:47], v[216:219], v[148:151], v[44:47]
	v_mfma_f32_16x16x32_bf16 v[44:47], v[212:215], v[144:147], v[44:47]
	v_mfma_f32_16x16x32_bf16 v[28:31], v[212:215], v[152:155], v[28:31]
	v_mfma_f32_16x16x32_bf16 v[28:31], v[216:219], v[156:159], v[28:31]
	v_mfma_f32_16x16x32_bf16 v[36:39], v[208:211], v[156:159], v[36:39]
	v_mfma_f32_16x16x32_bf16 v[36:39], v[204:207], v[152:155], v[36:39]
	v_mfma_f32_16x16x32_bf16 v[20:23], v[204:207], v[176:179], v[20:23]
	v_mfma_f32_16x16x32_bf16 v[20:23], v[208:211], v[180:183], v[20:23]
	v_mfma_f32_16x16x32_bf16 v[12:15], v[216:219], v[180:183], v[12:15]
	v_mfma_f32_16x16x32_bf16 v[12:15], v[212:215], v[176:179], v[12:15]
	v_mfma_f32_16x16x32_bf16 v[0:3], v[212:215], v[196:199], v[0:3]
	v_mfma_f32_16x16x32_bf16 v[0:3], v[216:219], v[200:203], v[0:3]
	v_mfma_f32_16x16x32_bf16 v[4:7], v[208:211], v[200:203], v[4:7]
	v_mfma_f32_16x16x32_bf16 v[4:7], v[204:207], v[196:199], v[4:7]
	s_add_i32 s47, 0, 0x18000
	v_add_u32_e32 v140, s47, v187
	s_barrier
	ds_read_b128 v[128:131], v140
	ds_read_b128 v[132:135], v140 offset:1024
	ds_read_b128 v[136:139], v140 offset:2048
	ds_read_b128 v[140:143], v140 offset:3072
	s_add_u32 s24, s24, 0x100000
	s_addc_u32 s25, s25, 0
	s_mov_b32 m0, s40
	ds_read_b128 v[144:147], v194 offset:32768
	ds_read_b128 v[148:151], v194 offset:33792
	ds_read_b128 v[152:155], v194 offset:34816
	ds_read_b128 v[156:159], v194 offset:35840
	ds_read_b128 v[176:179], v194 offset:36864
	ds_read_b128 v[180:183], v194 offset:37888
	ds_read_b128 v[196:199], v194 offset:38912
	ds_read_b128 v[200:203], v194 offset:39936
	global_load_lds_dwordx4 v160, s[24:25]
	s_mov_b32 m0, s41
	s_nop 0
	global_load_lds_dwordx4 v164, s[24:25]
	s_waitcnt lgkmcnt(8)
	s_barrier
; #define PG8_STAGE(bufoff, gbase, voff) do { _Pragma("unroll") for (int _i = 0; _i < 2; ++_i) \
;         __builtin_amdgcn_global_load_lds((const unsigned*)((const char*)(gbase) + (voff)[_i]), (LAS unsigned*)(lds + (bufoff) + ldsw + _i * 8192), 16, 0, 0); } while (0)
; #define PG8_LDA(dst, b, h) do { _Pragma("unroll") for (int m = 0; m < 4; ++m) _Pragma("unroll") for (int k = 0; k < 2; ++k) dst[m][k] = *(const LAS bf16x8*)(lds + PG8_SA(b, h) + aoff + m * 2048 + k * 1024); } while (0)
; #define PG8_LDB(dst, b, h) do { _Pragma("unroll") for (int n = 0; n < 2; ++n) _Pragma("unroll") for (int k = 0; k < 2; ++k) dst[n][k] = *(const LAS bf16x8*)(lds + PG8_SB(b, h) + boff + n * 2048 + k * 1024); } while (0)
; #define PG8_MMA(ai, bj, At, Bt) do { __builtin_amdgcn_s_setprio(1); _Pragma("unroll") for (int m = 0; m < 4; ++m) _Pragma("unroll") for (int n = 0; n < 2; ++n) _Pragma("unroll") for (int k = 0; k < 2; ++k) \
;         acc[ai][bj][m][n] = __builtin_amdgcn_mfma_f32_16x16x32_bf16(Bt[n][k], At[m][k], acc[ai][bj][m][n], 0, 0, 0); __builtin_amdgcn_s_setprio(0); } while (0)
; #define PG8_WAIT_V(n) asm volatile("s_waitcnt vmcnt(" #n ")" ::: "memory")
; #define PG8_WAIT_L(n) asm volatile("s_waitcnt lgkmcnt(" #n ")" ::: "memory")
; #define PG8_BAR __builtin_amdgcn_s_barrier()
; #define PG8_SCHED __builtin_amdgcn_sched_barrier(0)
; template <class Epi, class Ptrs>
; __device__ __forceinline__ void gemm_phase(LAS unsigned char* lds, const int K, const StaticOrder& S, const Ptrs& P, const Epi& E) {
;     ...
;             PG8_WAIT_L(8); PG8_BAR; PG8_WAIT_L(0); PG8_MMA(0, 0, At, B0); PG8_BAR; PG8_SCHED;
;             PG8_LDB(B1, 1, 1); PG8_STAGE(PG8_SB(1, 0), b3, voffB);
;             PG8_BAR; PG8_WAIT_L(0); PG8_MMA(0, 1, At, B1); PG8_BAR;
;             PG8_LDA(At, 1, 1); PG8_STAGE(PG8_SA(1, 0), a3, voffA);
;             PG8_BAR; PG8_WAIT_L(0); PG8_MMA(1, 0, At, B0); PG8_BAR; PG8_SCHED;
;             PG8_STAGE(PG8_SB(1, 1), b3 + hstep, voffB);
;             PG8_WAIT_V(6); PG8_BAR; PG8_MMA(1, 1, At, B1); PG8_BAR;
	s_waitcnt lgkmcnt(0)
	v_mfma_f32_16x16x32_bf16 v[124:127], v[128:131], v[144:147], v[124:127]
	v_mfma_f32_16x16x32_bf16 v[124:127], v[132:135], v[148:151], v[124:127]
	v_mfma_f32_16x16x32_bf16 v[120:123], v[140:143], v[148:151], v[120:123]
	v_mfma_f32_16x16x32_bf16 v[120:123], v[136:139], v[144:147], v[120:123]
	v_mfma_f32_16x16x32_bf16 v[104:107], v[136:139], v[152:155], v[104:107]
	v_mfma_f32_16x16x32_bf16 v[104:107], v[140:143], v[156:159], v[104:107]
	v_mfma_f32_16x16x32_bf16 v[112:115], v[132:135], v[156:159], v[112:115]
	v_mfma_f32_16x16x32_bf16 v[112:115], v[128:131], v[152:155], v[112:115]
	v_mfma_f32_16x16x32_bf16 v[92:95], v[128:131], v[176:179], v[92:95]
	v_mfma_f32_16x16x32_bf16 v[92:95], v[132:135], v[180:183], v[92:95]
	v_mfma_f32_16x16x32_bf16 v[88:91], v[140:143], v[180:183], v[88:91]
	v_mfma_f32_16x16x32_bf16 v[88:91], v[136:139], v[176:179], v[88:91]
	v_mfma_f32_16x16x32_bf16 v[72:75], v[136:139], v[196:199], v[72:75]
	v_mfma_f32_16x16x32_bf16 v[72:75], v[140:143], v[200:203], v[72:75]
	v_mfma_f32_16x16x32_bf16 v[76:79], v[132:135], v[200:203], v[76:79]
	v_mfma_f32_16x16x32_bf16 v[76:79], v[128:131], v[196:199], v[76:79]
	s_barrier
	s_add_i32 s24, 0, 0x1c000
	s_add_i32 s25, s47, s34
	v_add_u32_e32 v216, s24, v187
	v_lshl_add_u64 v[184:185], v[184:185], 0, s[8:9]
	s_mov_b32 m0, s25
	ds_read_b128 v[204:207], v216
	ds_read_b128 v[208:211], v216 offset:1024
	ds_read_b128 v[212:215], v216 offset:2048
	ds_read_b128 v[216:219], v216 offset:3072
	global_load_lds_dwordx4 v[184:185], off
	v_lshl_add_u64 v[184:185], v[220:221], 0, s[8:9]
	s_add_i32 m0, s25, 0x2000
	s_nop 0
	global_load_lds_dwordx4 v[184:185], off
	s_barrier
	s_waitcnt lgkmcnt(0)
	v_mfma_f32_16x16x32_bf16 v[116:119], v[204:207], v[144:147], v[116:119]
	v_mfma_f32_16x16x32_bf16 v[116:119], v[208:211], v[148:151], v[116:119]
	v_mfma_f32_16x16x32_bf16 v[108:111], v[216:219], v[148:151], v[108:111]
	v_mfma_f32_16x16x32_bf16 v[108:111], v[212:215], v[144:147], v[108:111]
	v_mfma_f32_16x16x32_bf16 v[96:99], v[212:215], v[152:155], v[96:99]
	v_mfma_f32_16x16x32_bf16 v[96:99], v[216:219], v[156:159], v[96:99]
	v_mfma_f32_16x16x32_bf16 v[100:103], v[208:211], v[156:159], v[100:103]
	v_mfma_f32_16x16x32_bf16 v[100:103], v[204:207], v[152:155], v[100:103]
	v_mfma_f32_16x16x32_bf16 v[84:87], v[204:207], v[176:179], v[84:87]
	v_mfma_f32_16x16x32_bf16 v[84:87], v[208:211], v[180:183], v[84:87]
	v_mfma_f32_16x16x32_bf16 v[80:83], v[216:219], v[180:183], v[80:83]
	v_mfma_f32_16x16x32_bf16 v[80:83], v[212:215], v[176:179], v[80:83]
	v_mfma_f32_16x16x32_bf16 v[64:67], v[212:215], v[196:199], v[64:67]
	v_mfma_f32_16x16x32_bf16 v[64:67], v[216:219], v[200:203], v[64:67]
	v_mfma_f32_16x16x32_bf16 v[68:71], v[208:211], v[200:203], v[68:71]
	v_mfma_f32_16x16x32_bf16 v[68:71], v[204:207], v[196:199], v[68:71]
	s_mov_b32 m0, s28
	v_lshl_add_u64 v[184:185], v[222:223], 0, s[8:9]
	s_barrier
	ds_read_b128 v[144:147], v194 offset:49152
	ds_read_b128 v[148:151], v194 offset:50176
	ds_read_b128 v[152:155], v194 offset:51200
	ds_read_b128 v[156:159], v194 offset:52224
	ds_read_b128 v[176:179], v194 offset:53248
	ds_read_b128 v[180:183], v194 offset:54272
	ds_read_b128 v[196:199], v194 offset:55296
	ds_read_b128 v[200:203], v194 offset:56320
	global_load_lds_dwordx4 v[184:185], off
	v_lshl_add_u64 v[184:185], v[224:225], 0, s[8:9]
	s_mov_b32 m0, s29
	s_nop 0
	global_load_lds_dwordx4 v[184:185], off
	s_barrier
	s_waitcnt lgkmcnt(0)
	v_mfma_f32_16x16x32_bf16 v[60:63], v[128:131], v[144:147], v[60:63]
	v_mfma_f32_16x16x32_bf16 v[60:63], v[132:135], v[148:151], v[60:63]
	v_mfma_f32_16x16x32_bf16 v[56:59], v[140:143], v[148:151], v[56:59]
	v_mfma_f32_16x16x32_bf16 v[56:59], v[136:139], v[144:147], v[56:59]
	v_mfma_f32_16x16x32_bf16 v[40:43], v[136:139], v[152:155], v[40:43]
	v_mfma_f32_16x16x32_bf16 v[40:43], v[140:143], v[156:159], v[40:43]
	v_mfma_f32_16x16x32_bf16 v[48:51], v[132:135], v[156:159], v[48:51]
	v_mfma_f32_16x16x32_bf16 v[48:51], v[128:131], v[152:155], v[48:51]
	v_mfma_f32_16x16x32_bf16 v[32:35], v[128:131], v[176:179], v[32:35]
	v_mfma_f32_16x16x32_bf16 v[32:35], v[132:135], v[180:183], v[32:35]
	v_mfma_f32_16x16x32_bf16 v[24:27], v[140:143], v[180:183], v[24:27]
	v_mfma_f32_16x16x32_bf16 v[24:27], v[136:139], v[176:179], v[24:27]
	v_mfma_f32_16x16x32_bf16 v[8:11], v[136:139], v[196:199], v[8:11]
	v_mfma_f32_16x16x32_bf16 v[8:11], v[140:143], v[200:203], v[8:11]
	v_mfma_f32_16x16x32_bf16 v[16:19], v[132:135], v[200:203], v[16:19]
	v_mfma_f32_16x16x32_bf16 v[16:19], v[128:131], v[196:199], v[16:19]
	s_barrier
	s_add_u32 s22, s22, 0x100080
	s_addc_u32 s23, s23, 0
	s_add_i32 s24, s24, s34
	s_mov_b32 m0, s24
	s_nop 0
	global_load_lds_dwordx4 v162, s[22:23]
	s_add_i32 m0, s24, 0x2000
	s_nop 0
	global_load_lds_dwordx4 v166, s[22:23]
	s_waitcnt vmcnt(6)
	s_barrier
	v_mfma_f32_16x16x32_bf16 v[52:55], v[204:207], v[144:147], v[52:55]
	v_mfma_f32_16x16x32_bf16 v[52:55], v[208:211], v[148:151], v[52:55]
	v_mfma_f32_16x16x32_bf16 v[44:47], v[216:219], v[148:151], v[44:47]
	v_mfma_f32_16x16x32_bf16 v[44:47], v[212:215], v[144:147], v[44:47]
	v_mfma_f32_16x16x32_bf16 v[28:31], v[212:215], v[152:155], v[28:31]
	v_mfma_f32_16x16x32_bf16 v[28:31], v[216:219], v[156:159], v[28:31]
	v_mfma_f32_16x16x32_bf16 v[36:39], v[208:211], v[156:159], v[36:39]
	v_mfma_f32_16x16x32_bf16 v[36:39], v[204:207], v[152:155], v[36:39]
	v_mfma_f32_16x16x32_bf16 v[20:23], v[204:207], v[176:179], v[20:23]
	v_mfma_f32_16x16x32_bf16 v[20:23], v[208:211], v[180:183], v[20:23]
	v_mfma_f32_16x16x32_bf16 v[12:15], v[216:219], v[180:183], v[12:15]
	v_mfma_f32_16x16x32_bf16 v[12:15], v[212:215], v[176:179], v[12:15]
	v_mfma_f32_16x16x32_bf16 v[0:3], v[212:215], v[196:199], v[0:3]
	v_mfma_f32_16x16x32_bf16 v[0:3], v[216:219], v[200:203], v[0:3]
	v_mfma_f32_16x16x32_bf16 v[4:7], v[208:211], v[200:203], v[4:7]
	v_mfma_f32_16x16x32_bf16 v[4:7], v[204:207], v[196:199], v[4:7]
	s_add_i32 s46, s46, 2
	s_add_u32 s20, s20, 0x100
	s_addc_u32 s21, s21, 0
	s_add_u32 s11, s11, 0x100
	s_addc_u32 s13, s13, 0
	s_cmp_gt_u32 s46, 61
	s_barrier
; __device__ __forceinline__ float bf_lo(unsigned w) { return __uint_as_float(w << 16); }
; __device__ __forceinline__ float bf_hi(unsigned w) { return __uint_as_float(w & 0xffff0000u); }
;     __device__ __forceinline__ void operator()(const f32x4 (&acc)[2][2][4][2], const Unit& u, int ui, int wr, int wc, int fr, int fq) const {
;         const int rl0 = wr * 64 + fr, col0 = u.pn * 256 + wc * 32 + 8 * fq;
;         u32x4 xv[2][4][2];
; #pragma unroll
;         for (int ai = 0; ai < 2; ++ai)
; #pragma unroll
;             for (int m = 0; m < 4; ++m)
; #pragma unroll
;                 for (int bj = 0; bj < 2; ++bj) xv[ai][m][bj] = *(const u32x4*)(xb + (size_t)(u.pm * 256 + rl0 + ai * 128 + m * 16) * DM + col0 + bj * 128);
; #pragma unroll
;         for (int ai = 0; ai < 2; ++ai)
; #pragma unroll
;             for (int m = 0; m < 4; ++m) { const int rl = rl0 + ai * 128 + m * 16; float* rowp = out + (size_t)(u.pm * 256 + rl) * DM + col0;
;                 const float r2 = tab[ui * 256 + rl];
; #pragma unroll
;                 for (int bj = 0; bj < 2; ++bj) { const u32x4 x = xv[ai][m][bj];
;                     const f32x4 x0 = {bf_lo(x.x), bf_hi(x.x), bf_lo(x.y), bf_hi(x.y)}, x1 = {bf_lo(x.z), bf_hi(x.z), bf_lo(x.w), bf_hi(x.w)};
;                     *(f32x4*)(rowp + bj * 128) = acc[ai][bj][m][0] * r2 + x0; *(f32x4*)(rowp + bj * 128 + 4) = acc[ai][bj][m][1] * r2 + x1; } }
	s_cbranch_scc0 .LBB0_522
	s_nop 0
	s_nop 0
	s_nop 0
	s_nop 0
	s_nop 0
	s_nop 0
	s_nop 0
	s_nop 0
	s_nop 0
	s_nop 0
	s_nop 0
	s_nop 0
	s_nop 0
	s_nop 0
	s_nop 0
	s_nop 0
	s_nop 0
	s_nop 0
	s_nop 0
	s_nop 0
	s_nop 0
	s_nop 0
	s_nop 0
	s_nop 0
	s_nop 0
	s_nop 0
	s_nop 0
	s_nop 0
	s_nop 0
	s_nop 0
	s_nop 0
	s_nop 0
	s_nop 0
	s_nop 0
	s_nop 0
	s_nop 0
	s_nop 0
	s_nop 0
	s_lshl_b32 s11, s18, 8
	v_lshl_or_b32 v128, s16, 8, v191
	v_add_u32_e32 v130, s11, v186
	v_ashrrev_i32_e32 v129, 31, v128
	v_ashrrev_i32_e32 v131, 31, v130
	v_lshl_add_u64 v[132:133], v[128:129], 1, s[6:7]
	v_lshlrev_b64 v[134:135], 11, v[130:131]
	v_lshl_add_u64 v[134:135], v[132:133], 0, v[134:135]
	global_load_dwordx4 v[198:201], v[134:135], off
	global_load_dwordx4 v[202:205], v[134:135], off offset:256
	v_or_b32_e32 v134, 16, v130
	v_ashrrev_i32_e32 v135, 31, v134
	v_lshlrev_b64 v[134:135], 11, v[134:135]
	v_lshl_add_u64 v[134:135], v[132:133], 0, v[134:135]
	global_load_dwordx4 v[206:209], v[134:135], off
	global_load_dwordx4 v[210:213], v[134:135], off offset:256
	v_or_b32_e32 v136, 32, v130
	v_ashrrev_i32_e32 v137, 31, v136
	v_or_b32_e32 v138, 48, v130
	v_add_u32_e32 v184, 0x80, v130
	v_add_u32_e32 v182, 0x90, v130
	v_add_u32_e32 v180, 0xa0, v130
	v_add_u32_e32 v178, 0xb0, v130
	v_lshlrev_b64 v[176:177], 2, v[128:129]
	v_lshlrev_b64 v[128:129], 12, v[130:131]
	v_lshlrev_b64 v[130:131], 11, v[136:137]
	v_lshl_add_u64 v[130:131], v[132:133], 0, v[130:131]
	global_load_dwordx4 v[214:217], v[130:131], off
	v_ashrrev_i32_e32 v139, 31, v138
	v_ashrrev_i32_e32 v185, 31, v184
	v_ashrrev_i32_e32 v183, 31, v182
	v_ashrrev_i32_e32 v181, 31, v180
	v_ashrrev_i32_e32 v179, 31, v178
	v_lshlrev_b64 v[134:135], 11, v[138:139]
	v_lshlrev_b64 v[136:137], 11, v[184:185]
	v_lshlrev_b64 v[138:139], 11, v[182:183]
	v_lshl_add_u32 v196, s45, 10, v192
	v_lshlrev_b64 v[140:141], 11, v[180:181]
	v_lshlrev_b64 v[142:143], 11, v[178:179]
	v_lshl_add_u64 v[128:129], s[26:27], 0, v[128:129]
	v_lshl_add_u64 v[134:135], v[132:133], 0, v[134:135]
	v_lshl_add_u64 v[136:137], v[132:133], 0, v[136:137]
	v_lshl_add_u64 v[138:139], v[132:133], 0, v[138:139]
	ds_read2_b32 v[230:231], v196 offset1:16
	v_lshl_add_u64 v[234:235], v[132:133], 0, v[140:141]
	v_lshl_add_u64 v[236:237], v[132:133], 0, v[142:143]
	v_lshl_add_u64 v[238:239], v[128:129], 0, v[176:177]
	global_load_dwordx4 v[218:221], v[130:131], off offset:256
	global_load_dwordx4 v[222:225], v[134:135], off
	global_load_dwordx4 v[226:229], v[134:135], off offset:256
	global_load_dwordx4 v[156:159], v[136:137], off
	global_load_dwordx4 v[152:155], v[136:137], off offset:256
	global_load_dwordx4 v[148:151], v[138:139], off
	global_load_dwordx4 v[144:147], v[138:139], off offset:256
	global_load_dwordx4 v[140:143], v[234:235], off
	s_nop 0
	global_load_dwordx4 v[136:139], v[234:235], off offset:256
	global_load_dwordx4 v[132:135], v[236:237], off
	global_load_dwordx4 v[128:131], v[236:237], off offset:256
	v_add_u32_e32 v232, s11, v188
	v_ashrrev_i32_e32 v233, 31, v232
	s_and_b64 vcc, exec, s[0:1]
	s_mov_b32 s16, s10
	s_mov_b32 s18, s12
	s_mov_b64 s[20:21], s[4:5]
	s_mov_b64 s[22:23], s[14:15]
	s_mov_b32 s45, s44
	s_waitcnt vmcnt(0)
	v_lshlrev_b32_e32 v234, 16, v198
	v_and_b32_e32 v235, 0xffff0000, v198
	v_lshlrev_b32_e32 v198, 16, v199
	v_and_b32_e32 v199, 0xffff0000, v199
	v_lshlrev_b32_e32 v242, 16, v204
	v_and_b32_e32 v243, 0xffff0000, v204
	v_lshlrev_b32_e32 v236, 16, v200
	v_and_b32_e32 v237, 0xffff0000, v200
	v_lshlrev_b32_e32 v200, 16, v201
	v_and_b32_e32 v201, 0xffff0000, v201
	v_lshlrev_b32_e32 v240, 16, v202
	v_and_b32_e32 v241, 0xffff0000, v202
	v_lshlrev_b32_e32 v202, 16, v203
	v_and_b32_e32 v203, 0xffff0000, v203
	v_lshlrev_b32_e32 v204, 16, v205
	v_and_b32_e32 v205, 0xffff0000, v205
	s_waitcnt lgkmcnt(0)
	v_pk_fma_f32 v[126:127], v[126:127], v[230:231], v[198:199] op_sel_hi:[1,0,1]
	v_pk_fma_f32 v[124:125], v[124:125], v[230:231], v[234:235] op_sel_hi:[1,0,1]
	v_pk_fma_f32 v[108:109], v[108:109], v[230:231], v[242:243] op_sel_hi:[1,0,1]
	v_pk_fma_f32 v[122:123], v[122:123], v[230:231], v[200:201] op_sel_hi:[1,0,1]
	v_pk_fma_f32 v[120:121], v[120:121], v[230:231], v[236:237] op_sel_hi:[1,0,1]
	v_pk_fma_f32 v[118:119], v[118:119], v[230:231], v[202:203] op_sel_hi:[1,0,1]
	v_pk_fma_f32 v[116:117], v[116:117], v[230:231], v[240:241] op_sel_hi:[1,0,1]
	v_pk_fma_f32 v[110:111], v[110:111], v[230:231], v[204:205] op_sel_hi:[1,0,1]
	global_store_dwordx4 v[238:239], v[124:127], off
	global_store_dwordx4 v[238:239], v[120:123], off offset:16
	global_store_dwordx4 v[238:239], v[116:119], off offset:512
	global_store_dwordx4 v[238:239], v[108:111], off offset:528
	v_mov_b32_e32 v122, v231
	v_lshlrev_b32_e32 v118, 16, v208
	v_lshlrev_b64 v[108:109], 12, v[232:233]
	v_lshl_add_u64 v[108:109], s[26:27], 0, v[108:109]
	v_lshl_add_u64 v[116:117], v[108:109], 0, v[176:177]
	v_lshlrev_b32_e32 v108, 16, v206
	v_and_b32_e32 v109, 0xffff0000, v206
	v_lshlrev_b32_e32 v110, 16, v207
	v_and_b32_e32 v111, 0xffff0000, v207
	v_pk_fma_f32 v[110:111], v[114:115], v[122:123], v[110:111] op_sel_hi:[1,0,1]
	v_pk_fma_f32 v[108:109], v[112:113], v[122:123], v[108:109] op_sel_hi:[1,0,1]
	global_store_dwordx4 v[116:117], v[108:111], off
	v_and_b32_e32 v119, 0xffff0000, v208
	v_lshlrev_b32_e32 v120, 16, v209
	v_lshlrev_b32_e32 v108, 16, v212
	v_and_b32_e32 v109, 0xffff0000, v212
	v_lshlrev_b32_e32 v110, 16, v213
	v_and_b32_e32 v111, 0xffff0000, v213
	v_pk_fma_f32 v[98:99], v[98:99], v[122:123], v[110:111] op_sel_hi:[1,0,1]
	v_pk_fma_f32 v[96:97], v[96:97], v[122:123], v[108:109] op_sel_hi:[1,0,1]
	v_and_b32_e32 v121, 0xffff0000, v209
	global_store_dwordx4 v[116:117], v[96:99], off offset:528
	ds_read2_b32 v[98:99], v196 offset0:32 offset1:48
	v_pk_fma_f32 v[106:107], v[106:107], v[122:123], v[120:121] op_sel_hi:[1,0,1]
	v_pk_fma_f32 v[104:105], v[104:105], v[122:123], v[118:119] op_sel_hi:[1,0,1]
	v_add_u32_e32 v96, s11, v189
	global_store_dwordx4 v[116:117], v[104:107], off offset:16
	v_ashrrev_i32_e32 v97, 31, v96
	v_lshlrev_b64 v[96:97], 12, v[96:97]
	v_lshlrev_b32_e32 v104, 16, v210
	v_and_b32_e32 v105, 0xffff0000, v210
	v_lshlrev_b32_e32 v106, 16, v211
	v_and_b32_e32 v107, 0xffff0000, v211
	v_pk_fma_f32 v[102:103], v[102:103], v[122:123], v[106:107] op_sel_hi:[1,0,1]
	v_pk_fma_f32 v[100:101], v[100:101], v[122:123], v[104:105] op_sel_hi:[1,0,1]
	global_store_dwordx4 v[116:117], v[100:103], off offset:512
	v_lshl_add_u64 v[96:97], s[26:27], 0, v[96:97]
	v_lshl_add_u64 v[96:97], v[96:97], 0, v[176:177]
	v_lshlrev_b32_e32 v100, 16, v214
	v_and_b32_e32 v101, 0xffff0000, v214
	v_lshlrev_b32_e32 v102, 16, v215
	v_and_b32_e32 v103, 0xffff0000, v215
	s_waitcnt lgkmcnt(0)
; __device__ __forceinline__ float bf_lo(unsigned w) { return __uint_as_float(w << 16); }
; __device__ __forceinline__ float bf_hi(unsigned w) { return __uint_as_float(w & 0xffff0000u); }
;     __device__ __forceinline__ void operator()(const f32x4 (&acc)[2][2][4][2], const Unit& u, int ui, int wr, int wc, int fr, int fq) const {
;     ...
;             for (int m = 0; m < 4; ++m) { const int rl = rl0 + ai * 128 + m * 16; float* rowp = out + (size_t)(u.pm * 256 + rl) * DM + col0;
;                 const float r2 = tab[ui * 256 + rl];
; #pragma unroll
;                 for (int bj = 0; bj < 2; ++bj) { const u32x4 x = xv[ai][m][bj];
;                     const f32x4 x0 = {bf_lo(x.x), bf_hi(x.x), bf_lo(x.y), bf_hi(x.y)}, x1 = {bf_lo(x.z), bf_hi(x.z), bf_lo(x.w), bf_hi(x.w)};
;                     *(f32x4*)(rowp + bj * 128) = acc[ai][bj][m][0] * r2 + x0; *(f32x4*)(rowp + bj * 128 + 4) = acc[ai][bj][m][1] * r2 + x1; } }
	v_pk_fma_f32 v[94:95], v[94:95], v[98:99], v[102:103] op_sel_hi:[1,0,1]
	v_pk_fma_f32 v[92:93], v[92:93], v[98:99], v[100:101] op_sel_hi:[1,0,1]
	global_store_dwordx4 v[96:97], v[92:95], off
	v_lshlrev_b32_e32 v104, 16, v216
	v_and_b32_e32 v105, 0xffff0000, v216
	v_lshlrev_b32_e32 v92, 16, v220
	v_and_b32_e32 v93, 0xffff0000, v220
	v_lshlrev_b32_e32 v94, 16, v221
	v_and_b32_e32 v95, 0xffff0000, v221
	v_lshlrev_b32_e32 v106, 16, v217
	v_and_b32_e32 v107, 0xffff0000, v217
	v_pk_fma_f32 v[82:83], v[82:83], v[98:99], v[94:95] op_sel_hi:[1,0,1]
	v_pk_fma_f32 v[80:81], v[80:81], v[98:99], v[92:93] op_sel_hi:[1,0,1]
	v_pk_fma_f32 v[90:91], v[90:91], v[98:99], v[106:107] op_sel_hi:[1,0,1]
	v_pk_fma_f32 v[88:89], v[88:89], v[98:99], v[104:105] op_sel_hi:[1,0,1]
	global_store_dwordx4 v[96:97], v[80:83], off offset:528
	global_store_dwordx4 v[96:97], v[88:91], off offset:16
	s_nop 0
	v_add_u32_e32 v80, s11, v190
	v_lshlrev_b32_e32 v88, 16, v218
	v_and_b32_e32 v89, 0xffff0000, v218
	v_lshlrev_b32_e32 v90, 16, v219
	v_and_b32_e32 v91, 0xffff0000, v219
	v_ashrrev_i32_e32 v81, 31, v80
	v_pk_fma_f32 v[86:87], v[86:87], v[98:99], v[90:91] op_sel_hi:[1,0,1]
	v_pk_fma_f32 v[84:85], v[84:85], v[98:99], v[88:89] op_sel_hi:[1,0,1]
	v_lshlrev_b64 v[80:81], 12, v[80:81]
	global_store_dwordx4 v[96:97], v[84:87], off offset:512
	v_lshl_add_u64 v[80:81], s[26:27], 0, v[80:81]
	v_lshlrev_b32_e32 v82, 16, v222
	v_and_b32_e32 v83, 0xffff0000, v222
	v_lshlrev_b32_e32 v84, 16, v223
	v_and_b32_e32 v85, 0xffff0000, v223
	v_mov_b32_e32 v90, v99
	v_lshl_add_u64 v[80:81], v[80:81], 0, v[176:177]
	v_pk_fma_f32 v[78:79], v[78:79], v[90:91], v[84:85] op_sel_hi:[1,0,1]
	v_pk_fma_f32 v[76:77], v[76:77], v[90:91], v[82:83] op_sel_hi:[1,0,1]
	global_store_dwordx4 v[80:81], v[76:79], off
	v_lshlrev_b32_e32 v86, 16, v224
	v_and_b32_e32 v87, 0xffff0000, v224
	v_lshlrev_b32_e32 v76, 16, v228
	v_and_b32_e32 v77, 0xffff0000, v228
	v_lshlrev_b32_e32 v78, 16, v229
	v_and_b32_e32 v79, 0xffff0000, v229
	v_pk_fma_f32 v[66:67], v[66:67], v[90:91], v[78:79] op_sel_hi:[1,0,1]
	v_pk_fma_f32 v[64:65], v[64:65], v[90:91], v[76:77] op_sel_hi:[1,0,1]
	v_lshlrev_b32_e32 v88, 16, v225
	v_and_b32_e32 v89, 0xffff0000, v225
	global_store_dwordx4 v[80:81], v[64:67], off offset:528
	ds_read2_b32 v[66:67], v196 offset0:128 offset1:144
	v_pk_fma_f32 v[74:75], v[74:75], v[90:91], v[88:89] op_sel_hi:[1,0,1]
	v_pk_fma_f32 v[72:73], v[72:73], v[90:91], v[86:87] op_sel_hi:[1,0,1]
	global_store_dwordx4 v[80:81], v[72:75], off offset:16
	v_lshlrev_b64 v[64:65], 12, v[184:185]
	v_lshl_add_u64 v[64:65], s[26:27], 0, v[64:65]
	v_lshlrev_b32_e32 v72, 16, v226
	v_and_b32_e32 v73, 0xffff0000, v226
	v_lshlrev_b32_e32 v74, 16, v227
	v_and_b32_e32 v75, 0xffff0000, v227
	v_pk_fma_f32 v[70:71], v[70:71], v[90:91], v[74:75] op_sel_hi:[1,0,1]
	v_pk_fma_f32 v[68:69], v[68:69], v[90:91], v[72:73] op_sel_hi:[1,0,1]
	global_store_dwordx4 v[80:81], v[68:71], off offset:512
	v_lshl_add_u64 v[64:65], v[64:65], 0, v[176:177]
	v_lshlrev_b32_e32 v72, 16, v158
	v_lshlrev_b32_e32 v68, 16, v156
	v_and_b32_e32 v69, 0xffff0000, v156
	v_lshlrev_b32_e32 v70, 16, v157
	v_and_b32_e32 v71, 0xffff0000, v157
	v_and_b32_e32 v73, 0xffff0000, v158
	v_lshlrev_b32_e32 v74, 16, v159
	v_and_b32_e32 v75, 0xffff0000, v159
	s_waitcnt lgkmcnt(0)
; __device__ __forceinline__ float bf_lo(unsigned w) { return __uint_as_float(w << 16); }
; __device__ __forceinline__ float bf_hi(unsigned w) { return __uint_as_float(w & 0xffff0000u); }
; #define PG8_WAIT_V(n) asm volatile("s_waitcnt vmcnt(" #n ")" ::: "memory")
; #define PG8_BAR __builtin_amdgcn_s_barrier()
; template <class Epi, class Ptrs>
; __device__ __forceinline__ void gemm_phase(LAS unsigned char* lds, const int K, const StaticOrder& S, const Ptrs& P, const Epi& E) {
;     ...
;         if (!has_next) break;
; #pragma unroll
;         for (int a = 0; a < 2; ++a)
; #pragma unroll
;             for (int b = 0; b < 2; ++b)
; #pragma unroll
;                 for (int m = 0; m < 4; ++m)
; #pragma unroll
;                     for (int n = 0; n < 2; ++n) acc[a][b][m][n] = (f32x4){0.f, 0.f, 0.f, 0.f};
;         cur = nxt; cA = nA; cB = nB; ++ui;
;     }
;     PG8_WAIT_V(0);
;     if (wr == 0) PG8_BAR;
;     __device__ __forceinline__ void operator()(const f32x4 (&acc)[2][2][4][2], const Unit& u, int ui, int wr, int wc, int fr, int fq) const {
;     ...
;             for (int m = 0; m < 4; ++m) { const int rl = rl0 + ai * 128 + m * 16; float* rowp = out + (size_t)(u.pm * 256 + rl) * DM + col0;
;                 const float r2 = tab[ui * 256 + rl];
; #pragma unroll
;                 for (int bj = 0; bj < 2; ++bj) { const u32x4 x = xv[ai][m][bj];
;                     const f32x4 x0 = {bf_lo(x.x), bf_hi(x.x), bf_lo(x.y), bf_hi(x.y)}, x1 = {bf_lo(x.z), bf_hi(x.z), bf_lo(x.w), bf_hi(x.w)};
;                     *(f32x4*)(rowp + bj * 128) = acc[ai][bj][m][0] * r2 + x0; *(f32x4*)(rowp + bj * 128 + 4) = acc[ai][bj][m][1] * r2 + x1; } }
	v_pk_fma_f32 v[62:63], v[62:63], v[66:67], v[70:71] op_sel_hi:[1,0,1]
	v_pk_fma_f32 v[60:61], v[60:61], v[66:67], v[68:69] op_sel_hi:[1,0,1]
	global_store_dwordx4 v[64:65], v[60:63], off
	v_pk_fma_f32 v[58:59], v[58:59], v[66:67], v[74:75] op_sel_hi:[1,0,1]
	v_pk_fma_f32 v[56:57], v[56:57], v[66:67], v[72:73] op_sel_hi:[1,0,1]
	v_lshlrev_b32_e32 v60, 16, v154
	v_and_b32_e32 v61, 0xffff0000, v154
	v_lshlrev_b32_e32 v62, 16, v155
	v_and_b32_e32 v63, 0xffff0000, v155
	global_store_dwordx4 v[64:65], v[56:59], off offset:16
	v_pk_fma_f32 v[46:47], v[46:47], v[66:67], v[62:63] op_sel_hi:[1,0,1]
	v_pk_fma_f32 v[44:45], v[44:45], v[66:67], v[60:61] op_sel_hi:[1,0,1]
	v_lshlrev_b32_e32 v56, 16, v152
	v_and_b32_e32 v57, 0xffff0000, v152
	v_lshlrev_b32_e32 v58, 16, v153
	v_and_b32_e32 v59, 0xffff0000, v153
	v_pk_fma_f32 v[54:55], v[54:55], v[66:67], v[58:59] op_sel_hi:[1,0,1]
	v_pk_fma_f32 v[52:53], v[52:53], v[66:67], v[56:57] op_sel_hi:[1,0,1]
	global_store_dwordx4 v[64:65], v[44:47], off offset:528
	global_store_dwordx4 v[64:65], v[52:55], off offset:512
	v_lshlrev_b32_e32 v56, 16, v151
	v_lshlrev_b64 v[44:45], 12, v[182:183]
	v_lshl_add_u64 v[44:45], s[26:27], 0, v[44:45]
	v_lshlrev_b32_e32 v54, 16, v150
	v_and_b32_e32 v55, 0xffff0000, v150
	v_and_b32_e32 v57, 0xffff0000, v151
	v_mov_b32_e32 v58, v67
	v_lshl_add_u64 v[52:53], v[44:45], 0, v[176:177]
	v_pk_fma_f32 v[42:43], v[42:43], v[58:59], v[56:57] op_sel_hi:[1,0,1]
	v_pk_fma_f32 v[40:41], v[40:41], v[58:59], v[54:55] op_sel_hi:[1,0,1]
	v_lshlrev_b32_e32 v44, 16, v148
	v_and_b32_e32 v45, 0xffff0000, v148
	v_lshlrev_b32_e32 v46, 16, v149
	v_and_b32_e32 v47, 0xffff0000, v149
	global_store_dwordx4 v[52:53], v[40:43], off offset:16
	v_pk_fma_f32 v[46:47], v[50:51], v[58:59], v[46:47] op_sel_hi:[1,0,1]
	v_pk_fma_f32 v[44:45], v[48:49], v[58:59], v[44:45] op_sel_hi:[1,0,1]
	v_lshlrev_b32_e32 v40, 16, v144
	v_and_b32_e32 v41, 0xffff0000, v144
	v_lshlrev_b32_e32 v42, 16, v145
	v_and_b32_e32 v43, 0xffff0000, v145
	v_pk_fma_f32 v[38:39], v[38:39], v[58:59], v[42:43] op_sel_hi:[1,0,1]
	v_pk_fma_f32 v[36:37], v[36:37], v[58:59], v[40:41] op_sel_hi:[1,0,1]
	global_store_dwordx4 v[52:53], v[44:47], off
	global_store_dwordx4 v[52:53], v[36:39], off offset:512
	ds_read2_b32 v[38:39], v196 offset0:160 offset1:176
	v_lshlrev_b32_e32 v44, 16, v146
	v_and_b32_e32 v45, 0xffff0000, v146
	v_lshlrev_b32_e32 v46, 16, v147
	v_and_b32_e32 v47, 0xffff0000, v147
	v_pk_fma_f32 v[30:31], v[30:31], v[58:59], v[46:47] op_sel_hi:[1,0,1]
	v_pk_fma_f32 v[28:29], v[28:29], v[58:59], v[44:45] op_sel_hi:[1,0,1]
	global_store_dwordx4 v[52:53], v[28:31], off offset:528
	v_lshlrev_b32_e32 v40, 16, v142
	v_and_b32_e32 v41, 0xffff0000, v142
	v_lshlrev_b64 v[28:29], 12, v[180:181]
	v_lshl_add_u64 v[28:29], s[26:27], 0, v[28:29]
	v_lshl_add_u64 v[36:37], v[28:29], 0, v[176:177]
	v_lshlrev_b32_e32 v28, 16, v140
	v_and_b32_e32 v29, 0xffff0000, v140
	v_lshlrev_b32_e32 v30, 16, v141
	v_and_b32_e32 v31, 0xffff0000, v141
	s_waitcnt lgkmcnt(0)
	v_pk_fma_f32 v[30:31], v[34:35], v[38:39], v[30:31] op_sel_hi:[1,0,1]
	v_pk_fma_f32 v[28:29], v[32:33], v[38:39], v[28:29] op_sel_hi:[1,0,1]
	v_lshlrev_b32_e32 v42, 16, v143
	v_and_b32_e32 v43, 0xffff0000, v143
	global_store_dwordx4 v[36:37], v[28:31], off
	v_pk_fma_f32 v[26:27], v[26:27], v[38:39], v[42:43] op_sel_hi:[1,0,1]
	v_pk_fma_f32 v[24:25], v[24:25], v[38:39], v[40:41] op_sel_hi:[1,0,1]
	v_lshlrev_b32_e32 v28, 16, v138
	v_and_b32_e32 v29, 0xffff0000, v138
	v_lshlrev_b32_e32 v30, 16, v139
	v_and_b32_e32 v31, 0xffff0000, v139
	v_pk_fma_f32 v[14:15], v[14:15], v[38:39], v[30:31] op_sel_hi:[1,0,1]
	v_pk_fma_f32 v[12:13], v[12:13], v[38:39], v[28:29] op_sel_hi:[1,0,1]
	global_store_dwordx4 v[36:37], v[24:27], off offset:16
	global_store_dwordx4 v[36:37], v[12:15], off offset:528
	s_nop 0
	v_lshlrev_b32_e32 v24, 16, v136
	v_and_b32_e32 v25, 0xffff0000, v136
	v_lshlrev_b32_e32 v26, 16, v137
	v_and_b32_e32 v27, 0xffff0000, v137
	v_lshlrev_b64 v[12:13], 12, v[178:179]
	v_pk_fma_f32 v[22:23], v[22:23], v[38:39], v[26:27] op_sel_hi:[1,0,1]
	v_pk_fma_f32 v[20:21], v[20:21], v[38:39], v[24:25] op_sel_hi:[1,0,1]
	v_lshl_add_u64 v[12:13], s[26:27], 0, v[12:13]
	global_store_dwordx4 v[36:37], v[20:23], off offset:512
	v_lshlrev_b32_e32 v14, 16, v133
	v_and_b32_e32 v15, 0xffff0000, v133
	v_lshl_add_u64 v[20:21], v[12:13], 0, v[176:177]
	v_lshlrev_b32_e32 v12, 16, v132
	v_and_b32_e32 v13, 0xffff0000, v132
	v_lshlrev_b32_e32 v22, 16, v134
	v_and_b32_e32 v23, 0xffff0000, v134
	v_lshlrev_b32_e32 v24, 16, v135
	v_and_b32_e32 v25, 0xffff0000, v135
	v_mov_b32_e32 v26, v39
	v_pk_fma_f32 v[14:15], v[18:19], v[26:27], v[14:15] op_sel_hi:[1,0,1]
	v_pk_fma_f32 v[12:13], v[16:17], v[26:27], v[12:13] op_sel_hi:[1,0,1]
	v_pk_fma_f32 v[10:11], v[10:11], v[26:27], v[24:25] op_sel_hi:[1,0,1]
	v_pk_fma_f32 v[8:9], v[8:9], v[26:27], v[22:23] op_sel_hi:[1,0,1]
	global_store_dwordx4 v[20:21], v[12:15], off
	global_store_dwordx4 v[20:21], v[8:11], off offset:16
	s_nop 0
	v_lshlrev_b32_e32 v12, 16, v130
	v_lshlrev_b32_e32 v8, 16, v128
	v_and_b32_e32 v9, 0xffff0000, v128
	v_lshlrev_b32_e32 v10, 16, v129
	v_and_b32_e32 v11, 0xffff0000, v129
	v_and_b32_e32 v13, 0xffff0000, v130
	v_lshlrev_b32_e32 v14, 16, v131
	v_and_b32_e32 v15, 0xffff0000, v131
	v_pk_fma_f32 v[6:7], v[6:7], v[26:27], v[10:11] op_sel_hi:[1,0,1]
	v_pk_fma_f32 v[4:5], v[4:5], v[26:27], v[8:9] op_sel_hi:[1,0,1]
	v_pk_fma_f32 v[2:3], v[2:3], v[26:27], v[14:15] op_sel_hi:[1,0,1]
	v_pk_fma_f32 v[0:1], v[0:1], v[26:27], v[12:13] op_sel_hi:[1,0,1]
	global_store_dwordx4 v[20:21], v[4:7], off offset:512
	global_store_dwordx4 v[20:21], v[0:3], off offset:528
	s_cbranch_vccz .LBB0_517
	s_waitcnt vmcnt(0)
	s_setprio 0
	s_cmpk_gt_u32 s33, 0xff
	s_cbranch_scc1 .LBB0_526
	s_barrier
